# FFN1 activations staged as 64-wide k pairs (full cache lines), barrier state moved to VGPR lanes, LDS 80 KiB
# baseline (speedup 1.0000x reference)
; #define LAS __attribute__((address_space(3)))
; DI unsigned xb_add(unsigned* p, unsigned v) { return __hip_atomic_fetch_add(p, v, __ATOMIC_RELAXED, __HIP_MEMORY_SCOPE_AGENT); }
; DI unsigned xb_xcc_id() { return (unsigned)__builtin_amdgcn_s_getreg((3 << 11) | 20) & 0xFu; }
; DI XcdBarrier xcd_barrier_post(unsigned* bar, volatile LAS unsigned* st) {
;   XcdBarrier b; b.bar = bar; b.x = xb_xcc_id(); b.st = st;
;   if (threadIdx.x == 0) (void)xb_add(&bar[XB_XCNT(b.x)], 1u);
;   return b;
; __global__ void __launch_bounds__(256, 2) mega_kernel(Params p) {
;   __shared__ __attribute__((aligned(16))) char smem[SMEM_BYTES];
;   __shared__ uint4 xb_words;
;   cg::grid_group grid = cg::this_grid();
;   if (threadIdx.x == 0) xb_words = make_uint4(0u, 0u, 0u, 0u);
;   __syncthreads();
;   const XcdBarrier xb = xcd_barrier_post((unsigned*)(p.ws + OFF_BAR), (volatile LAS unsigned*)&xb_words);
.LBB1_2:
	s_or_b64 exec, exec, s[4:5]
	v_writelane_b32 v255, 0, 60
	v_writelane_b32 v255, 0, 61
	s_load_dwordx16 s[4:19], s[0:1], 0x0
	s_waitcnt lgkmcnt(0)
	s_add_u32 s20, s76, 0x1c140000
	s_addc_u32 s21, s77, 0
	v_writelane_b32 v254, s4, 2
	s_nop 1
	v_writelane_b32 v254, s5, 3
	v_writelane_b32 v254, s6, 4
	v_writelane_b32 v254, s7, 5
	v_writelane_b32 v254, s8, 6
	v_writelane_b32 v254, s9, 7
	v_writelane_b32 v254, s10, 8
	v_writelane_b32 v254, s11, 9
	v_writelane_b32 v254, s12, 10
	v_writelane_b32 v254, s13, 11
	v_writelane_b32 v254, s14, 12
	v_writelane_b32 v254, s15, 13
	v_writelane_b32 v254, s16, 14
	v_writelane_b32 v254, s17, 15
	v_writelane_b32 v254, s18, 16
	v_writelane_b32 v254, s19, 17
	s_load_dwordx16 s[4:19], s[0:1], 0x40
	s_load_dwordx16 s[36:51], s[0:1], 0x80
	s_waitcnt lgkmcnt(0)
	s_barrier
	s_getreg_b32 s0, hwreg(HW_REG_XCC_ID, 0, 4)
	v_writelane_b32 v254, s36, 18
	s_and_b32 s2, s0, 15
	s_nop 0
	v_writelane_b32 v254, s37, 19
	v_writelane_b32 v254, s38, 20
	v_writelane_b32 v254, s39, 21
	v_writelane_b32 v254, s40, 22
	v_writelane_b32 v254, s41, 23
	v_writelane_b32 v254, s42, 24
	v_writelane_b32 v254, s43, 25
	v_writelane_b32 v254, s44, 26
	v_writelane_b32 v254, s45, 27
	v_writelane_b32 v254, s46, 28
	v_writelane_b32 v254, s47, 29
	v_writelane_b32 v254, s48, 30
	v_writelane_b32 v254, s49, 31
	v_writelane_b32 v254, s50, 32
	v_writelane_b32 v254, s51, 33
	s_mov_b64 s[0:1], exec
	v_readlane_b32 s24, v254, 0
	v_readlane_b32 s25, v254, 1
	s_and_b64 s[24:25], s[0:1], s[24:25]
	s_mov_b64 exec, s[24:25]
	s_cbranch_execz .LBB1_5
	s_mov_b64 s[24:25], exec
	v_mbcnt_lo_u32_b32 v1, s24, 0
	v_mbcnt_hi_u32_b32 v1, s25, v1
	v_cmp_eq_u32_e32 vcc, 0, v1
	s_and_b64 s[26:27], exec, vcc
	s_mov_b64 exec, s[26:27]
	s_cbranch_execz .LBB1_5
	s_lshl_b32 s26, s2, 8
	s_bcnt1_i32_b64 s24, s[24:25]
	v_mov_b32_e32 v1, s26
	v_mov_b32_e32 v2, s24
	global_atomic_add v1, v2, s[20:21] offset:1024

; DI int TID() { int t = (int)__builtin_amdgcn_workitem_id_x(); asm volatile("" : "+v"(t)); return t; }
; #define BLOAD(A_, B_, kt) do { _Pragma("unroll") for (int i = 0; i < 4; ++i) { \
;     A_[i] = *(const u32x4*)((const char*)Ap + (aoff + (unsigned)(32 * i * lda + (kt) * 64) * 2u)); B_[i] = *(const u32x4*)((const char*)Wt + (woff + (unsigned)(32 * i * K + (kt) * 64) * 2u)); } } while (0)
; DI RowSS rowss_load(const float* ps, int m0) { const int tid = TID(); const float* q = ps + (size_t)(m0 + (tid >> 1)) * 16 + (tid & 1) * 8; RowSS r; r.a = *(const f32x4*)q; r.b = *(const f32x4*)(q + 4); return r; }
; #define BLOAD(A_, B_, kt) do { _Pragma("unroll") for (int i = 0; i < 4; ++i) { \
;     A_[i] = *(const u32x4*)((const char*)Ap + (aoff + (unsigned)(32 * i * lda + (kt) * 64) * 2u)); B_[i] = *(const u32x4*)((const char*)Wt + (woff + (unsigned)(32 * i * K + (kt) * 64) * 2u)); } } while (0)
; template <int NK>
; DI void gemm_run(PF& pf, const u16* __restrict__ Ap, int lda, const u16* __restrict__ Wt, f32x16 (&acc)[2][2], char* smem) {
;   constexpr int K = NK * 64;
;   const int tid = TID(), lane = tid & 63, w = tid >> 6, wm = w >> 1, wn = w & 1, r32 = lane & 31, hi = lane >> 5;
;   u16* As = (u16*)smem; u16* Bs = As + 128 * LDT;
;   const int srow = tid >> 3, sc8 = (tid & 7) * 8;
;   constexpr int nk = NK;
;   const unsigned aoff = (unsigned)(srow * lda + sc8) * 2u, woff = (unsigned)(srow * K + sc8) * 2u;
;     ...
;   __builtin_amdgcn_s_setprio(0);
;   __syncthreads();
;   BSTORE(pf.a0, pf.b0, 0);
;   BLOAD(pf.a0, pf.b0, 2);
;   __syncthreads();
; DI void tile_ffn1(const Params& p, int l, const Chunk& ck, int tile, int next, PF& pf, char* smem) {
;   float* Cs = (float*)smem; float* rinv_s = (float*)(smem + SMEM_CS);
;   const int tid = TID(); const int mi = tile & (MTN - 1), ni = tile >> MTS; const int m0 = mi * 128, n0 = ni * 128;
;   f32x16 acc[2][2]; zero_acc(acc);
;   const RowSS rss = rowss_load((const float*)(p.ws + OFF_PSMID), m0);
;   { const u16* Ap; const u16* Wt; ffn1_ptrs(p, l, tile, Ap, Wt); gemm_run<16>(pf, Ap, 1024, Wt, acc, smem); }
;   if (next >= 0) { const u16* An; const u16* Wn; ffn1_ptrs(p, l, next, An, Wn); gemm_issue(pf, An, 1024, Wn, 1024); }
.LBB1_246:
	s_mov_b32 s26, s16
	s_add_i32 s16, s16, s78
	s_cmpk_gt_i32 s16, 0x7ff
	s_cselect_b64 s[24:25], -1, 0
	s_cmpk_lt_i32 s16, 0x800
	v_mov_b32_e32 v148, v172
	v_mov_b32_e32 v0, v172
	s_cselect_b32 s0, s16, -1
	s_and_b32 s41, s40, 0x3f80
	s_and_b32 s27, s35, 0xfe0000
	v_ashrrev_i32_e32 v2, 1, v0
	v_add_u32_e32 v2, s41, v2
	v_ashrrev_i32_e32 v3, 31, v2
	v_lshlrev_b64 v[2:3], 6, v[2:3]
	v_lshlrev_b32_e32 v0, 5, v0
	v_lshl_add_u64 v[2:3], s[20:21], 0, v[2:3]
	v_and_b32_e32 v0, 32, v0
	v_lshl_add_u64 v[2:3], v[2:3], 0, v[0:1]
	global_load_dwordx4 v[66:69], v[2:3], off offset:16
	global_load_dwordx4 v[70:73], v[2:3], off
	s_and_b32 s26, s26, 0xffffff80
	s_lshl_b32 s26, s26, 1
	s_lshl_b32 s27, s27, 1
	s_add_u32 s28, s17, s27
	s_addc_u32 s29, s34, 0
	s_ashr_i32 s27, s26, 31
	s_lshl_b64 s[30:31], s[26:27], 6
	s_add_u32 s30, s36, s30
	s_addc_u32 s31, s37, s31
	s_setprio 0
	s_waitcnt lgkmcnt(0)
	s_mov_b32 s0, 0
	v_and_b32_e32 v149, 63, v172
	v_lshrrev_b32_e32 v151, 6, v172
	v_lshrrev_b32_e32 v152, 4, v149
	v_xor_b32_e32 v152, v152, v149
	v_and_b32_e32 v152, 7, v152
	v_lshlrev_b32_e32 v152, 4, v152
	v_lshrrev_b32_e32 v153, 3, v149
	v_lshl_add_u32 v153, v151, 5, v153
	v_lshl_add_u32 v142, v153, 11, v152
	v_xor_b32_e32 v143, 64, v142
	v_add_u32_e32 v143, 0x3c00, v143
	v_add_u32_e32 v154, 0x7800, v142
	v_xor_b32_e32 v155, 64, v142
	v_add_u32_e32 v155, 0xb400, v155
	v_bfe_u32 v152, v149, 4, 2
	v_lshrrev_b32_e32 v153, 1, v152
	v_xor_b32_e32 v152, v152, v153
	v_and_b32_e32 v152, 1, v152
	v_lshl_or_b32 v152, v152, 1, v153
	v_xor_b32_e32 v152, v152, v149
	v_and_b32_e32 v152, 3, v152
	v_lshlrev_b32_e32 v152, 4, v152
	v_lshrrev_b32_e32 v153, 2, v149
	v_lshl_add_u32 v144, v151, 6, v153
	v_lshl_add_u32 v144, v144, 6, v152
	v_mov_b32_e32 v145, v144
	v_mov_b32_e32 v146, v144
	v_mov_b32_e32 v147, v144
	v_readfirstlane_b32 s42, v151
	s_lshl_b32 s42, s42, 12
	s_add_u32 s43, s42, 0x8000
	v_bfe_u32 v152, v149, 2, 2
	v_lshrrev_b32_e32 v153, 1, v152
	v_xor_b32_e32 v152, v152, v153
	v_and_b32_e32 v152, 1, v152
	v_lshl_or_b32 v152, v152, 1, v153
	v_lshrrev_b32_e32 v153, 4, v149
	v_xor_b32_e32 v152, v152, v153
	v_lshlrev_b32_e32 v152, 4, v152
	v_and_b32_e32 v153, 15, v149
	v_lshl_add_u32 v152, v153, 6, v152
	v_and_b32_e32 v140, 1, v151
	v_lshl_add_u32 v140, v140, 12, v152
	v_add_u32_e32 v140, 0x8000, v140
	v_bfe_u32 v152, v149, 1, 3
	v_lshrrev_b32_e32 v139, 4, v149
	v_xor_b32_e32 v152, v152, v139
	v_lshlrev_b32_e32 v152, 4, v152
	v_lshl_add_u32 v152, v153, 7, v152
	v_lshrrev_b32_e32 v153, 1, v151
	v_lshl_add_u32 v138, v153, 13, v152
	v_xor_b32_e32 v139, 64, v138
	s_barrier
	v_mov_b32_e32 v2, 0
	v_mov_b32_e32 v3, 0
	v_mov_b32_e32 v4, 0
	v_mov_b32_e32 v5, 0
	v_mov_b32_e32 v6, 0
	v_mov_b32_e32 v7, 0
	v_mov_b32_e32 v8, 0
	v_mov_b32_e32 v9, 0
	v_mov_b32_e32 v10, 0
	v_mov_b32_e32 v11, 0
	v_mov_b32_e32 v12, 0
	v_mov_b32_e32 v13, 0
	v_mov_b32_e32 v14, 0
	v_mov_b32_e32 v15, 0
	v_mov_b32_e32 v16, 0
	v_mov_b32_e32 v17, 0
	v_mov_b32_e32 v18, 0
	v_mov_b32_e32 v19, 0
	v_mov_b32_e32 v20, 0
	v_mov_b32_e32 v21, 0
	v_mov_b32_e32 v22, 0
	v_mov_b32_e32 v23, 0
	v_mov_b32_e32 v24, 0
	v_mov_b32_e32 v25, 0
	v_mov_b32_e32 v26, 0
	v_mov_b32_e32 v27, 0
	v_mov_b32_e32 v28, 0
	v_mov_b32_e32 v29, 0
	v_mov_b32_e32 v30, 0
	v_mov_b32_e32 v31, 0
	v_mov_b32_e32 v32, 0
	v_mov_b32_e32 v33, 0
	v_mov_b32_e32 v34, 0
	v_mov_b32_e32 v35, 0
	v_mov_b32_e32 v36, 0
	v_mov_b32_e32 v37, 0
	v_mov_b32_e32 v38, 0
	v_mov_b32_e32 v39, 0
	v_mov_b32_e32 v40, 0
	v_mov_b32_e32 v41, 0
	v_mov_b32_e32 v42, 0
	v_mov_b32_e32 v43, 0
	v_mov_b32_e32 v44, 0
	v_mov_b32_e32 v45, 0
	v_mov_b32_e32 v46, 0
	v_mov_b32_e32 v47, 0
	v_mov_b32_e32 v48, 0
	v_mov_b32_e32 v49, 0
	v_mov_b32_e32 v50, 0
	v_mov_b32_e32 v51, 0
	v_mov_b32_e32 v52, 0
	v_mov_b32_e32 v53, 0
	v_mov_b32_e32 v54, 0
	v_mov_b32_e32 v55, 0
	v_mov_b32_e32 v56, 0
	v_mov_b32_e32 v57, 0
	v_mov_b32_e32 v58, 0
	v_mov_b32_e32 v59, 0
	v_mov_b32_e32 v60, 0
	v_mov_b32_e32 v61, 0
	v_mov_b32_e32 v62, 0
	v_mov_b32_e32 v63, 0
	v_mov_b32_e32 v64, 0
	v_mov_b32_e32 v65, 0
	v_mov_b32_e32 v74, 0
	v_mov_b32_e32 v75, 0
	v_mov_b32_e32 v76, 0
	v_mov_b32_e32 v77, 0
	v_mov_b32_e32 v78, 0
	v_mov_b32_e32 v79, 0
	v_mov_b32_e32 v80, 0
	v_mov_b32_e32 v81, 0
	v_mov_b32_e32 v82, 0
	v_mov_b32_e32 v83, 0
	v_mov_b32_e32 v84, 0
	v_mov_b32_e32 v85, 0
	v_mov_b32_e32 v86, 0
	v_mov_b32_e32 v87, 0
	v_mov_b32_e32 v88, 0
	v_mov_b32_e32 v89, 0
	v_mov_b32_e32 v90, 0
	v_mov_b32_e32 v91, 0
	v_mov_b32_e32 v92, 0
	v_mov_b32_e32 v93, 0
	v_mov_b32_e32 v94, 0
	v_mov_b32_e32 v95, 0
	v_mov_b32_e32 v96, 0
	v_mov_b32_e32 v97, 0
	v_mov_b32_e32 v98, 0
	v_mov_b32_e32 v99, 0
	v_mov_b32_e32 v100, 0
	v_mov_b32_e32 v101, 0
	v_mov_b32_e32 v102, 0
	v_mov_b32_e32 v103, 0
	v_mov_b32_e32 v104, 0
	v_mov_b32_e32 v105, 0
	v_mov_b32_e32 v106, 0
	v_mov_b32_e32 v107, 0
	v_mov_b32_e32 v108, 0
	v_mov_b32_e32 v109, 0
	v_mov_b32_e32 v110, 0
	v_mov_b32_e32 v111, 0
	v_mov_b32_e32 v112, 0
	v_mov_b32_e32 v113, 0
	v_mov_b32_e32 v114, 0
	v_mov_b32_e32 v115, 0
	v_mov_b32_e32 v116, 0
	v_mov_b32_e32 v117, 0
	v_mov_b32_e32 v118, 0
	v_mov_b32_e32 v119, 0
	v_mov_b32_e32 v120, 0
	v_mov_b32_e32 v121, 0
	v_mov_b32_e32 v122, 0
	v_mov_b32_e32 v123, 0
	v_mov_b32_e32 v124, 0
	v_mov_b32_e32 v125, 0
	v_mov_b32_e32 v126, 0
	v_mov_b32_e32 v127, 0
	v_mov_b32_e32 v128, 0
	v_mov_b32_e32 v129, 0
	v_mov_b32_e32 v130, 0
	v_mov_b32_e32 v131, 0
	v_mov_b32_e32 v132, 0
	v_mov_b32_e32 v133, 0
	v_mov_b32_e32 v134, 0
	v_mov_b32_e32 v135, 0
	v_mov_b32_e32 v136, 0
	v_mov_b32_e32 v137, 0
	s_add_u32 m0, s42, 0x0
	s_nop 0
	global_load_lds_dwordx4 v142, s[28:29]
	global_load_lds_dwordx4 v143, s[28:29] offset:1024
	global_load_lds_dwordx4 v154, s[28:29] offset:2048
	global_load_lds_dwordx4 v155, s[28:29] offset:3072
	s_add_u32 m0, s43, 0x0
	s_nop 0
	global_load_lds_dwordx4 v144, s[30:31]
	global_load_lds_dwordx4 v145, s[30:31] offset:1024
	global_load_lds_dwordx4 v146, s[30:31] offset:2048
	global_load_lds_dwordx4 v147, s[30:31] offset:3072
	s_add_u32 m0, s43, 0x4000
	s_add_u32 s30, s30, 0x40000
	s_addc_u32 s31, s31, 0
	global_load_lds_dwordx4 v144, s[30:31]
	global_load_lds_dwordx4 v145, s[30:31] offset:1024
	global_load_lds_dwordx4 v146, s[30:31] offset:2048
	global_load_lds_dwordx4 v147, s[30:31] offset:3072
	s_waitcnt vmcnt(4)
	s_barrier
; #define BLOAD(A_, B_, kt) do { _Pragma("unroll") for (int i = 0; i < 4; ++i) { \
;     A_[i] = *(const u32x4*)((const char*)Ap + (aoff + (unsigned)(32 * i * lda + (kt) * 64) * 2u)); B_[i] = *(const u32x4*)((const char*)Wt + (woff + (unsigned)(32 * i * K + (kt) * 64) * 2u)); } } while (0)
; #define BLOAD(A_, B_, kt) do { _Pragma("unroll") for (int i = 0; i < 4; ++i) { \
;     A_[i] = *(const u32x4*)((const char*)Ap + (aoff + (unsigned)(32 * i * lda + (kt) * 64) * 2u)); B_[i] = *(const u32x4*)((const char*)Wt + (woff + (unsigned)(32 * i * K + (kt) * 64) * 2u)); } } while (0)
; #define BSTORE(A_, B_, buf) do { _Pragma("unroll") for (int i = 0; i < 4; ++i) { \
;     *(u32x4*)&As[(buf) * GBUF + (srow + 32 * i) * LDT + sc8] = A_[i]; \
;     *(u32x4*)&Bs[(buf) * GBUF + (srow + 32 * i) * LDT + sc8] = B_[i]; } } while (0)
; template <int NK>
; DI void gemm_run(PF& pf, const u16* __restrict__ Ap, int lda, const u16* __restrict__ Wt, f32x16 (&acc)[2][2], char* smem) {
;     ...
;   __builtin_amdgcn_s_setprio(0);
;   __syncthreads();
;   BSTORE(pf.a0, pf.b0, 0);
;   BLOAD(pf.a0, pf.b0, 2);
;   __syncthreads();
; #pragma unroll
;   for (int kt = 0; kt < nk; kt += 2) {
;     BCOMP(0);
;     BSTORE(pf.a1, pf.b1, 1);
;     if (kt + 3 < nk) BLOAD(pf.a1, pf.b1, kt + 3);
;     __syncthreads();
;     BCOMP(1);
;     if (kt + 2 < nk) { BSTORE(pf.a0, pf.b0, 0); if (kt + 4 < nk) BLOAD(pf.a0, pf.b0, kt + 4); }
;     __syncthreads();
	s_setprio 1
	ds_read_b128 v[208:211], v138 offset:0
	ds_read_b128 v[224:227], v140 offset:0
	ds_read_b128 v[228:231], v140 offset:1024
	ds_read_b128 v[232:235], v140 offset:2048
	ds_read_b128 v[236:239], v140 offset:3072
	ds_read_b128 v[212:215], v138 offset:2048
	ds_read_b128 v[216:219], v138 offset:4096
	ds_read_b128 v[220:223], v138 offset:6144
	ds_read_b128 v[240:243], v140 offset:8192
	ds_read_b128 v[244:247], v140 offset:9216
	ds_read_b128 v[248:251], v140 offset:10240
	ds_read_b128 v[156:159], v140 offset:11264
	s_add_u32 m0, s43, 0x8000
	s_add_u32 s30, s30, 0x40000
	s_addc_u32 s31, s31, 0
	global_load_lds_dwordx4 v144, s[30:31]
	global_load_lds_dwordx4 v145, s[30:31] offset:1024
	global_load_lds_dwordx4 v146, s[30:31] offset:2048
	global_load_lds_dwordx4 v147, s[30:31] offset:3072
	s_add_u32 m0, s42, 0x4000
	s_add_u32 s28, s28, 0x80
	s_addc_u32 s29, s29, 0
	global_load_lds_dwordx4 v142, s[28:29]
	global_load_lds_dwordx4 v143, s[28:29] offset:1024
	global_load_lds_dwordx4 v154, s[28:29] offset:2048
	global_load_lds_dwordx4 v155, s[28:29] offset:3072
	s_waitcnt lgkmcnt(10)
	v_mfma_f32_16x16x32_bf16 v[2:5], v[208:211], v[224:227], v[2:5]
	s_waitcnt lgkmcnt(9)
	v_mfma_f32_16x16x32_bf16 v[6:9], v[208:211], v[228:231], v[6:9]
	s_waitcnt lgkmcnt(8)
	v_mfma_f32_16x16x32_bf16 v[10:13], v[208:211], v[232:235], v[10:13]
	s_waitcnt lgkmcnt(7)
	v_mfma_f32_16x16x32_bf16 v[14:17], v[208:211], v[236:239], v[14:17]
	s_waitcnt lgkmcnt(6)
	v_mfma_f32_16x16x32_bf16 v[18:21], v[212:215], v[224:227], v[18:21]
	v_mfma_f32_16x16x32_bf16 v[22:25], v[212:215], v[228:231], v[22:25]
	v_mfma_f32_16x16x32_bf16 v[26:29], v[212:215], v[232:235], v[26:29]
	v_mfma_f32_16x16x32_bf16 v[30:33], v[212:215], v[236:239], v[30:33]
	s_waitcnt lgkmcnt(5)
	v_mfma_f32_16x16x32_bf16 v[34:37], v[216:219], v[224:227], v[34:37]
	v_mfma_f32_16x16x32_bf16 v[38:41], v[216:219], v[228:231], v[38:41]
	v_mfma_f32_16x16x32_bf16 v[42:45], v[216:219], v[232:235], v[42:45]
	v_mfma_f32_16x16x32_bf16 v[46:49], v[216:219], v[236:239], v[46:49]
	s_waitcnt lgkmcnt(4)
	v_mfma_f32_16x16x32_bf16 v[50:53], v[220:223], v[224:227], v[50:53]
	v_mfma_f32_16x16x32_bf16 v[54:57], v[220:223], v[228:231], v[54:57]
	v_mfma_f32_16x16x32_bf16 v[58:61], v[220:223], v[232:235], v[58:61]
	v_mfma_f32_16x16x32_bf16 v[62:65], v[220:223], v[236:239], v[62:65]
	s_waitcnt lgkmcnt(3)
	v_mfma_f32_16x16x32_bf16 v[74:77], v[208:211], v[240:243], v[74:77]
	s_waitcnt lgkmcnt(2)
	v_mfma_f32_16x16x32_bf16 v[78:81], v[208:211], v[244:247], v[78:81]
	s_waitcnt lgkmcnt(1)
	v_mfma_f32_16x16x32_bf16 v[82:85], v[208:211], v[248:251], v[82:85]
	s_waitcnt lgkmcnt(0)
	v_mfma_f32_16x16x32_bf16 v[86:89], v[208:211], v[156:159], v[86:89]
	v_mfma_f32_16x16x32_bf16 v[90:93], v[212:215], v[240:243], v[90:93]
	v_mfma_f32_16x16x32_bf16 v[94:97], v[212:215], v[244:247], v[94:97]
	v_mfma_f32_16x16x32_bf16 v[98:101], v[212:215], v[248:251], v[98:101]
	v_mfma_f32_16x16x32_bf16 v[102:105], v[212:215], v[156:159], v[102:105]
	v_mfma_f32_16x16x32_bf16 v[106:109], v[216:219], v[240:243], v[106:109]
	v_mfma_f32_16x16x32_bf16 v[110:113], v[216:219], v[244:247], v[110:113]
	v_mfma_f32_16x16x32_bf16 v[114:117], v[216:219], v[248:251], v[114:117]
	v_mfma_f32_16x16x32_bf16 v[118:121], v[216:219], v[156:159], v[118:121]
	v_mfma_f32_16x16x32_bf16 v[122:125], v[220:223], v[240:243], v[122:125]
	v_mfma_f32_16x16x32_bf16 v[126:129], v[220:223], v[244:247], v[126:129]
	v_mfma_f32_16x16x32_bf16 v[130:133], v[220:223], v[248:251], v[130:133]
	v_mfma_f32_16x16x32_bf16 v[134:137], v[220:223], v[156:159], v[134:137]
	s_setprio 0
	s_waitcnt vmcnt(8)
	s_barrier
	s_setprio 1
	ds_read_b128 v[208:211], v139 offset:0
	ds_read_b128 v[224:227], v140 offset:16384
	ds_read_b128 v[228:231], v140 offset:17408
	ds_read_b128 v[232:235], v140 offset:18432
	ds_read_b128 v[236:239], v140 offset:19456
	ds_read_b128 v[212:215], v139 offset:2048
	ds_read_b128 v[216:219], v139 offset:4096
	ds_read_b128 v[220:223], v139 offset:6144
	ds_read_b128 v[240:243], v140 offset:24576
	ds_read_b128 v[244:247], v140 offset:25600
	ds_read_b128 v[248:251], v140 offset:26624
	ds_read_b128 v[156:159], v140 offset:27648
	s_add_u32 m0, s43, 0x0
	s_add_u32 s30, s30, 0x40000
	s_addc_u32 s31, s31, 0
	global_load_lds_dwordx4 v144, s[30:31]
	global_load_lds_dwordx4 v145, s[30:31] offset:1024
	global_load_lds_dwordx4 v146, s[30:31] offset:2048
	global_load_lds_dwordx4 v147, s[30:31] offset:3072
	s_waitcnt lgkmcnt(10)
	v_mfma_f32_16x16x32_bf16 v[2:5], v[208:211], v[224:227], v[2:5]
	s_waitcnt lgkmcnt(9)
	v_mfma_f32_16x16x32_bf16 v[6:9], v[208:211], v[228:231], v[6:9]
	s_waitcnt lgkmcnt(8)
	v_mfma_f32_16x16x32_bf16 v[10:13], v[208:211], v[232:235], v[10:13]
	s_waitcnt lgkmcnt(7)
	v_mfma_f32_16x16x32_bf16 v[14:17], v[208:211], v[236:239], v[14:17]
	s_waitcnt lgkmcnt(6)
	v_mfma_f32_16x16x32_bf16 v[18:21], v[212:215], v[224:227], v[18:21]
	v_mfma_f32_16x16x32_bf16 v[22:25], v[212:215], v[228:231], v[22:25]
	v_mfma_f32_16x16x32_bf16 v[26:29], v[212:215], v[232:235], v[26:29]
	v_mfma_f32_16x16x32_bf16 v[30:33], v[212:215], v[236:239], v[30:33]
	s_waitcnt lgkmcnt(5)
	v_mfma_f32_16x16x32_bf16 v[34:37], v[216:219], v[224:227], v[34:37]
	v_mfma_f32_16x16x32_bf16 v[38:41], v[216:219], v[228:231], v[38:41]
	v_mfma_f32_16x16x32_bf16 v[42:45], v[216:219], v[232:235], v[42:45]
	v_mfma_f32_16x16x32_bf16 v[46:49], v[216:219], v[236:239], v[46:49]
	s_waitcnt lgkmcnt(4)
	v_mfma_f32_16x16x32_bf16 v[50:53], v[220:223], v[224:227], v[50:53]
	v_mfma_f32_16x16x32_bf16 v[54:57], v[220:223], v[228:231], v[54:57]
	v_mfma_f32_16x16x32_bf16 v[58:61], v[220:223], v[232:235], v[58:61]
	v_mfma_f32_16x16x32_bf16 v[62:65], v[220:223], v[236:239], v[62:65]
	s_waitcnt lgkmcnt(3)
	v_mfma_f32_16x16x32_bf16 v[74:77], v[208:211], v[240:243], v[74:77]
	s_waitcnt lgkmcnt(2)
	v_mfma_f32_16x16x32_bf16 v[78:81], v[208:211], v[244:247], v[78:81]
	s_waitcnt lgkmcnt(1)
	v_mfma_f32_16x16x32_bf16 v[82:85], v[208:211], v[248:251], v[82:85]
	s_waitcnt lgkmcnt(0)
	v_mfma_f32_16x16x32_bf16 v[86:89], v[208:211], v[156:159], v[86:89]
	v_mfma_f32_16x16x32_bf16 v[90:93], v[212:215], v[240:243], v[90:93]
	v_mfma_f32_16x16x32_bf16 v[94:97], v[212:215], v[244:247], v[94:97]
	v_mfma_f32_16x16x32_bf16 v[98:101], v[212:215], v[248:251], v[98:101]
	v_mfma_f32_16x16x32_bf16 v[102:105], v[212:215], v[156:159], v[102:105]
	v_mfma_f32_16x16x32_bf16 v[106:109], v[216:219], v[240:243], v[106:109]
	v_mfma_f32_16x16x32_bf16 v[110:113], v[216:219], v[244:247], v[110:113]
	v_mfma_f32_16x16x32_bf16 v[114:117], v[216:219], v[248:251], v[114:117]
	v_mfma_f32_16x16x32_bf16 v[118:121], v[216:219], v[156:159], v[118:121]
	v_mfma_f32_16x16x32_bf16 v[122:125], v[220:223], v[240:243], v[122:125]
	v_mfma_f32_16x16x32_bf16 v[126:129], v[220:223], v[244:247], v[126:129]
	v_mfma_f32_16x16x32_bf16 v[130:133], v[220:223], v[248:251], v[130:133]
	v_mfma_f32_16x16x32_bf16 v[134:137], v[220:223], v[156:159], v[134:137]
	s_setprio 0
	s_waitcnt vmcnt(4)
	s_barrier
; #define BLOAD(A_, B_, kt) do { _Pragma("unroll") for (int i = 0; i < 4; ++i) { \
;     A_[i] = *(const u32x4*)((const char*)Ap + (aoff + (unsigned)(32 * i * lda + (kt) * 64) * 2u)); B_[i] = *(const u32x4*)((const char*)Wt + (woff + (unsigned)(32 * i * K + (kt) * 64) * 2u)); } } while (0)
; #define BLOAD(A_, B_, kt) do { _Pragma("unroll") for (int i = 0; i < 4; ++i) { \
;     A_[i] = *(const u32x4*)((const char*)Ap + (aoff + (unsigned)(32 * i * lda + (kt) * 64) * 2u)); B_[i] = *(const u32x4*)((const char*)Wt + (woff + (unsigned)(32 * i * K + (kt) * 64) * 2u)); } } while (0)
; #define BSTORE(A_, B_, buf) do { _Pragma("unroll") for (int i = 0; i < 4; ++i) { \
;     *(u32x4*)&As[(buf) * GBUF + (srow + 32 * i) * LDT + sc8] = A_[i]; \
;     *(u32x4*)&Bs[(buf) * GBUF + (srow + 32 * i) * LDT + sc8] = B_[i]; } } while (0)
; template <int NK>
; DI void gemm_run(PF& pf, const u16* __restrict__ Ap, int lda, const u16* __restrict__ Wt, f32x16 (&acc)[2][2], char* smem) {
;     ...
;   __builtin_amdgcn_s_setprio(0);
;   __syncthreads();
;   BSTORE(pf.a0, pf.b0, 0);
;   BLOAD(pf.a0, pf.b0, 2);
;   __syncthreads();
; #pragma unroll
;   for (int kt = 0; kt < nk; kt += 2) {
;     BCOMP(0);
;     BSTORE(pf.a1, pf.b1, 1);
;     if (kt + 3 < nk) BLOAD(pf.a1, pf.b1, kt + 3);
;     __syncthreads();
;     BCOMP(1);
;     if (kt + 2 < nk) { BSTORE(pf.a0, pf.b0, 0); if (kt + 4 < nk) BLOAD(pf.a0, pf.b0, kt + 4); }
;     __syncthreads();
	s_setprio 1
	ds_read_b128 v[208:211], v138 offset:16384
	ds_read_b128 v[224:227], v140 offset:32768
	ds_read_b128 v[228:231], v140 offset:33792
	ds_read_b128 v[232:235], v140 offset:34816
	ds_read_b128 v[236:239], v140 offset:35840
	ds_read_b128 v[212:215], v138 offset:18432
	ds_read_b128 v[216:219], v138 offset:20480
	ds_read_b128 v[220:223], v138 offset:22528
	ds_read_b128 v[240:243], v140 offset:40960
	ds_read_b128 v[244:247], v140 offset:41984
	ds_read_b128 v[248:251], v140 offset:43008
	ds_read_b128 v[156:159], v140 offset:44032
	s_add_u32 m0, s43, 0x4000
	s_add_u32 s30, s30, 0x40000
	s_addc_u32 s31, s31, 0
	global_load_lds_dwordx4 v144, s[30:31]
	global_load_lds_dwordx4 v145, s[30:31] offset:1024
	global_load_lds_dwordx4 v146, s[30:31] offset:2048
	global_load_lds_dwordx4 v147, s[30:31] offset:3072
	s_add_u32 m0, s42, 0x0
	s_add_u32 s28, s28, 0x80
	s_addc_u32 s29, s29, 0
	global_load_lds_dwordx4 v142, s[28:29]
	global_load_lds_dwordx4 v143, s[28:29] offset:1024
	global_load_lds_dwordx4 v154, s[28:29] offset:2048
	global_load_lds_dwordx4 v155, s[28:29] offset:3072
	s_waitcnt lgkmcnt(10)
	v_mfma_f32_16x16x32_bf16 v[2:5], v[208:211], v[224:227], v[2:5]
	s_waitcnt lgkmcnt(9)
	v_mfma_f32_16x16x32_bf16 v[6:9], v[208:211], v[228:231], v[6:9]
	s_waitcnt lgkmcnt(8)
	v_mfma_f32_16x16x32_bf16 v[10:13], v[208:211], v[232:235], v[10:13]
	s_waitcnt lgkmcnt(7)
	v_mfma_f32_16x16x32_bf16 v[14:17], v[208:211], v[236:239], v[14:17]
	s_waitcnt lgkmcnt(6)
	v_mfma_f32_16x16x32_bf16 v[18:21], v[212:215], v[224:227], v[18:21]
	v_mfma_f32_16x16x32_bf16 v[22:25], v[212:215], v[228:231], v[22:25]
	v_mfma_f32_16x16x32_bf16 v[26:29], v[212:215], v[232:235], v[26:29]
	v_mfma_f32_16x16x32_bf16 v[30:33], v[212:215], v[236:239], v[30:33]
	s_waitcnt lgkmcnt(5)
	v_mfma_f32_16x16x32_bf16 v[34:37], v[216:219], v[224:227], v[34:37]
	v_mfma_f32_16x16x32_bf16 v[38:41], v[216:219], v[228:231], v[38:41]
	v_mfma_f32_16x16x32_bf16 v[42:45], v[216:219], v[232:235], v[42:45]
	v_mfma_f32_16x16x32_bf16 v[46:49], v[216:219], v[236:239], v[46:49]
	s_waitcnt lgkmcnt(4)
	v_mfma_f32_16x16x32_bf16 v[50:53], v[220:223], v[224:227], v[50:53]
	v_mfma_f32_16x16x32_bf16 v[54:57], v[220:223], v[228:231], v[54:57]
	v_mfma_f32_16x16x32_bf16 v[58:61], v[220:223], v[232:235], v[58:61]
	v_mfma_f32_16x16x32_bf16 v[62:65], v[220:223], v[236:239], v[62:65]
	s_waitcnt lgkmcnt(3)
	v_mfma_f32_16x16x32_bf16 v[74:77], v[208:211], v[240:243], v[74:77]
	s_waitcnt lgkmcnt(2)
	v_mfma_f32_16x16x32_bf16 v[78:81], v[208:211], v[244:247], v[78:81]
	s_waitcnt lgkmcnt(1)
	v_mfma_f32_16x16x32_bf16 v[82:85], v[208:211], v[248:251], v[82:85]
	s_waitcnt lgkmcnt(0)
	v_mfma_f32_16x16x32_bf16 v[86:89], v[208:211], v[156:159], v[86:89]
	v_mfma_f32_16x16x32_bf16 v[90:93], v[212:215], v[240:243], v[90:93]
	v_mfma_f32_16x16x32_bf16 v[94:97], v[212:215], v[244:247], v[94:97]
	v_mfma_f32_16x16x32_bf16 v[98:101], v[212:215], v[248:251], v[98:101]
	v_mfma_f32_16x16x32_bf16 v[102:105], v[212:215], v[156:159], v[102:105]
	v_mfma_f32_16x16x32_bf16 v[106:109], v[216:219], v[240:243], v[106:109]
	v_mfma_f32_16x16x32_bf16 v[110:113], v[216:219], v[244:247], v[110:113]
	v_mfma_f32_16x16x32_bf16 v[114:117], v[216:219], v[248:251], v[114:117]
	v_mfma_f32_16x16x32_bf16 v[118:121], v[216:219], v[156:159], v[118:121]
	v_mfma_f32_16x16x32_bf16 v[122:125], v[220:223], v[240:243], v[122:125]
	v_mfma_f32_16x16x32_bf16 v[126:129], v[220:223], v[244:247], v[126:129]
	v_mfma_f32_16x16x32_bf16 v[130:133], v[220:223], v[248:251], v[130:133]
	v_mfma_f32_16x16x32_bf16 v[134:137], v[220:223], v[156:159], v[134:137]
	s_setprio 0
	s_waitcnt vmcnt(8)
	s_barrier
	s_setprio 1
	ds_read_b128 v[208:211], v139 offset:16384
	ds_read_b128 v[224:227], v140 offset:0
	ds_read_b128 v[228:231], v140 offset:1024
	ds_read_b128 v[232:235], v140 offset:2048
	ds_read_b128 v[236:239], v140 offset:3072
	ds_read_b128 v[212:215], v139 offset:18432
	ds_read_b128 v[216:219], v139 offset:20480
	ds_read_b128 v[220:223], v139 offset:22528
	ds_read_b128 v[240:243], v140 offset:8192
	ds_read_b128 v[244:247], v140 offset:9216
	ds_read_b128 v[248:251], v140 offset:10240
	ds_read_b128 v[156:159], v140 offset:11264
	s_add_u32 m0, s43, 0x8000
	s_add_u32 s30, s30, 0x40000
	s_addc_u32 s31, s31, 0
	global_load_lds_dwordx4 v144, s[30:31]
	global_load_lds_dwordx4 v145, s[30:31] offset:1024
	global_load_lds_dwordx4 v146, s[30:31] offset:2048
	global_load_lds_dwordx4 v147, s[30:31] offset:3072
	s_waitcnt lgkmcnt(10)
	v_mfma_f32_16x16x32_bf16 v[2:5], v[208:211], v[224:227], v[2:5]
	s_waitcnt lgkmcnt(9)
	v_mfma_f32_16x16x32_bf16 v[6:9], v[208:211], v[228:231], v[6:9]
	s_waitcnt lgkmcnt(8)
	v_mfma_f32_16x16x32_bf16 v[10:13], v[208:211], v[232:235], v[10:13]
	s_waitcnt lgkmcnt(7)
	v_mfma_f32_16x16x32_bf16 v[14:17], v[208:211], v[236:239], v[14:17]
	s_waitcnt lgkmcnt(6)
	v_mfma_f32_16x16x32_bf16 v[18:21], v[212:215], v[224:227], v[18:21]
	v_mfma_f32_16x16x32_bf16 v[22:25], v[212:215], v[228:231], v[22:25]
	v_mfma_f32_16x16x32_bf16 v[26:29], v[212:215], v[232:235], v[26:29]
	v_mfma_f32_16x16x32_bf16 v[30:33], v[212:215], v[236:239], v[30:33]
	s_waitcnt lgkmcnt(5)
	v_mfma_f32_16x16x32_bf16 v[34:37], v[216:219], v[224:227], v[34:37]
	v_mfma_f32_16x16x32_bf16 v[38:41], v[216:219], v[228:231], v[38:41]
	v_mfma_f32_16x16x32_bf16 v[42:45], v[216:219], v[232:235], v[42:45]
	v_mfma_f32_16x16x32_bf16 v[46:49], v[216:219], v[236:239], v[46:49]
	s_waitcnt lgkmcnt(4)
	v_mfma_f32_16x16x32_bf16 v[50:53], v[220:223], v[224:227], v[50:53]
	v_mfma_f32_16x16x32_bf16 v[54:57], v[220:223], v[228:231], v[54:57]
	v_mfma_f32_16x16x32_bf16 v[58:61], v[220:223], v[232:235], v[58:61]
	v_mfma_f32_16x16x32_bf16 v[62:65], v[220:223], v[236:239], v[62:65]
	s_waitcnt lgkmcnt(3)
	v_mfma_f32_16x16x32_bf16 v[74:77], v[208:211], v[240:243], v[74:77]
	s_waitcnt lgkmcnt(2)
	v_mfma_f32_16x16x32_bf16 v[78:81], v[208:211], v[244:247], v[78:81]
	s_waitcnt lgkmcnt(1)
	v_mfma_f32_16x16x32_bf16 v[82:85], v[208:211], v[248:251], v[82:85]
	s_waitcnt lgkmcnt(0)
	v_mfma_f32_16x16x32_bf16 v[86:89], v[208:211], v[156:159], v[86:89]
	v_mfma_f32_16x16x32_bf16 v[90:93], v[212:215], v[240:243], v[90:93]
	v_mfma_f32_16x16x32_bf16 v[94:97], v[212:215], v[244:247], v[94:97]
	v_mfma_f32_16x16x32_bf16 v[98:101], v[212:215], v[248:251], v[98:101]
	v_mfma_f32_16x16x32_bf16 v[102:105], v[212:215], v[156:159], v[102:105]
	v_mfma_f32_16x16x32_bf16 v[106:109], v[216:219], v[240:243], v[106:109]
	v_mfma_f32_16x16x32_bf16 v[110:113], v[216:219], v[244:247], v[110:113]
	v_mfma_f32_16x16x32_bf16 v[114:117], v[216:219], v[248:251], v[114:117]
	v_mfma_f32_16x16x32_bf16 v[118:121], v[216:219], v[156:159], v[118:121]
	v_mfma_f32_16x16x32_bf16 v[122:125], v[220:223], v[240:243], v[122:125]
	v_mfma_f32_16x16x32_bf16 v[126:129], v[220:223], v[244:247], v[126:129]
	v_mfma_f32_16x16x32_bf16 v[130:133], v[220:223], v[248:251], v[130:133]
	v_mfma_f32_16x16x32_bf16 v[134:137], v[220:223], v[156:159], v[134:137]
	s_setprio 0
	s_waitcnt vmcnt(4)
	s_barrier
; #define BLOAD(A_, B_, kt) do { _Pragma("unroll") for (int i = 0; i < 4; ++i) { \
;     A_[i] = *(const u32x4*)((const char*)Ap + (aoff + (unsigned)(32 * i * lda + (kt) * 64) * 2u)); B_[i] = *(const u32x4*)((const char*)Wt + (woff + (unsigned)(32 * i * K + (kt) * 64) * 2u)); } } while (0)
; #define BLOAD(A_, B_, kt) do { _Pragma("unroll") for (int i = 0; i < 4; ++i) { \
;     A_[i] = *(const u32x4*)((const char*)Ap + (aoff + (unsigned)(32 * i * lda + (kt) * 64) * 2u)); B_[i] = *(const u32x4*)((const char*)Wt + (woff + (unsigned)(32 * i * K + (kt) * 64) * 2u)); } } while (0)
; #define BSTORE(A_, B_, buf) do { _Pragma("unroll") for (int i = 0; i < 4; ++i) { \
;     *(u32x4*)&As[(buf) * GBUF + (srow + 32 * i) * LDT + sc8] = A_[i]; \
;     *(u32x4*)&Bs[(buf) * GBUF + (srow + 32 * i) * LDT + sc8] = B_[i]; } } while (0)
; template <int NK>
; DI void gemm_run(PF& pf, const u16* __restrict__ Ap, int lda, const u16* __restrict__ Wt, f32x16 (&acc)[2][2], char* smem) {
;     ...
;   __builtin_amdgcn_s_setprio(0);
;   __syncthreads();
;   BSTORE(pf.a0, pf.b0, 0);
;   BLOAD(pf.a0, pf.b0, 2);
;   __syncthreads();
; #pragma unroll
;   for (int kt = 0; kt < nk; kt += 2) {
;     BCOMP(0);
;     BSTORE(pf.a1, pf.b1, 1);
;     if (kt + 3 < nk) BLOAD(pf.a1, pf.b1, kt + 3);
;     __syncthreads();
;     BCOMP(1);
;     if (kt + 2 < nk) { BSTORE(pf.a0, pf.b0, 0); if (kt + 4 < nk) BLOAD(pf.a0, pf.b0, kt + 4); }
;     __syncthreads();
	s_setprio 1
	ds_read_b128 v[208:211], v138 offset:0
	ds_read_b128 v[224:227], v140 offset:16384
	ds_read_b128 v[228:231], v140 offset:17408
	ds_read_b128 v[232:235], v140 offset:18432
	ds_read_b128 v[236:239], v140 offset:19456
	ds_read_b128 v[212:215], v138 offset:2048
	ds_read_b128 v[216:219], v138 offset:4096
	ds_read_b128 v[220:223], v138 offset:6144
	ds_read_b128 v[240:243], v140 offset:24576
	ds_read_b128 v[244:247], v140 offset:25600
	ds_read_b128 v[248:251], v140 offset:26624
	ds_read_b128 v[156:159], v140 offset:27648
	s_add_u32 m0, s43, 0x0
	s_add_u32 s30, s30, 0x40000
	s_addc_u32 s31, s31, 0
	global_load_lds_dwordx4 v144, s[30:31]
	global_load_lds_dwordx4 v145, s[30:31] offset:1024
	global_load_lds_dwordx4 v146, s[30:31] offset:2048
	global_load_lds_dwordx4 v147, s[30:31] offset:3072
	s_add_u32 m0, s42, 0x4000
	s_add_u32 s28, s28, 0x80
	s_addc_u32 s29, s29, 0
	global_load_lds_dwordx4 v142, s[28:29]
	global_load_lds_dwordx4 v143, s[28:29] offset:1024
	global_load_lds_dwordx4 v154, s[28:29] offset:2048
	global_load_lds_dwordx4 v155, s[28:29] offset:3072
	s_waitcnt lgkmcnt(10)
	v_mfma_f32_16x16x32_bf16 v[2:5], v[208:211], v[224:227], v[2:5]
	s_waitcnt lgkmcnt(9)
	v_mfma_f32_16x16x32_bf16 v[6:9], v[208:211], v[228:231], v[6:9]
	s_waitcnt lgkmcnt(8)
	v_mfma_f32_16x16x32_bf16 v[10:13], v[208:211], v[232:235], v[10:13]
	s_waitcnt lgkmcnt(7)
	v_mfma_f32_16x16x32_bf16 v[14:17], v[208:211], v[236:239], v[14:17]
	s_waitcnt lgkmcnt(6)
	v_mfma_f32_16x16x32_bf16 v[18:21], v[212:215], v[224:227], v[18:21]
	v_mfma_f32_16x16x32_bf16 v[22:25], v[212:215], v[228:231], v[22:25]
	v_mfma_f32_16x16x32_bf16 v[26:29], v[212:215], v[232:235], v[26:29]
	v_mfma_f32_16x16x32_bf16 v[30:33], v[212:215], v[236:239], v[30:33]
	s_waitcnt lgkmcnt(5)
	v_mfma_f32_16x16x32_bf16 v[34:37], v[216:219], v[224:227], v[34:37]
	v_mfma_f32_16x16x32_bf16 v[38:41], v[216:219], v[228:231], v[38:41]
	v_mfma_f32_16x16x32_bf16 v[42:45], v[216:219], v[232:235], v[42:45]
	v_mfma_f32_16x16x32_bf16 v[46:49], v[216:219], v[236:239], v[46:49]
	s_waitcnt lgkmcnt(4)
	v_mfma_f32_16x16x32_bf16 v[50:53], v[220:223], v[224:227], v[50:53]
	v_mfma_f32_16x16x32_bf16 v[54:57], v[220:223], v[228:231], v[54:57]
	v_mfma_f32_16x16x32_bf16 v[58:61], v[220:223], v[232:235], v[58:61]
	v_mfma_f32_16x16x32_bf16 v[62:65], v[220:223], v[236:239], v[62:65]
	s_waitcnt lgkmcnt(3)
	v_mfma_f32_16x16x32_bf16 v[74:77], v[208:211], v[240:243], v[74:77]
	s_waitcnt lgkmcnt(2)
	v_mfma_f32_16x16x32_bf16 v[78:81], v[208:211], v[244:247], v[78:81]
	s_waitcnt lgkmcnt(1)
	v_mfma_f32_16x16x32_bf16 v[82:85], v[208:211], v[248:251], v[82:85]
	s_waitcnt lgkmcnt(0)
	v_mfma_f32_16x16x32_bf16 v[86:89], v[208:211], v[156:159], v[86:89]
	v_mfma_f32_16x16x32_bf16 v[90:93], v[212:215], v[240:243], v[90:93]
	v_mfma_f32_16x16x32_bf16 v[94:97], v[212:215], v[244:247], v[94:97]
	v_mfma_f32_16x16x32_bf16 v[98:101], v[212:215], v[248:251], v[98:101]
	v_mfma_f32_16x16x32_bf16 v[102:105], v[212:215], v[156:159], v[102:105]
	v_mfma_f32_16x16x32_bf16 v[106:109], v[216:219], v[240:243], v[106:109]
	v_mfma_f32_16x16x32_bf16 v[110:113], v[216:219], v[244:247], v[110:113]
	v_mfma_f32_16x16x32_bf16 v[114:117], v[216:219], v[248:251], v[114:117]
	v_mfma_f32_16x16x32_bf16 v[118:121], v[216:219], v[156:159], v[118:121]
	v_mfma_f32_16x16x32_bf16 v[122:125], v[220:223], v[240:243], v[122:125]
	v_mfma_f32_16x16x32_bf16 v[126:129], v[220:223], v[244:247], v[126:129]
	v_mfma_f32_16x16x32_bf16 v[130:133], v[220:223], v[248:251], v[130:133]
	v_mfma_f32_16x16x32_bf16 v[134:137], v[220:223], v[156:159], v[134:137]
	s_setprio 0
	s_waitcnt vmcnt(8)
	s_barrier
	s_setprio 1
	ds_read_b128 v[208:211], v139 offset:0
	ds_read_b128 v[224:227], v140 offset:32768
	ds_read_b128 v[228:231], v140 offset:33792
	ds_read_b128 v[232:235], v140 offset:34816
	ds_read_b128 v[236:239], v140 offset:35840
	ds_read_b128 v[212:215], v139 offset:2048
	ds_read_b128 v[216:219], v139 offset:4096
	ds_read_b128 v[220:223], v139 offset:6144
	ds_read_b128 v[240:243], v140 offset:40960
	ds_read_b128 v[244:247], v140 offset:41984
	ds_read_b128 v[248:251], v140 offset:43008
	ds_read_b128 v[156:159], v140 offset:44032
	s_add_u32 m0, s43, 0x4000
	s_add_u32 s30, s30, 0x40000
	s_addc_u32 s31, s31, 0
	global_load_lds_dwordx4 v144, s[30:31]
	global_load_lds_dwordx4 v145, s[30:31] offset:1024
	global_load_lds_dwordx4 v146, s[30:31] offset:2048
	global_load_lds_dwordx4 v147, s[30:31] offset:3072
	s_waitcnt lgkmcnt(10)
	v_mfma_f32_16x16x32_bf16 v[2:5], v[208:211], v[224:227], v[2:5]
	s_waitcnt lgkmcnt(9)
	v_mfma_f32_16x16x32_bf16 v[6:9], v[208:211], v[228:231], v[6:9]
	s_waitcnt lgkmcnt(8)
	v_mfma_f32_16x16x32_bf16 v[10:13], v[208:211], v[232:235], v[10:13]
	s_waitcnt lgkmcnt(7)
	v_mfma_f32_16x16x32_bf16 v[14:17], v[208:211], v[236:239], v[14:17]
	s_waitcnt lgkmcnt(6)
	v_mfma_f32_16x16x32_bf16 v[18:21], v[212:215], v[224:227], v[18:21]
	v_mfma_f32_16x16x32_bf16 v[22:25], v[212:215], v[228:231], v[22:25]
	v_mfma_f32_16x16x32_bf16 v[26:29], v[212:215], v[232:235], v[26:29]
	v_mfma_f32_16x16x32_bf16 v[30:33], v[212:215], v[236:239], v[30:33]
	s_waitcnt lgkmcnt(5)
	v_mfma_f32_16x16x32_bf16 v[34:37], v[216:219], v[224:227], v[34:37]
	v_mfma_f32_16x16x32_bf16 v[38:41], v[216:219], v[228:231], v[38:41]
	v_mfma_f32_16x16x32_bf16 v[42:45], v[216:219], v[232:235], v[42:45]
	v_mfma_f32_16x16x32_bf16 v[46:49], v[216:219], v[236:239], v[46:49]
	s_waitcnt lgkmcnt(4)
	v_mfma_f32_16x16x32_bf16 v[50:53], v[220:223], v[224:227], v[50:53]
	v_mfma_f32_16x16x32_bf16 v[54:57], v[220:223], v[228:231], v[54:57]
	v_mfma_f32_16x16x32_bf16 v[58:61], v[220:223], v[232:235], v[58:61]
	v_mfma_f32_16x16x32_bf16 v[62:65], v[220:223], v[236:239], v[62:65]
	s_waitcnt lgkmcnt(3)
	v_mfma_f32_16x16x32_bf16 v[74:77], v[208:211], v[240:243], v[74:77]
	s_waitcnt lgkmcnt(2)
	v_mfma_f32_16x16x32_bf16 v[78:81], v[208:211], v[244:247], v[78:81]
	s_waitcnt lgkmcnt(1)
	v_mfma_f32_16x16x32_bf16 v[82:85], v[208:211], v[248:251], v[82:85]
	s_waitcnt lgkmcnt(0)
	v_mfma_f32_16x16x32_bf16 v[86:89], v[208:211], v[156:159], v[86:89]
	v_mfma_f32_16x16x32_bf16 v[90:93], v[212:215], v[240:243], v[90:93]
	v_mfma_f32_16x16x32_bf16 v[94:97], v[212:215], v[244:247], v[94:97]
	v_mfma_f32_16x16x32_bf16 v[98:101], v[212:215], v[248:251], v[98:101]
	v_mfma_f32_16x16x32_bf16 v[102:105], v[212:215], v[156:159], v[102:105]
	v_mfma_f32_16x16x32_bf16 v[106:109], v[216:219], v[240:243], v[106:109]
	v_mfma_f32_16x16x32_bf16 v[110:113], v[216:219], v[244:247], v[110:113]
	v_mfma_f32_16x16x32_bf16 v[114:117], v[216:219], v[248:251], v[114:117]
	v_mfma_f32_16x16x32_bf16 v[118:121], v[216:219], v[156:159], v[118:121]
	v_mfma_f32_16x16x32_bf16 v[122:125], v[220:223], v[240:243], v[122:125]
	v_mfma_f32_16x16x32_bf16 v[126:129], v[220:223], v[244:247], v[126:129]
	v_mfma_f32_16x16x32_bf16 v[130:133], v[220:223], v[248:251], v[130:133]
	v_mfma_f32_16x16x32_bf16 v[134:137], v[220:223], v[156:159], v[134:137]
	s_setprio 0
	s_waitcnt vmcnt(4)
	s_barrier
; #define BLOAD(A_, B_, kt) do { _Pragma("unroll") for (int i = 0; i < 4; ++i) { \
;     A_[i] = *(const u32x4*)((const char*)Ap + (aoff + (unsigned)(32 * i * lda + (kt) * 64) * 2u)); B_[i] = *(const u32x4*)((const char*)Wt + (woff + (unsigned)(32 * i * K + (kt) * 64) * 2u)); } } while (0)
; #define BLOAD(A_, B_, kt) do { _Pragma("unroll") for (int i = 0; i < 4; ++i) { \
;     A_[i] = *(const u32x4*)((const char*)Ap + (aoff + (unsigned)(32 * i * lda + (kt) * 64) * 2u)); B_[i] = *(const u32x4*)((const char*)Wt + (woff + (unsigned)(32 * i * K + (kt) * 64) * 2u)); } } while (0)
; #define BSTORE(A_, B_, buf) do { _Pragma("unroll") for (int i = 0; i < 4; ++i) { \
;     *(u32x4*)&As[(buf) * GBUF + (srow + 32 * i) * LDT + sc8] = A_[i]; \
;     *(u32x4*)&Bs[(buf) * GBUF + (srow + 32 * i) * LDT + sc8] = B_[i]; } } while (0)
; template <int NK>
; DI void gemm_run(PF& pf, const u16* __restrict__ Ap, int lda, const u16* __restrict__ Wt, f32x16 (&acc)[2][2], char* smem) {
;     ...
;   __builtin_amdgcn_s_setprio(0);
;   __syncthreads();
;   BSTORE(pf.a0, pf.b0, 0);
;   BLOAD(pf.a0, pf.b0, 2);
;   __syncthreads();
; #pragma unroll
;   for (int kt = 0; kt < nk; kt += 2) {
;     BCOMP(0);
;     BSTORE(pf.a1, pf.b1, 1);
;     if (kt + 3 < nk) BLOAD(pf.a1, pf.b1, kt + 3);
;     __syncthreads();
;     BCOMP(1);
;     if (kt + 2 < nk) { BSTORE(pf.a0, pf.b0, 0); if (kt + 4 < nk) BLOAD(pf.a0, pf.b0, kt + 4); }
;     __syncthreads();
	s_setprio 1
	ds_read_b128 v[208:211], v138 offset:16384
	ds_read_b128 v[224:227], v140 offset:0
	ds_read_b128 v[228:231], v140 offset:1024
	ds_read_b128 v[232:235], v140 offset:2048
	ds_read_b128 v[236:239], v140 offset:3072
	ds_read_b128 v[212:215], v138 offset:18432
	ds_read_b128 v[216:219], v138 offset:20480
	ds_read_b128 v[220:223], v138 offset:22528
	ds_read_b128 v[240:243], v140 offset:8192
	ds_read_b128 v[244:247], v140 offset:9216
	ds_read_b128 v[248:251], v140 offset:10240
	ds_read_b128 v[156:159], v140 offset:11264
	s_add_u32 m0, s43, 0x8000
	s_add_u32 s30, s30, 0x40000
	s_addc_u32 s31, s31, 0
	global_load_lds_dwordx4 v144, s[30:31]
	global_load_lds_dwordx4 v145, s[30:31] offset:1024
	global_load_lds_dwordx4 v146, s[30:31] offset:2048
	global_load_lds_dwordx4 v147, s[30:31] offset:3072
	s_add_u32 m0, s42, 0x0
	s_add_u32 s28, s28, 0x80
	s_addc_u32 s29, s29, 0
	global_load_lds_dwordx4 v142, s[28:29]
	global_load_lds_dwordx4 v143, s[28:29] offset:1024
	global_load_lds_dwordx4 v154, s[28:29] offset:2048
	global_load_lds_dwordx4 v155, s[28:29] offset:3072
	s_waitcnt lgkmcnt(10)
	v_mfma_f32_16x16x32_bf16 v[2:5], v[208:211], v[224:227], v[2:5]
	s_waitcnt lgkmcnt(9)
	v_mfma_f32_16x16x32_bf16 v[6:9], v[208:211], v[228:231], v[6:9]
	s_waitcnt lgkmcnt(8)
	v_mfma_f32_16x16x32_bf16 v[10:13], v[208:211], v[232:235], v[10:13]
	s_waitcnt lgkmcnt(7)
	v_mfma_f32_16x16x32_bf16 v[14:17], v[208:211], v[236:239], v[14:17]
	s_waitcnt lgkmcnt(6)
	v_mfma_f32_16x16x32_bf16 v[18:21], v[212:215], v[224:227], v[18:21]
	v_mfma_f32_16x16x32_bf16 v[22:25], v[212:215], v[228:231], v[22:25]
	v_mfma_f32_16x16x32_bf16 v[26:29], v[212:215], v[232:235], v[26:29]
	v_mfma_f32_16x16x32_bf16 v[30:33], v[212:215], v[236:239], v[30:33]
	s_waitcnt lgkmcnt(5)
	v_mfma_f32_16x16x32_bf16 v[34:37], v[216:219], v[224:227], v[34:37]
	v_mfma_f32_16x16x32_bf16 v[38:41], v[216:219], v[228:231], v[38:41]
	v_mfma_f32_16x16x32_bf16 v[42:45], v[216:219], v[232:235], v[42:45]
	v_mfma_f32_16x16x32_bf16 v[46:49], v[216:219], v[236:239], v[46:49]
	s_waitcnt lgkmcnt(4)
	v_mfma_f32_16x16x32_bf16 v[50:53], v[220:223], v[224:227], v[50:53]
	v_mfma_f32_16x16x32_bf16 v[54:57], v[220:223], v[228:231], v[54:57]
	v_mfma_f32_16x16x32_bf16 v[58:61], v[220:223], v[232:235], v[58:61]
	v_mfma_f32_16x16x32_bf16 v[62:65], v[220:223], v[236:239], v[62:65]
	s_waitcnt lgkmcnt(3)
	v_mfma_f32_16x16x32_bf16 v[74:77], v[208:211], v[240:243], v[74:77]
	s_waitcnt lgkmcnt(2)
	v_mfma_f32_16x16x32_bf16 v[78:81], v[208:211], v[244:247], v[78:81]
	s_waitcnt lgkmcnt(1)
	v_mfma_f32_16x16x32_bf16 v[82:85], v[208:211], v[248:251], v[82:85]
	s_waitcnt lgkmcnt(0)
	v_mfma_f32_16x16x32_bf16 v[86:89], v[208:211], v[156:159], v[86:89]
	v_mfma_f32_16x16x32_bf16 v[90:93], v[212:215], v[240:243], v[90:93]
	v_mfma_f32_16x16x32_bf16 v[94:97], v[212:215], v[244:247], v[94:97]
	v_mfma_f32_16x16x32_bf16 v[98:101], v[212:215], v[248:251], v[98:101]
	v_mfma_f32_16x16x32_bf16 v[102:105], v[212:215], v[156:159], v[102:105]
	v_mfma_f32_16x16x32_bf16 v[106:109], v[216:219], v[240:243], v[106:109]
	v_mfma_f32_16x16x32_bf16 v[110:113], v[216:219], v[244:247], v[110:113]
	v_mfma_f32_16x16x32_bf16 v[114:117], v[216:219], v[248:251], v[114:117]
	v_mfma_f32_16x16x32_bf16 v[118:121], v[216:219], v[156:159], v[118:121]
	v_mfma_f32_16x16x32_bf16 v[122:125], v[220:223], v[240:243], v[122:125]
	v_mfma_f32_16x16x32_bf16 v[126:129], v[220:223], v[244:247], v[126:129]
	v_mfma_f32_16x16x32_bf16 v[130:133], v[220:223], v[248:251], v[130:133]
	v_mfma_f32_16x16x32_bf16 v[134:137], v[220:223], v[156:159], v[134:137]
	s_setprio 0
	s_waitcnt vmcnt(8)
	s_barrier
	s_setprio 1
	ds_read_b128 v[208:211], v139 offset:16384
	ds_read_b128 v[224:227], v140 offset:16384
	ds_read_b128 v[228:231], v140 offset:17408
	ds_read_b128 v[232:235], v140 offset:18432
	ds_read_b128 v[236:239], v140 offset:19456
	ds_read_b128 v[212:215], v139 offset:18432
	ds_read_b128 v[216:219], v139 offset:20480
	ds_read_b128 v[220:223], v139 offset:22528
	ds_read_b128 v[240:243], v140 offset:24576
	ds_read_b128 v[244:247], v140 offset:25600
	ds_read_b128 v[248:251], v140 offset:26624
	ds_read_b128 v[156:159], v140 offset:27648
	s_add_u32 m0, s43, 0x0
	s_add_u32 s30, s30, 0x40000
	s_addc_u32 s31, s31, 0
	global_load_lds_dwordx4 v144, s[30:31]
	global_load_lds_dwordx4 v145, s[30:31] offset:1024
	global_load_lds_dwordx4 v146, s[30:31] offset:2048
	global_load_lds_dwordx4 v147, s[30:31] offset:3072
	s_waitcnt lgkmcnt(10)
	v_mfma_f32_16x16x32_bf16 v[2:5], v[208:211], v[224:227], v[2:5]
	s_waitcnt lgkmcnt(9)
	v_mfma_f32_16x16x32_bf16 v[6:9], v[208:211], v[228:231], v[6:9]
	s_waitcnt lgkmcnt(8)
	v_mfma_f32_16x16x32_bf16 v[10:13], v[208:211], v[232:235], v[10:13]
	s_waitcnt lgkmcnt(7)
	v_mfma_f32_16x16x32_bf16 v[14:17], v[208:211], v[236:239], v[14:17]
	s_waitcnt lgkmcnt(6)
	v_mfma_f32_16x16x32_bf16 v[18:21], v[212:215], v[224:227], v[18:21]
	v_mfma_f32_16x16x32_bf16 v[22:25], v[212:215], v[228:231], v[22:25]
	v_mfma_f32_16x16x32_bf16 v[26:29], v[212:215], v[232:235], v[26:29]
	v_mfma_f32_16x16x32_bf16 v[30:33], v[212:215], v[236:239], v[30:33]
	s_waitcnt lgkmcnt(5)
	v_mfma_f32_16x16x32_bf16 v[34:37], v[216:219], v[224:227], v[34:37]
	v_mfma_f32_16x16x32_bf16 v[38:41], v[216:219], v[228:231], v[38:41]
	v_mfma_f32_16x16x32_bf16 v[42:45], v[216:219], v[232:235], v[42:45]
	v_mfma_f32_16x16x32_bf16 v[46:49], v[216:219], v[236:239], v[46:49]
	s_waitcnt lgkmcnt(4)
	v_mfma_f32_16x16x32_bf16 v[50:53], v[220:223], v[224:227], v[50:53]
	v_mfma_f32_16x16x32_bf16 v[54:57], v[220:223], v[228:231], v[54:57]
	v_mfma_f32_16x16x32_bf16 v[58:61], v[220:223], v[232:235], v[58:61]
	v_mfma_f32_16x16x32_bf16 v[62:65], v[220:223], v[236:239], v[62:65]
	s_waitcnt lgkmcnt(3)
	v_mfma_f32_16x16x32_bf16 v[74:77], v[208:211], v[240:243], v[74:77]
	s_waitcnt lgkmcnt(2)
	v_mfma_f32_16x16x32_bf16 v[78:81], v[208:211], v[244:247], v[78:81]
	s_waitcnt lgkmcnt(1)
	v_mfma_f32_16x16x32_bf16 v[82:85], v[208:211], v[248:251], v[82:85]
	s_waitcnt lgkmcnt(0)
	v_mfma_f32_16x16x32_bf16 v[86:89], v[208:211], v[156:159], v[86:89]
	v_mfma_f32_16x16x32_bf16 v[90:93], v[212:215], v[240:243], v[90:93]
	v_mfma_f32_16x16x32_bf16 v[94:97], v[212:215], v[244:247], v[94:97]
	v_mfma_f32_16x16x32_bf16 v[98:101], v[212:215], v[248:251], v[98:101]
	v_mfma_f32_16x16x32_bf16 v[102:105], v[212:215], v[156:159], v[102:105]
	v_mfma_f32_16x16x32_bf16 v[106:109], v[216:219], v[240:243], v[106:109]
	v_mfma_f32_16x16x32_bf16 v[110:113], v[216:219], v[244:247], v[110:113]
	v_mfma_f32_16x16x32_bf16 v[114:117], v[216:219], v[248:251], v[114:117]
	v_mfma_f32_16x16x32_bf16 v[118:121], v[216:219], v[156:159], v[118:121]
	v_mfma_f32_16x16x32_bf16 v[122:125], v[220:223], v[240:243], v[122:125]
	v_mfma_f32_16x16x32_bf16 v[126:129], v[220:223], v[244:247], v[126:129]
	v_mfma_f32_16x16x32_bf16 v[130:133], v[220:223], v[248:251], v[130:133]
	v_mfma_f32_16x16x32_bf16 v[134:137], v[220:223], v[156:159], v[134:137]
	s_setprio 0
	s_waitcnt vmcnt(4)
	s_barrier
; #define BLOAD(A_, B_, kt) do { _Pragma("unroll") for (int i = 0; i < 4; ++i) { \
;     A_[i] = *(const u32x4*)((const char*)Ap + (aoff + (unsigned)(32 * i * lda + (kt) * 64) * 2u)); B_[i] = *(const u32x4*)((const char*)Wt + (woff + (unsigned)(32 * i * K + (kt) * 64) * 2u)); } } while (0)
; #define BLOAD(A_, B_, kt) do { _Pragma("unroll") for (int i = 0; i < 4; ++i) { \
;     A_[i] = *(const u32x4*)((const char*)Ap + (aoff + (unsigned)(32 * i * lda + (kt) * 64) * 2u)); B_[i] = *(const u32x4*)((const char*)Wt + (woff + (unsigned)(32 * i * K + (kt) * 64) * 2u)); } } while (0)
; #define BSTORE(A_, B_, buf) do { _Pragma("unroll") for (int i = 0; i < 4; ++i) { \
;     *(u32x4*)&As[(buf) * GBUF + (srow + 32 * i) * LDT + sc8] = A_[i]; \
;     *(u32x4*)&Bs[(buf) * GBUF + (srow + 32 * i) * LDT + sc8] = B_[i]; } } while (0)
; template <int NK>
; DI void gemm_run(PF& pf, const u16* __restrict__ Ap, int lda, const u16* __restrict__ Wt, f32x16 (&acc)[2][2], char* smem) {
;     ...
;   __builtin_amdgcn_s_setprio(0);
;   __syncthreads();
;   BSTORE(pf.a0, pf.b0, 0);
;   BLOAD(pf.a0, pf.b0, 2);
;   __syncthreads();
; #pragma unroll
;   for (int kt = 0; kt < nk; kt += 2) {
;     BCOMP(0);
;     BSTORE(pf.a1, pf.b1, 1);
;     if (kt + 3 < nk) BLOAD(pf.a1, pf.b1, kt + 3);
;     __syncthreads();
;     BCOMP(1);
;     if (kt + 2 < nk) { BSTORE(pf.a0, pf.b0, 0); if (kt + 4 < nk) BLOAD(pf.a0, pf.b0, kt + 4); }
;     __syncthreads();
	s_setprio 1
	ds_read_b128 v[208:211], v138 offset:0
	ds_read_b128 v[224:227], v140 offset:32768
	ds_read_b128 v[228:231], v140 offset:33792
	ds_read_b128 v[232:235], v140 offset:34816
	ds_read_b128 v[236:239], v140 offset:35840
	ds_read_b128 v[212:215], v138 offset:2048
	ds_read_b128 v[216:219], v138 offset:4096
	ds_read_b128 v[220:223], v138 offset:6144
	ds_read_b128 v[240:243], v140 offset:40960
	ds_read_b128 v[244:247], v140 offset:41984
	ds_read_b128 v[248:251], v140 offset:43008
	ds_read_b128 v[156:159], v140 offset:44032
	s_add_u32 m0, s43, 0x4000
	s_add_u32 s30, s30, 0x40000
	s_addc_u32 s31, s31, 0
	global_load_lds_dwordx4 v144, s[30:31]
	global_load_lds_dwordx4 v145, s[30:31] offset:1024
	global_load_lds_dwordx4 v146, s[30:31] offset:2048
	global_load_lds_dwordx4 v147, s[30:31] offset:3072
	s_add_u32 m0, s42, 0x4000
	s_add_u32 s28, s28, 0x80
	s_addc_u32 s29, s29, 0
	global_load_lds_dwordx4 v142, s[28:29]
	global_load_lds_dwordx4 v143, s[28:29] offset:1024
	global_load_lds_dwordx4 v154, s[28:29] offset:2048
	global_load_lds_dwordx4 v155, s[28:29] offset:3072
	s_waitcnt lgkmcnt(10)
	v_mfma_f32_16x16x32_bf16 v[2:5], v[208:211], v[224:227], v[2:5]
	s_waitcnt lgkmcnt(9)
	v_mfma_f32_16x16x32_bf16 v[6:9], v[208:211], v[228:231], v[6:9]
	s_waitcnt lgkmcnt(8)
	v_mfma_f32_16x16x32_bf16 v[10:13], v[208:211], v[232:235], v[10:13]
	s_waitcnt lgkmcnt(7)
	v_mfma_f32_16x16x32_bf16 v[14:17], v[208:211], v[236:239], v[14:17]
	s_waitcnt lgkmcnt(6)
	v_mfma_f32_16x16x32_bf16 v[18:21], v[212:215], v[224:227], v[18:21]
	v_mfma_f32_16x16x32_bf16 v[22:25], v[212:215], v[228:231], v[22:25]
	v_mfma_f32_16x16x32_bf16 v[26:29], v[212:215], v[232:235], v[26:29]
	v_mfma_f32_16x16x32_bf16 v[30:33], v[212:215], v[236:239], v[30:33]
	s_waitcnt lgkmcnt(5)
	v_mfma_f32_16x16x32_bf16 v[34:37], v[216:219], v[224:227], v[34:37]
	v_mfma_f32_16x16x32_bf16 v[38:41], v[216:219], v[228:231], v[38:41]
	v_mfma_f32_16x16x32_bf16 v[42:45], v[216:219], v[232:235], v[42:45]
	v_mfma_f32_16x16x32_bf16 v[46:49], v[216:219], v[236:239], v[46:49]
	s_waitcnt lgkmcnt(4)
	v_mfma_f32_16x16x32_bf16 v[50:53], v[220:223], v[224:227], v[50:53]
	v_mfma_f32_16x16x32_bf16 v[54:57], v[220:223], v[228:231], v[54:57]
	v_mfma_f32_16x16x32_bf16 v[58:61], v[220:223], v[232:235], v[58:61]
	v_mfma_f32_16x16x32_bf16 v[62:65], v[220:223], v[236:239], v[62:65]
	s_waitcnt lgkmcnt(3)
	v_mfma_f32_16x16x32_bf16 v[74:77], v[208:211], v[240:243], v[74:77]
	s_waitcnt lgkmcnt(2)
	v_mfma_f32_16x16x32_bf16 v[78:81], v[208:211], v[244:247], v[78:81]
	s_waitcnt lgkmcnt(1)
	v_mfma_f32_16x16x32_bf16 v[82:85], v[208:211], v[248:251], v[82:85]
	s_waitcnt lgkmcnt(0)
	v_mfma_f32_16x16x32_bf16 v[86:89], v[208:211], v[156:159], v[86:89]
	v_mfma_f32_16x16x32_bf16 v[90:93], v[212:215], v[240:243], v[90:93]
	v_mfma_f32_16x16x32_bf16 v[94:97], v[212:215], v[244:247], v[94:97]
	v_mfma_f32_16x16x32_bf16 v[98:101], v[212:215], v[248:251], v[98:101]
	v_mfma_f32_16x16x32_bf16 v[102:105], v[212:215], v[156:159], v[102:105]
	v_mfma_f32_16x16x32_bf16 v[106:109], v[216:219], v[240:243], v[106:109]
	v_mfma_f32_16x16x32_bf16 v[110:113], v[216:219], v[244:247], v[110:113]
	v_mfma_f32_16x16x32_bf16 v[114:117], v[216:219], v[248:251], v[114:117]
	v_mfma_f32_16x16x32_bf16 v[118:121], v[216:219], v[156:159], v[118:121]
	v_mfma_f32_16x16x32_bf16 v[122:125], v[220:223], v[240:243], v[122:125]
	v_mfma_f32_16x16x32_bf16 v[126:129], v[220:223], v[244:247], v[126:129]
	v_mfma_f32_16x16x32_bf16 v[130:133], v[220:223], v[248:251], v[130:133]
	v_mfma_f32_16x16x32_bf16 v[134:137], v[220:223], v[156:159], v[134:137]
	s_setprio 0
	s_waitcnt vmcnt(8)
	s_barrier
	s_setprio 1
	ds_read_b128 v[208:211], v139 offset:0
	ds_read_b128 v[224:227], v140 offset:0
	ds_read_b128 v[228:231], v140 offset:1024
	ds_read_b128 v[232:235], v140 offset:2048
	ds_read_b128 v[236:239], v140 offset:3072
	ds_read_b128 v[212:215], v139 offset:2048
	ds_read_b128 v[216:219], v139 offset:4096
	ds_read_b128 v[220:223], v139 offset:6144
	ds_read_b128 v[240:243], v140 offset:8192
	ds_read_b128 v[244:247], v140 offset:9216
	ds_read_b128 v[248:251], v140 offset:10240
	ds_read_b128 v[156:159], v140 offset:11264
	s_add_u32 m0, s43, 0x8000
	s_add_u32 s30, s30, 0x40000
	s_addc_u32 s31, s31, 0
	global_load_lds_dwordx4 v144, s[30:31]
	global_load_lds_dwordx4 v145, s[30:31] offset:1024
	global_load_lds_dwordx4 v146, s[30:31] offset:2048
	global_load_lds_dwordx4 v147, s[30:31] offset:3072
	s_waitcnt lgkmcnt(10)
	v_mfma_f32_16x16x32_bf16 v[2:5], v[208:211], v[224:227], v[2:5]
	s_waitcnt lgkmcnt(9)
	v_mfma_f32_16x16x32_bf16 v[6:9], v[208:211], v[228:231], v[6:9]
	s_waitcnt lgkmcnt(8)
	v_mfma_f32_16x16x32_bf16 v[10:13], v[208:211], v[232:235], v[10:13]
	s_waitcnt lgkmcnt(7)
	v_mfma_f32_16x16x32_bf16 v[14:17], v[208:211], v[236:239], v[14:17]
	s_waitcnt lgkmcnt(6)
	v_mfma_f32_16x16x32_bf16 v[18:21], v[212:215], v[224:227], v[18:21]
	v_mfma_f32_16x16x32_bf16 v[22:25], v[212:215], v[228:231], v[22:25]
	v_mfma_f32_16x16x32_bf16 v[26:29], v[212:215], v[232:235], v[26:29]
	v_mfma_f32_16x16x32_bf16 v[30:33], v[212:215], v[236:239], v[30:33]
	s_waitcnt lgkmcnt(5)
	v_mfma_f32_16x16x32_bf16 v[34:37], v[216:219], v[224:227], v[34:37]
	v_mfma_f32_16x16x32_bf16 v[38:41], v[216:219], v[228:231], v[38:41]
	v_mfma_f32_16x16x32_bf16 v[42:45], v[216:219], v[232:235], v[42:45]
	v_mfma_f32_16x16x32_bf16 v[46:49], v[216:219], v[236:239], v[46:49]
	s_waitcnt lgkmcnt(4)
	v_mfma_f32_16x16x32_bf16 v[50:53], v[220:223], v[224:227], v[50:53]
	v_mfma_f32_16x16x32_bf16 v[54:57], v[220:223], v[228:231], v[54:57]
	v_mfma_f32_16x16x32_bf16 v[58:61], v[220:223], v[232:235], v[58:61]
	v_mfma_f32_16x16x32_bf16 v[62:65], v[220:223], v[236:239], v[62:65]
	s_waitcnt lgkmcnt(3)
	v_mfma_f32_16x16x32_bf16 v[74:77], v[208:211], v[240:243], v[74:77]
	s_waitcnt lgkmcnt(2)
	v_mfma_f32_16x16x32_bf16 v[78:81], v[208:211], v[244:247], v[78:81]
	s_waitcnt lgkmcnt(1)
	v_mfma_f32_16x16x32_bf16 v[82:85], v[208:211], v[248:251], v[82:85]
	s_waitcnt lgkmcnt(0)
	v_mfma_f32_16x16x32_bf16 v[86:89], v[208:211], v[156:159], v[86:89]
	v_mfma_f32_16x16x32_bf16 v[90:93], v[212:215], v[240:243], v[90:93]
	v_mfma_f32_16x16x32_bf16 v[94:97], v[212:215], v[244:247], v[94:97]
	v_mfma_f32_16x16x32_bf16 v[98:101], v[212:215], v[248:251], v[98:101]
	v_mfma_f32_16x16x32_bf16 v[102:105], v[212:215], v[156:159], v[102:105]
	v_mfma_f32_16x16x32_bf16 v[106:109], v[216:219], v[240:243], v[106:109]
	v_mfma_f32_16x16x32_bf16 v[110:113], v[216:219], v[244:247], v[110:113]
	v_mfma_f32_16x16x32_bf16 v[114:117], v[216:219], v[248:251], v[114:117]
	v_mfma_f32_16x16x32_bf16 v[118:121], v[216:219], v[156:159], v[118:121]
	v_mfma_f32_16x16x32_bf16 v[122:125], v[220:223], v[240:243], v[122:125]
	v_mfma_f32_16x16x32_bf16 v[126:129], v[220:223], v[244:247], v[126:129]
	v_mfma_f32_16x16x32_bf16 v[130:133], v[220:223], v[248:251], v[130:133]
	v_mfma_f32_16x16x32_bf16 v[134:137], v[220:223], v[156:159], v[134:137]
	s_setprio 0
	s_waitcnt vmcnt(4)
	s_barrier
; #define BLOAD(A_, B_, kt) do { _Pragma("unroll") for (int i = 0; i < 4; ++i) { \
;     A_[i] = *(const u32x4*)((const char*)Ap + (aoff + (unsigned)(32 * i * lda + (kt) * 64) * 2u)); B_[i] = *(const u32x4*)((const char*)Wt + (woff + (unsigned)(32 * i * K + (kt) * 64) * 2u)); } } while (0)
; #define BLOAD(A_, B_, kt) do { _Pragma("unroll") for (int i = 0; i < 4; ++i) { \
;     A_[i] = *(const u32x4*)((const char*)Ap + (aoff + (unsigned)(32 * i * lda + (kt) * 64) * 2u)); B_[i] = *(const u32x4*)((const char*)Wt + (woff + (unsigned)(32 * i * K + (kt) * 64) * 2u)); } } while (0)
; #define BSTORE(A_, B_, buf) do { _Pragma("unroll") for (int i = 0; i < 4; ++i) { \
;     *(u32x4*)&As[(buf) * GBUF + (srow + 32 * i) * LDT + sc8] = A_[i]; \
;     *(u32x4*)&Bs[(buf) * GBUF + (srow + 32 * i) * LDT + sc8] = B_[i]; } } while (0)
; template <int NK>
; DI void gemm_run(PF& pf, const u16* __restrict__ Ap, int lda, const u16* __restrict__ Wt, f32x16 (&acc)[2][2], char* smem) {
;     ...
;   __builtin_amdgcn_s_setprio(0);
;   __syncthreads();
;   BSTORE(pf.a0, pf.b0, 0);
;   BLOAD(pf.a0, pf.b0, 2);
;   __syncthreads();
; #pragma unroll
;   for (int kt = 0; kt < nk; kt += 2) {
;     BCOMP(0);
;     BSTORE(pf.a1, pf.b1, 1);
;     if (kt + 3 < nk) BLOAD(pf.a1, pf.b1, kt + 3);
;     __syncthreads();
;     BCOMP(1);
;     if (kt + 2 < nk) { BSTORE(pf.a0, pf.b0, 0); if (kt + 4 < nk) BLOAD(pf.a0, pf.b0, kt + 4); }
;     __syncthreads();
;   }
	s_setprio 1
	ds_read_b128 v[208:211], v138 offset:16384
	ds_read_b128 v[224:227], v140 offset:16384
	ds_read_b128 v[228:231], v140 offset:17408
	ds_read_b128 v[232:235], v140 offset:18432
	ds_read_b128 v[236:239], v140 offset:19456
	ds_read_b128 v[212:215], v138 offset:18432
	ds_read_b128 v[216:219], v138 offset:20480
	ds_read_b128 v[220:223], v138 offset:22528
	ds_read_b128 v[240:243], v140 offset:24576
	ds_read_b128 v[244:247], v140 offset:25600
	ds_read_b128 v[248:251], v140 offset:26624
	ds_read_b128 v[156:159], v140 offset:27648
	s_add_u32 m0, s43, 0x0
	s_add_u32 s30, s30, 0x40000
	s_addc_u32 s31, s31, 0
	global_load_lds_dwordx4 v144, s[30:31]
	global_load_lds_dwordx4 v145, s[30:31] offset:1024
	global_load_lds_dwordx4 v146, s[30:31] offset:2048
	global_load_lds_dwordx4 v147, s[30:31] offset:3072
	s_add_u32 m0, s42, 0x0
	s_add_u32 s28, s28, 0x80
	s_addc_u32 s29, s29, 0
	global_load_lds_dwordx4 v142, s[28:29]
	global_load_lds_dwordx4 v143, s[28:29] offset:1024
	global_load_lds_dwordx4 v154, s[28:29] offset:2048
	global_load_lds_dwordx4 v155, s[28:29] offset:3072
	s_waitcnt lgkmcnt(10)
	v_mfma_f32_16x16x32_bf16 v[2:5], v[208:211], v[224:227], v[2:5]
	s_waitcnt lgkmcnt(9)
	v_mfma_f32_16x16x32_bf16 v[6:9], v[208:211], v[228:231], v[6:9]
	s_waitcnt lgkmcnt(8)
	v_mfma_f32_16x16x32_bf16 v[10:13], v[208:211], v[232:235], v[10:13]
	s_waitcnt lgkmcnt(7)
	v_mfma_f32_16x16x32_bf16 v[14:17], v[208:211], v[236:239], v[14:17]
	s_waitcnt lgkmcnt(6)
	v_mfma_f32_16x16x32_bf16 v[18:21], v[212:215], v[224:227], v[18:21]
	v_mfma_f32_16x16x32_bf16 v[22:25], v[212:215], v[228:231], v[22:25]
	v_mfma_f32_16x16x32_bf16 v[26:29], v[212:215], v[232:235], v[26:29]
	v_mfma_f32_16x16x32_bf16 v[30:33], v[212:215], v[236:239], v[30:33]
	s_waitcnt lgkmcnt(5)
	v_mfma_f32_16x16x32_bf16 v[34:37], v[216:219], v[224:227], v[34:37]
	v_mfma_f32_16x16x32_bf16 v[38:41], v[216:219], v[228:231], v[38:41]
	v_mfma_f32_16x16x32_bf16 v[42:45], v[216:219], v[232:235], v[42:45]
	v_mfma_f32_16x16x32_bf16 v[46:49], v[216:219], v[236:239], v[46:49]
	s_waitcnt lgkmcnt(4)
	v_mfma_f32_16x16x32_bf16 v[50:53], v[220:223], v[224:227], v[50:53]
	v_mfma_f32_16x16x32_bf16 v[54:57], v[220:223], v[228:231], v[54:57]
	v_mfma_f32_16x16x32_bf16 v[58:61], v[220:223], v[232:235], v[58:61]
	v_mfma_f32_16x16x32_bf16 v[62:65], v[220:223], v[236:239], v[62:65]
	s_waitcnt lgkmcnt(3)
	v_mfma_f32_16x16x32_bf16 v[74:77], v[208:211], v[240:243], v[74:77]
	s_waitcnt lgkmcnt(2)
	v_mfma_f32_16x16x32_bf16 v[78:81], v[208:211], v[244:247], v[78:81]
	s_waitcnt lgkmcnt(1)
	v_mfma_f32_16x16x32_bf16 v[82:85], v[208:211], v[248:251], v[82:85]
	s_waitcnt lgkmcnt(0)
	v_mfma_f32_16x16x32_bf16 v[86:89], v[208:211], v[156:159], v[86:89]
	v_mfma_f32_16x16x32_bf16 v[90:93], v[212:215], v[240:243], v[90:93]
	v_mfma_f32_16x16x32_bf16 v[94:97], v[212:215], v[244:247], v[94:97]
	v_mfma_f32_16x16x32_bf16 v[98:101], v[212:215], v[248:251], v[98:101]
	v_mfma_f32_16x16x32_bf16 v[102:105], v[212:215], v[156:159], v[102:105]
	v_mfma_f32_16x16x32_bf16 v[106:109], v[216:219], v[240:243], v[106:109]
	v_mfma_f32_16x16x32_bf16 v[110:113], v[216:219], v[244:247], v[110:113]
	v_mfma_f32_16x16x32_bf16 v[114:117], v[216:219], v[248:251], v[114:117]
	v_mfma_f32_16x16x32_bf16 v[118:121], v[216:219], v[156:159], v[118:121]
	v_mfma_f32_16x16x32_bf16 v[122:125], v[220:223], v[240:243], v[122:125]
	v_mfma_f32_16x16x32_bf16 v[126:129], v[220:223], v[244:247], v[126:129]
	v_mfma_f32_16x16x32_bf16 v[130:133], v[220:223], v[248:251], v[130:133]
	v_mfma_f32_16x16x32_bf16 v[134:137], v[220:223], v[156:159], v[134:137]
	s_setprio 0
	s_waitcnt vmcnt(8)
	s_barrier
	s_setprio 1
	ds_read_b128 v[208:211], v139 offset:16384
	ds_read_b128 v[224:227], v140 offset:32768
	ds_read_b128 v[228:231], v140 offset:33792
	ds_read_b128 v[232:235], v140 offset:34816
	ds_read_b128 v[236:239], v140 offset:35840
	ds_read_b128 v[212:215], v139 offset:18432
	ds_read_b128 v[216:219], v139 offset:20480
	ds_read_b128 v[220:223], v139 offset:22528
	ds_read_b128 v[240:243], v140 offset:40960
	ds_read_b128 v[244:247], v140 offset:41984
	ds_read_b128 v[248:251], v140 offset:43008
	ds_read_b128 v[156:159], v140 offset:44032
	s_add_u32 m0, s43, 0x4000
	s_add_u32 s30, s30, 0x40000
	s_addc_u32 s31, s31, 0
	global_load_lds_dwordx4 v144, s[30:31]
	global_load_lds_dwordx4 v145, s[30:31] offset:1024
	global_load_lds_dwordx4 v146, s[30:31] offset:2048
	global_load_lds_dwordx4 v147, s[30:31] offset:3072
	s_waitcnt lgkmcnt(10)
	v_mfma_f32_16x16x32_bf16 v[2:5], v[208:211], v[224:227], v[2:5]
	s_waitcnt lgkmcnt(9)
	v_mfma_f32_16x16x32_bf16 v[6:9], v[208:211], v[228:231], v[6:9]
	s_waitcnt lgkmcnt(8)
	v_mfma_f32_16x16x32_bf16 v[10:13], v[208:211], v[232:235], v[10:13]
	s_waitcnt lgkmcnt(7)
	v_mfma_f32_16x16x32_bf16 v[14:17], v[208:211], v[236:239], v[14:17]
	s_waitcnt lgkmcnt(6)
	v_mfma_f32_16x16x32_bf16 v[18:21], v[212:215], v[224:227], v[18:21]
	v_mfma_f32_16x16x32_bf16 v[22:25], v[212:215], v[228:231], v[22:25]
	v_mfma_f32_16x16x32_bf16 v[26:29], v[212:215], v[232:235], v[26:29]
	v_mfma_f32_16x16x32_bf16 v[30:33], v[212:215], v[236:239], v[30:33]
	s_waitcnt lgkmcnt(5)
	v_mfma_f32_16x16x32_bf16 v[34:37], v[216:219], v[224:227], v[34:37]
	v_mfma_f32_16x16x32_bf16 v[38:41], v[216:219], v[228:231], v[38:41]
	v_mfma_f32_16x16x32_bf16 v[42:45], v[216:219], v[232:235], v[42:45]
	v_mfma_f32_16x16x32_bf16 v[46:49], v[216:219], v[236:239], v[46:49]
	s_waitcnt lgkmcnt(4)
	v_mfma_f32_16x16x32_bf16 v[50:53], v[220:223], v[224:227], v[50:53]
	v_mfma_f32_16x16x32_bf16 v[54:57], v[220:223], v[228:231], v[54:57]
	v_mfma_f32_16x16x32_bf16 v[58:61], v[220:223], v[232:235], v[58:61]
	v_mfma_f32_16x16x32_bf16 v[62:65], v[220:223], v[236:239], v[62:65]
	s_waitcnt lgkmcnt(3)
	v_mfma_f32_16x16x32_bf16 v[74:77], v[208:211], v[240:243], v[74:77]
	s_waitcnt lgkmcnt(2)
	v_mfma_f32_16x16x32_bf16 v[78:81], v[208:211], v[244:247], v[78:81]
	s_waitcnt lgkmcnt(1)
	v_mfma_f32_16x16x32_bf16 v[82:85], v[208:211], v[248:251], v[82:85]
	s_waitcnt lgkmcnt(0)
	v_mfma_f32_16x16x32_bf16 v[86:89], v[208:211], v[156:159], v[86:89]
	v_mfma_f32_16x16x32_bf16 v[90:93], v[212:215], v[240:243], v[90:93]
	v_mfma_f32_16x16x32_bf16 v[94:97], v[212:215], v[244:247], v[94:97]
	v_mfma_f32_16x16x32_bf16 v[98:101], v[212:215], v[248:251], v[98:101]
	v_mfma_f32_16x16x32_bf16 v[102:105], v[212:215], v[156:159], v[102:105]
	v_mfma_f32_16x16x32_bf16 v[106:109], v[216:219], v[240:243], v[106:109]
	v_mfma_f32_16x16x32_bf16 v[110:113], v[216:219], v[244:247], v[110:113]
	v_mfma_f32_16x16x32_bf16 v[114:117], v[216:219], v[248:251], v[114:117]
	v_mfma_f32_16x16x32_bf16 v[118:121], v[216:219], v[156:159], v[118:121]
	v_mfma_f32_16x16x32_bf16 v[122:125], v[220:223], v[240:243], v[122:125]
	v_mfma_f32_16x16x32_bf16 v[126:129], v[220:223], v[244:247], v[126:129]
	v_mfma_f32_16x16x32_bf16 v[130:133], v[220:223], v[248:251], v[130:133]
	v_mfma_f32_16x16x32_bf16 v[134:137], v[220:223], v[156:159], v[134:137]
	s_setprio 0
	s_waitcnt vmcnt(4)
	s_barrier
; #define BLOAD(A_, B_, kt) do { _Pragma("unroll") for (int i = 0; i < 4; ++i) { \
;     A_[i] = *(const u32x4*)((const char*)Ap + (aoff + (unsigned)(32 * i * lda + (kt) * 64) * 2u)); B_[i] = *(const u32x4*)((const char*)Wt + (woff + (unsigned)(32 * i * K + (kt) * 64) * 2u)); } } while (0)
; #define BLOAD(A_, B_, kt) do { _Pragma("unroll") for (int i = 0; i < 4; ++i) { \
;     A_[i] = *(const u32x4*)((const char*)Ap + (aoff + (unsigned)(32 * i * lda + (kt) * 64) * 2u)); B_[i] = *(const u32x4*)((const char*)Wt + (woff + (unsigned)(32 * i * K + (kt) * 64) * 2u)); } } while (0)
; #define BSTORE(A_, B_, buf) do { _Pragma("unroll") for (int i = 0; i < 4; ++i) { \
;     *(u32x4*)&As[(buf) * GBUF + (srow + 32 * i) * LDT + sc8] = A_[i]; \
;     *(u32x4*)&Bs[(buf) * GBUF + (srow + 32 * i) * LDT + sc8] = B_[i]; } } while (0)
; template <int NK>
; DI void gemm_run(PF& pf, const u16* __restrict__ Ap, int lda, const u16* __restrict__ Wt, f32x16 (&acc)[2][2], char* smem) {
;     ...
;   __builtin_amdgcn_s_setprio(0);
;   __syncthreads();
;   BSTORE(pf.a0, pf.b0, 0);
;   BLOAD(pf.a0, pf.b0, 2);
;   __syncthreads();
; #pragma unroll
;   for (int kt = 0; kt < nk; kt += 2) {
;     BCOMP(0);
;     BSTORE(pf.a1, pf.b1, 1);
;     if (kt + 3 < nk) BLOAD(pf.a1, pf.b1, kt + 3);
;     __syncthreads();
;     BCOMP(1);
;     if (kt + 2 < nk) { BSTORE(pf.a0, pf.b0, 0); if (kt + 4 < nk) BLOAD(pf.a0, pf.b0, kt + 4); }
;     __syncthreads();
;   }
	s_setprio 1
	ds_read_b128 v[208:211], v138 offset:0
	ds_read_b128 v[224:227], v140 offset:0
	ds_read_b128 v[228:231], v140 offset:1024
	ds_read_b128 v[232:235], v140 offset:2048
	ds_read_b128 v[236:239], v140 offset:3072
	ds_read_b128 v[212:215], v138 offset:2048
	ds_read_b128 v[216:219], v138 offset:4096
	ds_read_b128 v[220:223], v138 offset:6144
	ds_read_b128 v[240:243], v140 offset:8192
	ds_read_b128 v[244:247], v140 offset:9216
	ds_read_b128 v[248:251], v140 offset:10240
	ds_read_b128 v[156:159], v140 offset:11264
	s_add_u32 m0, s43, 0x8000
	s_add_u32 s30, s30, 0x40000
	s_addc_u32 s31, s31, 0
	global_load_lds_dwordx4 v144, s[30:31]
	global_load_lds_dwordx4 v145, s[30:31] offset:1024
	global_load_lds_dwordx4 v146, s[30:31] offset:2048
	global_load_lds_dwordx4 v147, s[30:31] offset:3072
	s_add_u32 m0, s42, 0x4000
	s_add_u32 s28, s28, 0x80
	s_addc_u32 s29, s29, 0
	global_load_lds_dwordx4 v142, s[28:29]
	global_load_lds_dwordx4 v143, s[28:29] offset:1024
	global_load_lds_dwordx4 v154, s[28:29] offset:2048
	global_load_lds_dwordx4 v155, s[28:29] offset:3072
	s_waitcnt lgkmcnt(10)
	v_mfma_f32_16x16x32_bf16 v[2:5], v[208:211], v[224:227], v[2:5]
	s_waitcnt lgkmcnt(9)
	v_mfma_f32_16x16x32_bf16 v[6:9], v[208:211], v[228:231], v[6:9]
	s_waitcnt lgkmcnt(8)
	v_mfma_f32_16x16x32_bf16 v[10:13], v[208:211], v[232:235], v[10:13]
	s_waitcnt lgkmcnt(7)
	v_mfma_f32_16x16x32_bf16 v[14:17], v[208:211], v[236:239], v[14:17]
	s_waitcnt lgkmcnt(6)
	v_mfma_f32_16x16x32_bf16 v[18:21], v[212:215], v[224:227], v[18:21]
	v_mfma_f32_16x16x32_bf16 v[22:25], v[212:215], v[228:231], v[22:25]
	v_mfma_f32_16x16x32_bf16 v[26:29], v[212:215], v[232:235], v[26:29]
	v_mfma_f32_16x16x32_bf16 v[30:33], v[212:215], v[236:239], v[30:33]
	s_waitcnt lgkmcnt(5)
	v_mfma_f32_16x16x32_bf16 v[34:37], v[216:219], v[224:227], v[34:37]
	v_mfma_f32_16x16x32_bf16 v[38:41], v[216:219], v[228:231], v[38:41]
	v_mfma_f32_16x16x32_bf16 v[42:45], v[216:219], v[232:235], v[42:45]
	v_mfma_f32_16x16x32_bf16 v[46:49], v[216:219], v[236:239], v[46:49]
	s_waitcnt lgkmcnt(4)
	v_mfma_f32_16x16x32_bf16 v[50:53], v[220:223], v[224:227], v[50:53]
	v_mfma_f32_16x16x32_bf16 v[54:57], v[220:223], v[228:231], v[54:57]
	v_mfma_f32_16x16x32_bf16 v[58:61], v[220:223], v[232:235], v[58:61]
	v_mfma_f32_16x16x32_bf16 v[62:65], v[220:223], v[236:239], v[62:65]
	s_waitcnt lgkmcnt(3)
	v_mfma_f32_16x16x32_bf16 v[74:77], v[208:211], v[240:243], v[74:77]
	s_waitcnt lgkmcnt(2)
	v_mfma_f32_16x16x32_bf16 v[78:81], v[208:211], v[244:247], v[78:81]
	s_waitcnt lgkmcnt(1)
	v_mfma_f32_16x16x32_bf16 v[82:85], v[208:211], v[248:251], v[82:85]
	s_waitcnt lgkmcnt(0)
	v_mfma_f32_16x16x32_bf16 v[86:89], v[208:211], v[156:159], v[86:89]
	v_mfma_f32_16x16x32_bf16 v[90:93], v[212:215], v[240:243], v[90:93]
	v_mfma_f32_16x16x32_bf16 v[94:97], v[212:215], v[244:247], v[94:97]
	v_mfma_f32_16x16x32_bf16 v[98:101], v[212:215], v[248:251], v[98:101]
	v_mfma_f32_16x16x32_bf16 v[102:105], v[212:215], v[156:159], v[102:105]
	v_mfma_f32_16x16x32_bf16 v[106:109], v[216:219], v[240:243], v[106:109]
	v_mfma_f32_16x16x32_bf16 v[110:113], v[216:219], v[244:247], v[110:113]
	v_mfma_f32_16x16x32_bf16 v[114:117], v[216:219], v[248:251], v[114:117]
	v_mfma_f32_16x16x32_bf16 v[118:121], v[216:219], v[156:159], v[118:121]
	v_mfma_f32_16x16x32_bf16 v[122:125], v[220:223], v[240:243], v[122:125]
	v_mfma_f32_16x16x32_bf16 v[126:129], v[220:223], v[244:247], v[126:129]
	v_mfma_f32_16x16x32_bf16 v[130:133], v[220:223], v[248:251], v[130:133]
	v_mfma_f32_16x16x32_bf16 v[134:137], v[220:223], v[156:159], v[134:137]
	s_setprio 0
	s_waitcnt vmcnt(8)
	s_barrier
	s_setprio 1
	ds_read_b128 v[208:211], v139 offset:0
	ds_read_b128 v[224:227], v140 offset:16384
	ds_read_b128 v[228:231], v140 offset:17408
	ds_read_b128 v[232:235], v140 offset:18432
	ds_read_b128 v[236:239], v140 offset:19456
	ds_read_b128 v[212:215], v139 offset:2048
	ds_read_b128 v[216:219], v139 offset:4096
	ds_read_b128 v[220:223], v139 offset:6144
	ds_read_b128 v[240:243], v140 offset:24576
	ds_read_b128 v[244:247], v140 offset:25600
	ds_read_b128 v[248:251], v140 offset:26624
	ds_read_b128 v[156:159], v140 offset:27648
	s_add_u32 m0, s43, 0x0
	s_add_u32 s30, s30, 0x40000
	s_addc_u32 s31, s31, 0
	global_load_lds_dwordx4 v144, s[30:31]
	global_load_lds_dwordx4 v145, s[30:31] offset:1024
	global_load_lds_dwordx4 v146, s[30:31] offset:2048
	global_load_lds_dwordx4 v147, s[30:31] offset:3072
	s_waitcnt lgkmcnt(10)
	v_mfma_f32_16x16x32_bf16 v[2:5], v[208:211], v[224:227], v[2:5]
	s_waitcnt lgkmcnt(9)
	v_mfma_f32_16x16x32_bf16 v[6:9], v[208:211], v[228:231], v[6:9]
	s_waitcnt lgkmcnt(8)
	v_mfma_f32_16x16x32_bf16 v[10:13], v[208:211], v[232:235], v[10:13]
	s_waitcnt lgkmcnt(7)
	v_mfma_f32_16x16x32_bf16 v[14:17], v[208:211], v[236:239], v[14:17]
	s_waitcnt lgkmcnt(6)
	v_mfma_f32_16x16x32_bf16 v[18:21], v[212:215], v[224:227], v[18:21]
	v_mfma_f32_16x16x32_bf16 v[22:25], v[212:215], v[228:231], v[22:25]
	v_mfma_f32_16x16x32_bf16 v[26:29], v[212:215], v[232:235], v[26:29]
	v_mfma_f32_16x16x32_bf16 v[30:33], v[212:215], v[236:239], v[30:33]
	s_waitcnt lgkmcnt(5)
	v_mfma_f32_16x16x32_bf16 v[34:37], v[216:219], v[224:227], v[34:37]
	v_mfma_f32_16x16x32_bf16 v[38:41], v[216:219], v[228:231], v[38:41]
	v_mfma_f32_16x16x32_bf16 v[42:45], v[216:219], v[232:235], v[42:45]
	v_mfma_f32_16x16x32_bf16 v[46:49], v[216:219], v[236:239], v[46:49]
	s_waitcnt lgkmcnt(4)
	v_mfma_f32_16x16x32_bf16 v[50:53], v[220:223], v[224:227], v[50:53]
	v_mfma_f32_16x16x32_bf16 v[54:57], v[220:223], v[228:231], v[54:57]
	v_mfma_f32_16x16x32_bf16 v[58:61], v[220:223], v[232:235], v[58:61]
	v_mfma_f32_16x16x32_bf16 v[62:65], v[220:223], v[236:239], v[62:65]
	s_waitcnt lgkmcnt(3)
	v_mfma_f32_16x16x32_bf16 v[74:77], v[208:211], v[240:243], v[74:77]
	s_waitcnt lgkmcnt(2)
	v_mfma_f32_16x16x32_bf16 v[78:81], v[208:211], v[244:247], v[78:81]
	s_waitcnt lgkmcnt(1)
	v_mfma_f32_16x16x32_bf16 v[82:85], v[208:211], v[248:251], v[82:85]
	s_waitcnt lgkmcnt(0)
	v_mfma_f32_16x16x32_bf16 v[86:89], v[208:211], v[156:159], v[86:89]
	v_mfma_f32_16x16x32_bf16 v[90:93], v[212:215], v[240:243], v[90:93]
	v_mfma_f32_16x16x32_bf16 v[94:97], v[212:215], v[244:247], v[94:97]
	v_mfma_f32_16x16x32_bf16 v[98:101], v[212:215], v[248:251], v[98:101]
	v_mfma_f32_16x16x32_bf16 v[102:105], v[212:215], v[156:159], v[102:105]
	v_mfma_f32_16x16x32_bf16 v[106:109], v[216:219], v[240:243], v[106:109]
	v_mfma_f32_16x16x32_bf16 v[110:113], v[216:219], v[244:247], v[110:113]
	v_mfma_f32_16x16x32_bf16 v[114:117], v[216:219], v[248:251], v[114:117]
	v_mfma_f32_16x16x32_bf16 v[118:121], v[216:219], v[156:159], v[118:121]
	v_mfma_f32_16x16x32_bf16 v[122:125], v[220:223], v[240:243], v[122:125]
	v_mfma_f32_16x16x32_bf16 v[126:129], v[220:223], v[244:247], v[126:129]
	v_mfma_f32_16x16x32_bf16 v[130:133], v[220:223], v[248:251], v[130:133]
	v_mfma_f32_16x16x32_bf16 v[134:137], v[220:223], v[156:159], v[134:137]
	s_setprio 0
	s_waitcnt vmcnt(4)
	s_barrier
; #define BLOAD(A_, B_, kt) do { _Pragma("unroll") for (int i = 0; i < 4; ++i) { \
;     A_[i] = *(const u32x4*)((const char*)Ap + (aoff + (unsigned)(32 * i * lda + (kt) * 64) * 2u)); B_[i] = *(const u32x4*)((const char*)Wt + (woff + (unsigned)(32 * i * K + (kt) * 64) * 2u)); } } while (0)
; #define BLOAD(A_, B_, kt) do { _Pragma("unroll") for (int i = 0; i < 4; ++i) { \
;     A_[i] = *(const u32x4*)((const char*)Ap + (aoff + (unsigned)(32 * i * lda + (kt) * 64) * 2u)); B_[i] = *(const u32x4*)((const char*)Wt + (woff + (unsigned)(32 * i * K + (kt) * 64) * 2u)); } } while (0)
; #define BSTORE(A_, B_, buf) do { _Pragma("unroll") for (int i = 0; i < 4; ++i) { \
;     *(u32x4*)&As[(buf) * GBUF + (srow + 32 * i) * LDT + sc8] = A_[i]; \
;     *(u32x4*)&Bs[(buf) * GBUF + (srow + 32 * i) * LDT + sc8] = B_[i]; } } while (0)
; template <int NK>
; DI void gemm_run(PF& pf, const u16* __restrict__ Ap, int lda, const u16* __restrict__ Wt, f32x16 (&acc)[2][2], char* smem) {
;     ...
;   __builtin_amdgcn_s_setprio(0);
;   __syncthreads();
;   BSTORE(pf.a0, pf.b0, 0);
;   BLOAD(pf.a0, pf.b0, 2);
;   __syncthreads();
; #pragma unroll
;   for (int kt = 0; kt < nk; kt += 2) {
;     BCOMP(0);
;     BSTORE(pf.a1, pf.b1, 1);
;     if (kt + 3 < nk) BLOAD(pf.a1, pf.b1, kt + 3);
;     __syncthreads();
;     BCOMP(1);
;     if (kt + 2 < nk) { BSTORE(pf.a0, pf.b0, 0); if (kt + 4 < nk) BLOAD(pf.a0, pf.b0, kt + 4); }
;     __syncthreads();
;   }
	s_setprio 1
	ds_read_b128 v[208:211], v138 offset:16384
	ds_read_b128 v[224:227], v140 offset:32768
	ds_read_b128 v[228:231], v140 offset:33792
	ds_read_b128 v[232:235], v140 offset:34816
	ds_read_b128 v[236:239], v140 offset:35840
	ds_read_b128 v[212:215], v138 offset:18432
	ds_read_b128 v[216:219], v138 offset:20480
	ds_read_b128 v[220:223], v138 offset:22528
	ds_read_b128 v[240:243], v140 offset:40960
	ds_read_b128 v[244:247], v140 offset:41984
	ds_read_b128 v[248:251], v140 offset:43008
	ds_read_b128 v[156:159], v140 offset:44032
	s_add_u32 m0, s43, 0x4000
	s_add_u32 s30, s30, 0x40000
	s_addc_u32 s31, s31, 0
	global_load_lds_dwordx4 v144, s[30:31]
	global_load_lds_dwordx4 v145, s[30:31] offset:1024
	global_load_lds_dwordx4 v146, s[30:31] offset:2048
	global_load_lds_dwordx4 v147, s[30:31] offset:3072
	s_add_u32 m0, s42, 0x0
	s_add_u32 s28, s28, 0x80
	s_addc_u32 s29, s29, 0
	global_load_lds_dwordx4 v142, s[28:29]
	global_load_lds_dwordx4 v143, s[28:29] offset:1024
	global_load_lds_dwordx4 v154, s[28:29] offset:2048
	global_load_lds_dwordx4 v155, s[28:29] offset:3072
	s_waitcnt lgkmcnt(10)
	v_mfma_f32_16x16x32_bf16 v[2:5], v[208:211], v[224:227], v[2:5]
	s_waitcnt lgkmcnt(9)
	v_mfma_f32_16x16x32_bf16 v[6:9], v[208:211], v[228:231], v[6:9]
	s_waitcnt lgkmcnt(8)
	v_mfma_f32_16x16x32_bf16 v[10:13], v[208:211], v[232:235], v[10:13]
	s_waitcnt lgkmcnt(7)
	v_mfma_f32_16x16x32_bf16 v[14:17], v[208:211], v[236:239], v[14:17]
	s_waitcnt lgkmcnt(6)
	v_mfma_f32_16x16x32_bf16 v[18:21], v[212:215], v[224:227], v[18:21]
	v_mfma_f32_16x16x32_bf16 v[22:25], v[212:215], v[228:231], v[22:25]
	v_mfma_f32_16x16x32_bf16 v[26:29], v[212:215], v[232:235], v[26:29]
	v_mfma_f32_16x16x32_bf16 v[30:33], v[212:215], v[236:239], v[30:33]
	s_waitcnt lgkmcnt(5)
	v_mfma_f32_16x16x32_bf16 v[34:37], v[216:219], v[224:227], v[34:37]
	v_mfma_f32_16x16x32_bf16 v[38:41], v[216:219], v[228:231], v[38:41]
	v_mfma_f32_16x16x32_bf16 v[42:45], v[216:219], v[232:235], v[42:45]
	v_mfma_f32_16x16x32_bf16 v[46:49], v[216:219], v[236:239], v[46:49]
	s_waitcnt lgkmcnt(4)
	v_mfma_f32_16x16x32_bf16 v[50:53], v[220:223], v[224:227], v[50:53]
	v_mfma_f32_16x16x32_bf16 v[54:57], v[220:223], v[228:231], v[54:57]
	v_mfma_f32_16x16x32_bf16 v[58:61], v[220:223], v[232:235], v[58:61]
	v_mfma_f32_16x16x32_bf16 v[62:65], v[220:223], v[236:239], v[62:65]
	s_waitcnt lgkmcnt(3)
	v_mfma_f32_16x16x32_bf16 v[74:77], v[208:211], v[240:243], v[74:77]
	s_waitcnt lgkmcnt(2)
	v_mfma_f32_16x16x32_bf16 v[78:81], v[208:211], v[244:247], v[78:81]
	s_waitcnt lgkmcnt(1)
	v_mfma_f32_16x16x32_bf16 v[82:85], v[208:211], v[248:251], v[82:85]
	s_waitcnt lgkmcnt(0)
	v_mfma_f32_16x16x32_bf16 v[86:89], v[208:211], v[156:159], v[86:89]
	v_mfma_f32_16x16x32_bf16 v[90:93], v[212:215], v[240:243], v[90:93]
	v_mfma_f32_16x16x32_bf16 v[94:97], v[212:215], v[244:247], v[94:97]
	v_mfma_f32_16x16x32_bf16 v[98:101], v[212:215], v[248:251], v[98:101]
	v_mfma_f32_16x16x32_bf16 v[102:105], v[212:215], v[156:159], v[102:105]
	v_mfma_f32_16x16x32_bf16 v[106:109], v[216:219], v[240:243], v[106:109]
	v_mfma_f32_16x16x32_bf16 v[110:113], v[216:219], v[244:247], v[110:113]
	v_mfma_f32_16x16x32_bf16 v[114:117], v[216:219], v[248:251], v[114:117]
	v_mfma_f32_16x16x32_bf16 v[118:121], v[216:219], v[156:159], v[118:121]
	v_mfma_f32_16x16x32_bf16 v[122:125], v[220:223], v[240:243], v[122:125]
	v_mfma_f32_16x16x32_bf16 v[126:129], v[220:223], v[244:247], v[126:129]
	v_mfma_f32_16x16x32_bf16 v[130:133], v[220:223], v[248:251], v[130:133]
	v_mfma_f32_16x16x32_bf16 v[134:137], v[220:223], v[156:159], v[134:137]
	s_setprio 0
	s_waitcnt vmcnt(8)
	s_barrier
	s_setprio 1
	ds_read_b128 v[208:211], v139 offset:16384
	ds_read_b128 v[224:227], v140 offset:0
	ds_read_b128 v[228:231], v140 offset:1024
	ds_read_b128 v[232:235], v140 offset:2048
	ds_read_b128 v[236:239], v140 offset:3072
	ds_read_b128 v[212:215], v139 offset:18432
	ds_read_b128 v[216:219], v139 offset:20480
	ds_read_b128 v[220:223], v139 offset:22528
	ds_read_b128 v[240:243], v140 offset:8192
	ds_read_b128 v[244:247], v140 offset:9216
	ds_read_b128 v[248:251], v140 offset:10240
	ds_read_b128 v[156:159], v140 offset:11264
	s_add_u32 m0, s43, 0x8000
	s_add_u32 s30, s30, 0x40000
	s_addc_u32 s31, s31, 0
	global_load_lds_dwordx4 v144, s[30:31]
	global_load_lds_dwordx4 v145, s[30:31] offset:1024
	global_load_lds_dwordx4 v146, s[30:31] offset:2048
	global_load_lds_dwordx4 v147, s[30:31] offset:3072
	s_waitcnt lgkmcnt(10)
	v_mfma_f32_16x16x32_bf16 v[2:5], v[208:211], v[224:227], v[2:5]
	s_waitcnt lgkmcnt(9)
	v_mfma_f32_16x16x32_bf16 v[6:9], v[208:211], v[228:231], v[6:9]
	s_waitcnt lgkmcnt(8)
	v_mfma_f32_16x16x32_bf16 v[10:13], v[208:211], v[232:235], v[10:13]
	s_waitcnt lgkmcnt(7)
	v_mfma_f32_16x16x32_bf16 v[14:17], v[208:211], v[236:239], v[14:17]
	s_waitcnt lgkmcnt(6)
	v_mfma_f32_16x16x32_bf16 v[18:21], v[212:215], v[224:227], v[18:21]
	v_mfma_f32_16x16x32_bf16 v[22:25], v[212:215], v[228:231], v[22:25]
	v_mfma_f32_16x16x32_bf16 v[26:29], v[212:215], v[232:235], v[26:29]
	v_mfma_f32_16x16x32_bf16 v[30:33], v[212:215], v[236:239], v[30:33]
	s_waitcnt lgkmcnt(5)
	v_mfma_f32_16x16x32_bf16 v[34:37], v[216:219], v[224:227], v[34:37]
	v_mfma_f32_16x16x32_bf16 v[38:41], v[216:219], v[228:231], v[38:41]
	v_mfma_f32_16x16x32_bf16 v[42:45], v[216:219], v[232:235], v[42:45]
	v_mfma_f32_16x16x32_bf16 v[46:49], v[216:219], v[236:239], v[46:49]
	s_waitcnt lgkmcnt(4)
	v_mfma_f32_16x16x32_bf16 v[50:53], v[220:223], v[224:227], v[50:53]
	v_mfma_f32_16x16x32_bf16 v[54:57], v[220:223], v[228:231], v[54:57]
	v_mfma_f32_16x16x32_bf16 v[58:61], v[220:223], v[232:235], v[58:61]
	v_mfma_f32_16x16x32_bf16 v[62:65], v[220:223], v[236:239], v[62:65]
	s_waitcnt lgkmcnt(3)
	v_mfma_f32_16x16x32_bf16 v[74:77], v[208:211], v[240:243], v[74:77]
	s_waitcnt lgkmcnt(2)
	v_mfma_f32_16x16x32_bf16 v[78:81], v[208:211], v[244:247], v[78:81]
	s_waitcnt lgkmcnt(1)
	v_mfma_f32_16x16x32_bf16 v[82:85], v[208:211], v[248:251], v[82:85]
	s_waitcnt lgkmcnt(0)
	v_mfma_f32_16x16x32_bf16 v[86:89], v[208:211], v[156:159], v[86:89]
	v_mfma_f32_16x16x32_bf16 v[90:93], v[212:215], v[240:243], v[90:93]
	v_mfma_f32_16x16x32_bf16 v[94:97], v[212:215], v[244:247], v[94:97]
	v_mfma_f32_16x16x32_bf16 v[98:101], v[212:215], v[248:251], v[98:101]
	v_mfma_f32_16x16x32_bf16 v[102:105], v[212:215], v[156:159], v[102:105]
	v_mfma_f32_16x16x32_bf16 v[106:109], v[216:219], v[240:243], v[106:109]
	v_mfma_f32_16x16x32_bf16 v[110:113], v[216:219], v[244:247], v[110:113]
	v_mfma_f32_16x16x32_bf16 v[114:117], v[216:219], v[248:251], v[114:117]
	v_mfma_f32_16x16x32_bf16 v[118:121], v[216:219], v[156:159], v[118:121]
	v_mfma_f32_16x16x32_bf16 v[122:125], v[220:223], v[240:243], v[122:125]
	v_mfma_f32_16x16x32_bf16 v[126:129], v[220:223], v[244:247], v[126:129]
	v_mfma_f32_16x16x32_bf16 v[130:133], v[220:223], v[248:251], v[130:133]
	v_mfma_f32_16x16x32_bf16 v[134:137], v[220:223], v[156:159], v[134:137]
	s_setprio 0
	s_waitcnt vmcnt(4)
	s_barrier
; #define BLOAD(A_, B_, kt) do { _Pragma("unroll") for (int i = 0; i < 4; ++i) { \
;     A_[i] = *(const u32x4*)((const char*)Ap + (aoff + (unsigned)(32 * i * lda + (kt) * 64) * 2u)); B_[i] = *(const u32x4*)((const char*)Wt + (woff + (unsigned)(32 * i * K + (kt) * 64) * 2u)); } } while (0)
; #define BLOAD(A_, B_, kt) do { _Pragma("unroll") for (int i = 0; i < 4; ++i) { \
;     A_[i] = *(const u32x4*)((const char*)Ap + (aoff + (unsigned)(32 * i * lda + (kt) * 64) * 2u)); B_[i] = *(const u32x4*)((const char*)Wt + (woff + (unsigned)(32 * i * K + (kt) * 64) * 2u)); } } while (0)
; #define BSTORE(A_, B_, buf) do { _Pragma("unroll") for (int i = 0; i < 4; ++i) { \
;     *(u32x4*)&As[(buf) * GBUF + (srow + 32 * i) * LDT + sc8] = A_[i]; \
;     *(u32x4*)&Bs[(buf) * GBUF + (srow + 32 * i) * LDT + sc8] = B_[i]; } } while (0)
; template <int NK>
; DI void gemm_run(PF& pf, const u16* __restrict__ Ap, int lda, const u16* __restrict__ Wt, f32x16 (&acc)[2][2], char* smem) {
;     ...
;   __builtin_amdgcn_s_setprio(0);
;   __syncthreads();
;   BSTORE(pf.a0, pf.b0, 0);
;   BLOAD(pf.a0, pf.b0, 2);
;   __syncthreads();
; #pragma unroll
;   for (int kt = 0; kt < nk; kt += 2) {
;     BCOMP(0);
;     BSTORE(pf.a1, pf.b1, 1);
;     if (kt + 3 < nk) BLOAD(pf.a1, pf.b1, kt + 3);
;     __syncthreads();
;     BCOMP(1);
;     if (kt + 2 < nk) { BSTORE(pf.a0, pf.b0, 0); if (kt + 4 < nk) BLOAD(pf.a0, pf.b0, kt + 4); }
;     __syncthreads();
;   }
	s_setprio 1
	ds_read_b128 v[208:211], v138 offset:0
	ds_read_b128 v[224:227], v140 offset:16384
	ds_read_b128 v[228:231], v140 offset:17408
	ds_read_b128 v[232:235], v140 offset:18432
	ds_read_b128 v[236:239], v140 offset:19456
	ds_read_b128 v[212:215], v138 offset:2048
	ds_read_b128 v[216:219], v138 offset:4096
	ds_read_b128 v[220:223], v138 offset:6144
	ds_read_b128 v[240:243], v140 offset:24576
	ds_read_b128 v[244:247], v140 offset:25600
	ds_read_b128 v[248:251], v140 offset:26624
	ds_read_b128 v[156:159], v140 offset:27648
	s_add_u32 m0, s43, 0x0
	s_add_u32 s30, s30, 0x40000
	s_addc_u32 s31, s31, 0
	global_load_lds_dwordx4 v144, s[30:31]
	global_load_lds_dwordx4 v145, s[30:31] offset:1024
	global_load_lds_dwordx4 v146, s[30:31] offset:2048
	global_load_lds_dwordx4 v147, s[30:31] offset:3072
	s_add_u32 m0, s42, 0x4000
	s_add_u32 s28, s28, 0x80
	s_addc_u32 s29, s29, 0
	global_load_lds_dwordx4 v142, s[28:29]
	global_load_lds_dwordx4 v143, s[28:29] offset:1024
	global_load_lds_dwordx4 v154, s[28:29] offset:2048
	global_load_lds_dwordx4 v155, s[28:29] offset:3072
	s_waitcnt lgkmcnt(10)
	v_mfma_f32_16x16x32_bf16 v[2:5], v[208:211], v[224:227], v[2:5]
	s_waitcnt lgkmcnt(9)
	v_mfma_f32_16x16x32_bf16 v[6:9], v[208:211], v[228:231], v[6:9]
	s_waitcnt lgkmcnt(8)
	v_mfma_f32_16x16x32_bf16 v[10:13], v[208:211], v[232:235], v[10:13]
	s_waitcnt lgkmcnt(7)
	v_mfma_f32_16x16x32_bf16 v[14:17], v[208:211], v[236:239], v[14:17]
	s_waitcnt lgkmcnt(6)
	v_mfma_f32_16x16x32_bf16 v[18:21], v[212:215], v[224:227], v[18:21]
	v_mfma_f32_16x16x32_bf16 v[22:25], v[212:215], v[228:231], v[22:25]
	v_mfma_f32_16x16x32_bf16 v[26:29], v[212:215], v[232:235], v[26:29]
	v_mfma_f32_16x16x32_bf16 v[30:33], v[212:215], v[236:239], v[30:33]
	s_waitcnt lgkmcnt(5)
	v_mfma_f32_16x16x32_bf16 v[34:37], v[216:219], v[224:227], v[34:37]
	v_mfma_f32_16x16x32_bf16 v[38:41], v[216:219], v[228:231], v[38:41]
	v_mfma_f32_16x16x32_bf16 v[42:45], v[216:219], v[232:235], v[42:45]
	v_mfma_f32_16x16x32_bf16 v[46:49], v[216:219], v[236:239], v[46:49]
	s_waitcnt lgkmcnt(4)
	v_mfma_f32_16x16x32_bf16 v[50:53], v[220:223], v[224:227], v[50:53]
	v_mfma_f32_16x16x32_bf16 v[54:57], v[220:223], v[228:231], v[54:57]
	v_mfma_f32_16x16x32_bf16 v[58:61], v[220:223], v[232:235], v[58:61]
	v_mfma_f32_16x16x32_bf16 v[62:65], v[220:223], v[236:239], v[62:65]
	s_waitcnt lgkmcnt(3)
	v_mfma_f32_16x16x32_bf16 v[74:77], v[208:211], v[240:243], v[74:77]
	s_waitcnt lgkmcnt(2)
	v_mfma_f32_16x16x32_bf16 v[78:81], v[208:211], v[244:247], v[78:81]
	s_waitcnt lgkmcnt(1)
	v_mfma_f32_16x16x32_bf16 v[82:85], v[208:211], v[248:251], v[82:85]
	s_waitcnt lgkmcnt(0)
	v_mfma_f32_16x16x32_bf16 v[86:89], v[208:211], v[156:159], v[86:89]
	v_mfma_f32_16x16x32_bf16 v[90:93], v[212:215], v[240:243], v[90:93]
	v_mfma_f32_16x16x32_bf16 v[94:97], v[212:215], v[244:247], v[94:97]
	v_mfma_f32_16x16x32_bf16 v[98:101], v[212:215], v[248:251], v[98:101]
	v_mfma_f32_16x16x32_bf16 v[102:105], v[212:215], v[156:159], v[102:105]
	v_mfma_f32_16x16x32_bf16 v[106:109], v[216:219], v[240:243], v[106:109]
	v_mfma_f32_16x16x32_bf16 v[110:113], v[216:219], v[244:247], v[110:113]
	v_mfma_f32_16x16x32_bf16 v[114:117], v[216:219], v[248:251], v[114:117]
	v_mfma_f32_16x16x32_bf16 v[118:121], v[216:219], v[156:159], v[118:121]
	v_mfma_f32_16x16x32_bf16 v[122:125], v[220:223], v[240:243], v[122:125]
	v_mfma_f32_16x16x32_bf16 v[126:129], v[220:223], v[244:247], v[126:129]
	v_mfma_f32_16x16x32_bf16 v[130:133], v[220:223], v[248:251], v[130:133]
	v_mfma_f32_16x16x32_bf16 v[134:137], v[220:223], v[156:159], v[134:137]
	s_setprio 0
	s_waitcnt vmcnt(8)
	s_barrier
	s_setprio 1
	ds_read_b128 v[208:211], v139 offset:0
	ds_read_b128 v[224:227], v140 offset:32768
	ds_read_b128 v[228:231], v140 offset:33792
	ds_read_b128 v[232:235], v140 offset:34816
	ds_read_b128 v[236:239], v140 offset:35840
	ds_read_b128 v[212:215], v139 offset:2048
	ds_read_b128 v[216:219], v139 offset:4096
	ds_read_b128 v[220:223], v139 offset:6144
	ds_read_b128 v[240:243], v140 offset:40960
	ds_read_b128 v[244:247], v140 offset:41984
	ds_read_b128 v[248:251], v140 offset:43008
	ds_read_b128 v[156:159], v140 offset:44032
	s_add_u32 m0, s43, 0x4000
	s_add_u32 s30, s30, 0x40000
	s_addc_u32 s31, s31, 0
	global_load_lds_dwordx4 v144, s[30:31]
	global_load_lds_dwordx4 v145, s[30:31] offset:1024
	global_load_lds_dwordx4 v146, s[30:31] offset:2048
	global_load_lds_dwordx4 v147, s[30:31] offset:3072
	s_waitcnt lgkmcnt(10)
	v_mfma_f32_16x16x32_bf16 v[2:5], v[208:211], v[224:227], v[2:5]
	s_waitcnt lgkmcnt(9)
	v_mfma_f32_16x16x32_bf16 v[6:9], v[208:211], v[228:231], v[6:9]
	s_waitcnt lgkmcnt(8)
	v_mfma_f32_16x16x32_bf16 v[10:13], v[208:211], v[232:235], v[10:13]
	s_waitcnt lgkmcnt(7)
	v_mfma_f32_16x16x32_bf16 v[14:17], v[208:211], v[236:239], v[14:17]
	s_waitcnt lgkmcnt(6)
	v_mfma_f32_16x16x32_bf16 v[18:21], v[212:215], v[224:227], v[18:21]
	v_mfma_f32_16x16x32_bf16 v[22:25], v[212:215], v[228:231], v[22:25]
	v_mfma_f32_16x16x32_bf16 v[26:29], v[212:215], v[232:235], v[26:29]
	v_mfma_f32_16x16x32_bf16 v[30:33], v[212:215], v[236:239], v[30:33]
	s_waitcnt lgkmcnt(5)
	v_mfma_f32_16x16x32_bf16 v[34:37], v[216:219], v[224:227], v[34:37]
	v_mfma_f32_16x16x32_bf16 v[38:41], v[216:219], v[228:231], v[38:41]
	v_mfma_f32_16x16x32_bf16 v[42:45], v[216:219], v[232:235], v[42:45]
	v_mfma_f32_16x16x32_bf16 v[46:49], v[216:219], v[236:239], v[46:49]
	s_waitcnt lgkmcnt(4)
	v_mfma_f32_16x16x32_bf16 v[50:53], v[220:223], v[224:227], v[50:53]
	v_mfma_f32_16x16x32_bf16 v[54:57], v[220:223], v[228:231], v[54:57]
	v_mfma_f32_16x16x32_bf16 v[58:61], v[220:223], v[232:235], v[58:61]
	v_mfma_f32_16x16x32_bf16 v[62:65], v[220:223], v[236:239], v[62:65]
	s_waitcnt lgkmcnt(3)
	v_mfma_f32_16x16x32_bf16 v[74:77], v[208:211], v[240:243], v[74:77]
	s_waitcnt lgkmcnt(2)
	v_mfma_f32_16x16x32_bf16 v[78:81], v[208:211], v[244:247], v[78:81]
	s_waitcnt lgkmcnt(1)
	v_mfma_f32_16x16x32_bf16 v[82:85], v[208:211], v[248:251], v[82:85]
	s_waitcnt lgkmcnt(0)
	v_mfma_f32_16x16x32_bf16 v[86:89], v[208:211], v[156:159], v[86:89]
	v_mfma_f32_16x16x32_bf16 v[90:93], v[212:215], v[240:243], v[90:93]
	v_mfma_f32_16x16x32_bf16 v[94:97], v[212:215], v[244:247], v[94:97]
	v_mfma_f32_16x16x32_bf16 v[98:101], v[212:215], v[248:251], v[98:101]
	v_mfma_f32_16x16x32_bf16 v[102:105], v[212:215], v[156:159], v[102:105]
	v_mfma_f32_16x16x32_bf16 v[106:109], v[216:219], v[240:243], v[106:109]
	v_mfma_f32_16x16x32_bf16 v[110:113], v[216:219], v[244:247], v[110:113]
	v_mfma_f32_16x16x32_bf16 v[114:117], v[216:219], v[248:251], v[114:117]
	v_mfma_f32_16x16x32_bf16 v[118:121], v[216:219], v[156:159], v[118:121]
	v_mfma_f32_16x16x32_bf16 v[122:125], v[220:223], v[240:243], v[122:125]
	v_mfma_f32_16x16x32_bf16 v[126:129], v[220:223], v[244:247], v[126:129]
	v_mfma_f32_16x16x32_bf16 v[130:133], v[220:223], v[248:251], v[130:133]
	v_mfma_f32_16x16x32_bf16 v[134:137], v[220:223], v[156:159], v[134:137]
	s_setprio 0
	s_waitcnt vmcnt(4)
	s_barrier
; #define BLOAD(A_, B_, kt) do { _Pragma("unroll") for (int i = 0; i < 4; ++i) { \
;     A_[i] = *(const u32x4*)((const char*)Ap + (aoff + (unsigned)(32 * i * lda + (kt) * 64) * 2u)); B_[i] = *(const u32x4*)((const char*)Wt + (woff + (unsigned)(32 * i * K + (kt) * 64) * 2u)); } } while (0)
; #define BLOAD(A_, B_, kt) do { _Pragma("unroll") for (int i = 0; i < 4; ++i) { \
;     A_[i] = *(const u32x4*)((const char*)Ap + (aoff + (unsigned)(32 * i * lda + (kt) * 64) * 2u)); B_[i] = *(const u32x4*)((const char*)Wt + (woff + (unsigned)(32 * i * K + (kt) * 64) * 2u)); } } while (0)
; #define BSTORE(A_, B_, buf) do { _Pragma("unroll") for (int i = 0; i < 4; ++i) { \
;     *(u32x4*)&As[(buf) * GBUF + (srow + 32 * i) * LDT + sc8] = A_[i]; \
;     *(u32x4*)&Bs[(buf) * GBUF + (srow + 32 * i) * LDT + sc8] = B_[i]; } } while (0)
; template <int NK>
; DI void gemm_run(PF& pf, const u16* __restrict__ Ap, int lda, const u16* __restrict__ Wt, f32x16 (&acc)[2][2], char* smem) {
;     ...
;   __builtin_amdgcn_s_setprio(0);
;   __syncthreads();
;   BSTORE(pf.a0, pf.b0, 0);
;   BLOAD(pf.a0, pf.b0, 2);
;   __syncthreads();
; #pragma unroll
;   for (int kt = 0; kt < nk; kt += 2) {
;     BCOMP(0);
;     BSTORE(pf.a1, pf.b1, 1);
;     if (kt + 3 < nk) BLOAD(pf.a1, pf.b1, kt + 3);
;     __syncthreads();
;     BCOMP(1);
;     if (kt + 2 < nk) { BSTORE(pf.a0, pf.b0, 0); if (kt + 4 < nk) BLOAD(pf.a0, pf.b0, kt + 4); }
;     __syncthreads();
;   }
	s_setprio 1
	ds_read_b128 v[208:211], v138 offset:16384
	ds_read_b128 v[224:227], v140 offset:0
	ds_read_b128 v[228:231], v140 offset:1024
	ds_read_b128 v[232:235], v140 offset:2048
	ds_read_b128 v[236:239], v140 offset:3072
	ds_read_b128 v[212:215], v138 offset:18432
	ds_read_b128 v[216:219], v138 offset:20480
	ds_read_b128 v[220:223], v138 offset:22528
	ds_read_b128 v[240:243], v140 offset:8192
	ds_read_b128 v[244:247], v140 offset:9216
	ds_read_b128 v[248:251], v140 offset:10240
	ds_read_b128 v[156:159], v140 offset:11264
	s_add_u32 m0, s43, 0x8000
	s_add_u32 s30, s30, 0x40000
	s_addc_u32 s31, s31, 0
	global_load_lds_dwordx4 v144, s[30:31]
	global_load_lds_dwordx4 v145, s[30:31] offset:1024
	global_load_lds_dwordx4 v146, s[30:31] offset:2048
	global_load_lds_dwordx4 v147, s[30:31] offset:3072
	s_add_u32 m0, s42, 0x0
	s_add_u32 s28, s28, 0x80
	s_addc_u32 s29, s29, 0
	global_load_lds_dwordx4 v142, s[28:29]
	global_load_lds_dwordx4 v143, s[28:29] offset:1024
	global_load_lds_dwordx4 v154, s[28:29] offset:2048
	global_load_lds_dwordx4 v155, s[28:29] offset:3072
	s_waitcnt lgkmcnt(10)
	v_mfma_f32_16x16x32_bf16 v[2:5], v[208:211], v[224:227], v[2:5]
	s_waitcnt lgkmcnt(9)
	v_mfma_f32_16x16x32_bf16 v[6:9], v[208:211], v[228:231], v[6:9]
	s_waitcnt lgkmcnt(8)
	v_mfma_f32_16x16x32_bf16 v[10:13], v[208:211], v[232:235], v[10:13]
	s_waitcnt lgkmcnt(7)
	v_mfma_f32_16x16x32_bf16 v[14:17], v[208:211], v[236:239], v[14:17]
	s_waitcnt lgkmcnt(6)
	v_mfma_f32_16x16x32_bf16 v[18:21], v[212:215], v[224:227], v[18:21]
	v_mfma_f32_16x16x32_bf16 v[22:25], v[212:215], v[228:231], v[22:25]
	v_mfma_f32_16x16x32_bf16 v[26:29], v[212:215], v[232:235], v[26:29]
	v_mfma_f32_16x16x32_bf16 v[30:33], v[212:215], v[236:239], v[30:33]
	s_waitcnt lgkmcnt(5)
	v_mfma_f32_16x16x32_bf16 v[34:37], v[216:219], v[224:227], v[34:37]
	v_mfma_f32_16x16x32_bf16 v[38:41], v[216:219], v[228:231], v[38:41]
	v_mfma_f32_16x16x32_bf16 v[42:45], v[216:219], v[232:235], v[42:45]
	v_mfma_f32_16x16x32_bf16 v[46:49], v[216:219], v[236:239], v[46:49]
	s_waitcnt lgkmcnt(4)
	v_mfma_f32_16x16x32_bf16 v[50:53], v[220:223], v[224:227], v[50:53]
	v_mfma_f32_16x16x32_bf16 v[54:57], v[220:223], v[228:231], v[54:57]
	v_mfma_f32_16x16x32_bf16 v[58:61], v[220:223], v[232:235], v[58:61]
	v_mfma_f32_16x16x32_bf16 v[62:65], v[220:223], v[236:239], v[62:65]
	s_waitcnt lgkmcnt(3)
	v_mfma_f32_16x16x32_bf16 v[74:77], v[208:211], v[240:243], v[74:77]
	s_waitcnt lgkmcnt(2)
	v_mfma_f32_16x16x32_bf16 v[78:81], v[208:211], v[244:247], v[78:81]
	s_waitcnt lgkmcnt(1)
	v_mfma_f32_16x16x32_bf16 v[82:85], v[208:211], v[248:251], v[82:85]
	s_waitcnt lgkmcnt(0)
	v_mfma_f32_16x16x32_bf16 v[86:89], v[208:211], v[156:159], v[86:89]
	v_mfma_f32_16x16x32_bf16 v[90:93], v[212:215], v[240:243], v[90:93]
	v_mfma_f32_16x16x32_bf16 v[94:97], v[212:215], v[244:247], v[94:97]
	v_mfma_f32_16x16x32_bf16 v[98:101], v[212:215], v[248:251], v[98:101]
	v_mfma_f32_16x16x32_bf16 v[102:105], v[212:215], v[156:159], v[102:105]
	v_mfma_f32_16x16x32_bf16 v[106:109], v[216:219], v[240:243], v[106:109]
	v_mfma_f32_16x16x32_bf16 v[110:113], v[216:219], v[244:247], v[110:113]
	v_mfma_f32_16x16x32_bf16 v[114:117], v[216:219], v[248:251], v[114:117]
	v_mfma_f32_16x16x32_bf16 v[118:121], v[216:219], v[156:159], v[118:121]
	v_mfma_f32_16x16x32_bf16 v[122:125], v[220:223], v[240:243], v[122:125]
	v_mfma_f32_16x16x32_bf16 v[126:129], v[220:223], v[244:247], v[126:129]
	v_mfma_f32_16x16x32_bf16 v[130:133], v[220:223], v[248:251], v[130:133]
	v_mfma_f32_16x16x32_bf16 v[134:137], v[220:223], v[156:159], v[134:137]
	s_setprio 0
	s_waitcnt vmcnt(8)
	s_barrier
	s_setprio 1
	ds_read_b128 v[208:211], v139 offset:16384
	ds_read_b128 v[224:227], v140 offset:16384
	ds_read_b128 v[228:231], v140 offset:17408
	ds_read_b128 v[232:235], v140 offset:18432
	ds_read_b128 v[236:239], v140 offset:19456
	ds_read_b128 v[212:215], v139 offset:18432
	ds_read_b128 v[216:219], v139 offset:20480
	ds_read_b128 v[220:223], v139 offset:22528
	ds_read_b128 v[240:243], v140 offset:24576
	ds_read_b128 v[244:247], v140 offset:25600
	ds_read_b128 v[248:251], v140 offset:26624
	ds_read_b128 v[156:159], v140 offset:27648
	s_add_u32 m0, s43, 0x0
	s_add_u32 s30, s30, 0x40000
	s_addc_u32 s31, s31, 0
	global_load_lds_dwordx4 v144, s[30:31]
	global_load_lds_dwordx4 v145, s[30:31] offset:1024
	global_load_lds_dwordx4 v146, s[30:31] offset:2048
	global_load_lds_dwordx4 v147, s[30:31] offset:3072
	s_waitcnt lgkmcnt(10)
	v_mfma_f32_16x16x32_bf16 v[2:5], v[208:211], v[224:227], v[2:5]
	s_waitcnt lgkmcnt(9)
	v_mfma_f32_16x16x32_bf16 v[6:9], v[208:211], v[228:231], v[6:9]
	s_waitcnt lgkmcnt(8)
	v_mfma_f32_16x16x32_bf16 v[10:13], v[208:211], v[232:235], v[10:13]
	s_waitcnt lgkmcnt(7)
	v_mfma_f32_16x16x32_bf16 v[14:17], v[208:211], v[236:239], v[14:17]
	s_waitcnt lgkmcnt(6)
	v_mfma_f32_16x16x32_bf16 v[18:21], v[212:215], v[224:227], v[18:21]
	v_mfma_f32_16x16x32_bf16 v[22:25], v[212:215], v[228:231], v[22:25]
	v_mfma_f32_16x16x32_bf16 v[26:29], v[212:215], v[232:235], v[26:29]
	v_mfma_f32_16x16x32_bf16 v[30:33], v[212:215], v[236:239], v[30:33]
	s_waitcnt lgkmcnt(5)
	v_mfma_f32_16x16x32_bf16 v[34:37], v[216:219], v[224:227], v[34:37]
	v_mfma_f32_16x16x32_bf16 v[38:41], v[216:219], v[228:231], v[38:41]
	v_mfma_f32_16x16x32_bf16 v[42:45], v[216:219], v[232:235], v[42:45]
	v_mfma_f32_16x16x32_bf16 v[46:49], v[216:219], v[236:239], v[46:49]
	s_waitcnt lgkmcnt(4)
	v_mfma_f32_16x16x32_bf16 v[50:53], v[220:223], v[224:227], v[50:53]
	v_mfma_f32_16x16x32_bf16 v[54:57], v[220:223], v[228:231], v[54:57]
	v_mfma_f32_16x16x32_bf16 v[58:61], v[220:223], v[232:235], v[58:61]
	v_mfma_f32_16x16x32_bf16 v[62:65], v[220:223], v[236:239], v[62:65]
	s_waitcnt lgkmcnt(3)
	v_mfma_f32_16x16x32_bf16 v[74:77], v[208:211], v[240:243], v[74:77]
	s_waitcnt lgkmcnt(2)
	v_mfma_f32_16x16x32_bf16 v[78:81], v[208:211], v[244:247], v[78:81]
	s_waitcnt lgkmcnt(1)
	v_mfma_f32_16x16x32_bf16 v[82:85], v[208:211], v[248:251], v[82:85]
	s_waitcnt lgkmcnt(0)
	v_mfma_f32_16x16x32_bf16 v[86:89], v[208:211], v[156:159], v[86:89]
	v_mfma_f32_16x16x32_bf16 v[90:93], v[212:215], v[240:243], v[90:93]
	v_mfma_f32_16x16x32_bf16 v[94:97], v[212:215], v[244:247], v[94:97]
	v_mfma_f32_16x16x32_bf16 v[98:101], v[212:215], v[248:251], v[98:101]
	v_mfma_f32_16x16x32_bf16 v[102:105], v[212:215], v[156:159], v[102:105]
	v_mfma_f32_16x16x32_bf16 v[106:109], v[216:219], v[240:243], v[106:109]
	v_mfma_f32_16x16x32_bf16 v[110:113], v[216:219], v[244:247], v[110:113]
	v_mfma_f32_16x16x32_bf16 v[114:117], v[216:219], v[248:251], v[114:117]
	v_mfma_f32_16x16x32_bf16 v[118:121], v[216:219], v[156:159], v[118:121]
	v_mfma_f32_16x16x32_bf16 v[122:125], v[220:223], v[240:243], v[122:125]
	v_mfma_f32_16x16x32_bf16 v[126:129], v[220:223], v[244:247], v[126:129]
	v_mfma_f32_16x16x32_bf16 v[130:133], v[220:223], v[248:251], v[130:133]
	v_mfma_f32_16x16x32_bf16 v[134:137], v[220:223], v[156:159], v[134:137]
	s_setprio 0
	s_waitcnt vmcnt(4)
	s_barrier
; #define BLOAD(A_, B_, kt) do { _Pragma("unroll") for (int i = 0; i < 4; ++i) { \
;     A_[i] = *(const u32x4*)((const char*)Ap + (aoff + (unsigned)(32 * i * lda + (kt) * 64) * 2u)); B_[i] = *(const u32x4*)((const char*)Wt + (woff + (unsigned)(32 * i * K + (kt) * 64) * 2u)); } } while (0)
; #define BLOAD(A_, B_, kt) do { _Pragma("unroll") for (int i = 0; i < 4; ++i) { \
;     A_[i] = *(const u32x4*)((const char*)Ap + (aoff + (unsigned)(32 * i * lda + (kt) * 64) * 2u)); B_[i] = *(const u32x4*)((const char*)Wt + (woff + (unsigned)(32 * i * K + (kt) * 64) * 2u)); } } while (0)
; #define BSTORE(A_, B_, buf) do { _Pragma("unroll") for (int i = 0; i < 4; ++i) { \
;     *(u32x4*)&As[(buf) * GBUF + (srow + 32 * i) * LDT + sc8] = A_[i]; \
;     *(u32x4*)&Bs[(buf) * GBUF + (srow + 32 * i) * LDT + sc8] = B_[i]; } } while (0)
; template <int NK>
; DI void gemm_run(PF& pf, const u16* __restrict__ Ap, int lda, const u16* __restrict__ Wt, f32x16 (&acc)[2][2], char* smem) {
;     ...
;   __builtin_amdgcn_s_setprio(0);
;   __syncthreads();
;   BSTORE(pf.a0, pf.b0, 0);
;   BLOAD(pf.a0, pf.b0, 2);
;   __syncthreads();
; #pragma unroll
;   for (int kt = 0; kt < nk; kt += 2) {
;     BCOMP(0);
;     BSTORE(pf.a1, pf.b1, 1);
;     if (kt + 3 < nk) BLOAD(pf.a1, pf.b1, kt + 3);
;     __syncthreads();
;     BCOMP(1);
;     if (kt + 2 < nk) { BSTORE(pf.a0, pf.b0, 0); if (kt + 4 < nk) BLOAD(pf.a0, pf.b0, kt + 4); }
;     __syncthreads();
;   }
	s_setprio 1
	ds_read_b128 v[208:211], v138 offset:0
	ds_read_b128 v[224:227], v140 offset:32768
	ds_read_b128 v[228:231], v140 offset:33792
	ds_read_b128 v[232:235], v140 offset:34816
	ds_read_b128 v[236:239], v140 offset:35840
	ds_read_b128 v[212:215], v138 offset:2048
	ds_read_b128 v[216:219], v138 offset:4096
	ds_read_b128 v[220:223], v138 offset:6144
	ds_read_b128 v[240:243], v140 offset:40960
	ds_read_b128 v[244:247], v140 offset:41984
	ds_read_b128 v[248:251], v140 offset:43008
	ds_read_b128 v[156:159], v140 offset:44032
	s_add_u32 m0, s43, 0x4000
	s_add_u32 s30, s30, 0x40000
	s_addc_u32 s31, s31, 0
	global_load_lds_dwordx4 v144, s[30:31]
	global_load_lds_dwordx4 v145, s[30:31] offset:1024
	global_load_lds_dwordx4 v146, s[30:31] offset:2048
	global_load_lds_dwordx4 v147, s[30:31] offset:3072
	s_add_u32 m0, s42, 0x4000
	s_add_u32 s28, s28, 0x80
	s_addc_u32 s29, s29, 0
	global_load_lds_dwordx4 v142, s[28:29]
	global_load_lds_dwordx4 v143, s[28:29] offset:1024
	global_load_lds_dwordx4 v154, s[28:29] offset:2048
	global_load_lds_dwordx4 v155, s[28:29] offset:3072
	s_waitcnt lgkmcnt(10)
	v_mfma_f32_16x16x32_bf16 v[2:5], v[208:211], v[224:227], v[2:5]
	s_waitcnt lgkmcnt(9)
	v_mfma_f32_16x16x32_bf16 v[6:9], v[208:211], v[228:231], v[6:9]
	s_waitcnt lgkmcnt(8)
	v_mfma_f32_16x16x32_bf16 v[10:13], v[208:211], v[232:235], v[10:13]
	s_waitcnt lgkmcnt(7)
	v_mfma_f32_16x16x32_bf16 v[14:17], v[208:211], v[236:239], v[14:17]
	s_waitcnt lgkmcnt(6)
	v_mfma_f32_16x16x32_bf16 v[18:21], v[212:215], v[224:227], v[18:21]
	v_mfma_f32_16x16x32_bf16 v[22:25], v[212:215], v[228:231], v[22:25]
	v_mfma_f32_16x16x32_bf16 v[26:29], v[212:215], v[232:235], v[26:29]
	v_mfma_f32_16x16x32_bf16 v[30:33], v[212:215], v[236:239], v[30:33]
	s_waitcnt lgkmcnt(5)
	v_mfma_f32_16x16x32_bf16 v[34:37], v[216:219], v[224:227], v[34:37]
	v_mfma_f32_16x16x32_bf16 v[38:41], v[216:219], v[228:231], v[38:41]
	v_mfma_f32_16x16x32_bf16 v[42:45], v[216:219], v[232:235], v[42:45]
	v_mfma_f32_16x16x32_bf16 v[46:49], v[216:219], v[236:239], v[46:49]
	s_waitcnt lgkmcnt(4)
	v_mfma_f32_16x16x32_bf16 v[50:53], v[220:223], v[224:227], v[50:53]
	v_mfma_f32_16x16x32_bf16 v[54:57], v[220:223], v[228:231], v[54:57]
	v_mfma_f32_16x16x32_bf16 v[58:61], v[220:223], v[232:235], v[58:61]
	v_mfma_f32_16x16x32_bf16 v[62:65], v[220:223], v[236:239], v[62:65]
	s_waitcnt lgkmcnt(3)
	v_mfma_f32_16x16x32_bf16 v[74:77], v[208:211], v[240:243], v[74:77]
	s_waitcnt lgkmcnt(2)
	v_mfma_f32_16x16x32_bf16 v[78:81], v[208:211], v[244:247], v[78:81]
	s_waitcnt lgkmcnt(1)
	v_mfma_f32_16x16x32_bf16 v[82:85], v[208:211], v[248:251], v[82:85]
	s_waitcnt lgkmcnt(0)
	v_mfma_f32_16x16x32_bf16 v[86:89], v[208:211], v[156:159], v[86:89]
	v_mfma_f32_16x16x32_bf16 v[90:93], v[212:215], v[240:243], v[90:93]
	v_mfma_f32_16x16x32_bf16 v[94:97], v[212:215], v[244:247], v[94:97]
	v_mfma_f32_16x16x32_bf16 v[98:101], v[212:215], v[248:251], v[98:101]
	v_mfma_f32_16x16x32_bf16 v[102:105], v[212:215], v[156:159], v[102:105]
	v_mfma_f32_16x16x32_bf16 v[106:109], v[216:219], v[240:243], v[106:109]
	v_mfma_f32_16x16x32_bf16 v[110:113], v[216:219], v[244:247], v[110:113]
	v_mfma_f32_16x16x32_bf16 v[114:117], v[216:219], v[248:251], v[114:117]
	v_mfma_f32_16x16x32_bf16 v[118:121], v[216:219], v[156:159], v[118:121]
	v_mfma_f32_16x16x32_bf16 v[122:125], v[220:223], v[240:243], v[122:125]
	v_mfma_f32_16x16x32_bf16 v[126:129], v[220:223], v[244:247], v[126:129]
	v_mfma_f32_16x16x32_bf16 v[130:133], v[220:223], v[248:251], v[130:133]
	v_mfma_f32_16x16x32_bf16 v[134:137], v[220:223], v[156:159], v[134:137]
	s_setprio 0
	s_waitcnt vmcnt(8)
	s_barrier
	s_setprio 1
	ds_read_b128 v[208:211], v139 offset:0
	ds_read_b128 v[224:227], v140 offset:0
	ds_read_b128 v[228:231], v140 offset:1024
	ds_read_b128 v[232:235], v140 offset:2048
	ds_read_b128 v[236:239], v140 offset:3072
	ds_read_b128 v[212:215], v139 offset:2048
	ds_read_b128 v[216:219], v139 offset:4096
	ds_read_b128 v[220:223], v139 offset:6144
	ds_read_b128 v[240:243], v140 offset:8192
	ds_read_b128 v[244:247], v140 offset:9216
	ds_read_b128 v[248:251], v140 offset:10240
	ds_read_b128 v[156:159], v140 offset:11264
	s_add_u32 m0, s43, 0x8000
	s_add_u32 s30, s30, 0x40000
	s_addc_u32 s31, s31, 0
	global_load_lds_dwordx4 v144, s[30:31]
	global_load_lds_dwordx4 v145, s[30:31] offset:1024
	global_load_lds_dwordx4 v146, s[30:31] offset:2048
	global_load_lds_dwordx4 v147, s[30:31] offset:3072
	s_waitcnt lgkmcnt(10)
	v_mfma_f32_16x16x32_bf16 v[2:5], v[208:211], v[224:227], v[2:5]
	s_waitcnt lgkmcnt(9)
	v_mfma_f32_16x16x32_bf16 v[6:9], v[208:211], v[228:231], v[6:9]
	s_waitcnt lgkmcnt(8)
	v_mfma_f32_16x16x32_bf16 v[10:13], v[208:211], v[232:235], v[10:13]
	s_waitcnt lgkmcnt(7)
	v_mfma_f32_16x16x32_bf16 v[14:17], v[208:211], v[236:239], v[14:17]
	s_waitcnt lgkmcnt(6)
	v_mfma_f32_16x16x32_bf16 v[18:21], v[212:215], v[224:227], v[18:21]
	v_mfma_f32_16x16x32_bf16 v[22:25], v[212:215], v[228:231], v[22:25]
	v_mfma_f32_16x16x32_bf16 v[26:29], v[212:215], v[232:235], v[26:29]
	v_mfma_f32_16x16x32_bf16 v[30:33], v[212:215], v[236:239], v[30:33]
	s_waitcnt lgkmcnt(5)
	v_mfma_f32_16x16x32_bf16 v[34:37], v[216:219], v[224:227], v[34:37]
	v_mfma_f32_16x16x32_bf16 v[38:41], v[216:219], v[228:231], v[38:41]
	v_mfma_f32_16x16x32_bf16 v[42:45], v[216:219], v[232:235], v[42:45]
	v_mfma_f32_16x16x32_bf16 v[46:49], v[216:219], v[236:239], v[46:49]
	s_waitcnt lgkmcnt(4)
	v_mfma_f32_16x16x32_bf16 v[50:53], v[220:223], v[224:227], v[50:53]
	v_mfma_f32_16x16x32_bf16 v[54:57], v[220:223], v[228:231], v[54:57]
	v_mfma_f32_16x16x32_bf16 v[58:61], v[220:223], v[232:235], v[58:61]
	v_mfma_f32_16x16x32_bf16 v[62:65], v[220:223], v[236:239], v[62:65]
	s_waitcnt lgkmcnt(3)
	v_mfma_f32_16x16x32_bf16 v[74:77], v[208:211], v[240:243], v[74:77]
	s_waitcnt lgkmcnt(2)
	v_mfma_f32_16x16x32_bf16 v[78:81], v[208:211], v[244:247], v[78:81]
	s_waitcnt lgkmcnt(1)
	v_mfma_f32_16x16x32_bf16 v[82:85], v[208:211], v[248:251], v[82:85]
	s_waitcnt lgkmcnt(0)
	v_mfma_f32_16x16x32_bf16 v[86:89], v[208:211], v[156:159], v[86:89]
	v_mfma_f32_16x16x32_bf16 v[90:93], v[212:215], v[240:243], v[90:93]
	v_mfma_f32_16x16x32_bf16 v[94:97], v[212:215], v[244:247], v[94:97]
	v_mfma_f32_16x16x32_bf16 v[98:101], v[212:215], v[248:251], v[98:101]
	v_mfma_f32_16x16x32_bf16 v[102:105], v[212:215], v[156:159], v[102:105]
	v_mfma_f32_16x16x32_bf16 v[106:109], v[216:219], v[240:243], v[106:109]
	v_mfma_f32_16x16x32_bf16 v[110:113], v[216:219], v[244:247], v[110:113]
	v_mfma_f32_16x16x32_bf16 v[114:117], v[216:219], v[248:251], v[114:117]
	v_mfma_f32_16x16x32_bf16 v[118:121], v[216:219], v[156:159], v[118:121]
	v_mfma_f32_16x16x32_bf16 v[122:125], v[220:223], v[240:243], v[122:125]
	v_mfma_f32_16x16x32_bf16 v[126:129], v[220:223], v[244:247], v[126:129]
	v_mfma_f32_16x16x32_bf16 v[130:133], v[220:223], v[248:251], v[130:133]
	v_mfma_f32_16x16x32_bf16 v[134:137], v[220:223], v[156:159], v[134:137]
	s_setprio 0
	s_waitcnt vmcnt(4)
	s_barrier
; #define BLOAD(A_, B_, kt) do { _Pragma("unroll") for (int i = 0; i < 4; ++i) { \
;     A_[i] = *(const u32x4*)((const char*)Ap + (aoff + (unsigned)(32 * i * lda + (kt) * 64) * 2u)); B_[i] = *(const u32x4*)((const char*)Wt + (woff + (unsigned)(32 * i * K + (kt) * 64) * 2u)); } } while (0)
; #define BLOAD(A_, B_, kt) do { _Pragma("unroll") for (int i = 0; i < 4; ++i) { \
;     A_[i] = *(const u32x4*)((const char*)Ap + (aoff + (unsigned)(32 * i * lda + (kt) * 64) * 2u)); B_[i] = *(const u32x4*)((const char*)Wt + (woff + (unsigned)(32 * i * K + (kt) * 64) * 2u)); } } while (0)
; #define BSTORE(A_, B_, buf) do { _Pragma("unroll") for (int i = 0; i < 4; ++i) { \
;     *(u32x4*)&As[(buf) * GBUF + (srow + 32 * i) * LDT + sc8] = A_[i]; \
;     *(u32x4*)&Bs[(buf) * GBUF + (srow + 32 * i) * LDT + sc8] = B_[i]; } } while (0)
; template <int NK>
; DI void gemm_run(PF& pf, const u16* __restrict__ Ap, int lda, const u16* __restrict__ Wt, f32x16 (&acc)[2][2], char* smem) {
;     ...
;   __builtin_amdgcn_s_setprio(0);
;   __syncthreads();
;   BSTORE(pf.a0, pf.b0, 0);
;   BLOAD(pf.a0, pf.b0, 2);
;   __syncthreads();
; #pragma unroll
;   for (int kt = 0; kt < nk; kt += 2) {
;     BCOMP(0);
;     BSTORE(pf.a1, pf.b1, 1);
;     if (kt + 3 < nk) BLOAD(pf.a1, pf.b1, kt + 3);
;     __syncthreads();
;     BCOMP(1);
;     if (kt + 2 < nk) { BSTORE(pf.a0, pf.b0, 0); if (kt + 4 < nk) BLOAD(pf.a0, pf.b0, kt + 4); }
;     __syncthreads();
;   }
	s_setprio 1
	ds_read_b128 v[208:211], v138 offset:16384
	ds_read_b128 v[224:227], v140 offset:16384
	ds_read_b128 v[228:231], v140 offset:17408
	ds_read_b128 v[232:235], v140 offset:18432
	ds_read_b128 v[236:239], v140 offset:19456
	ds_read_b128 v[212:215], v138 offset:18432
	ds_read_b128 v[216:219], v138 offset:20480
	ds_read_b128 v[220:223], v138 offset:22528
	ds_read_b128 v[240:243], v140 offset:24576
	ds_read_b128 v[244:247], v140 offset:25600
	ds_read_b128 v[248:251], v140 offset:26624
	ds_read_b128 v[156:159], v140 offset:27648
	s_add_u32 m0, s43, 0x0
	s_add_u32 s30, s30, 0x40000
	s_addc_u32 s31, s31, 0
	global_load_lds_dwordx4 v144, s[30:31]
	global_load_lds_dwordx4 v145, s[30:31] offset:1024
	global_load_lds_dwordx4 v146, s[30:31] offset:2048
	global_load_lds_dwordx4 v147, s[30:31] offset:3072
	s_add_u32 m0, s42, 0x0
	s_add_u32 s28, s28, 0x80
	s_addc_u32 s29, s29, 0
	global_load_lds_dwordx4 v142, s[28:29]
	global_load_lds_dwordx4 v143, s[28:29] offset:1024
	global_load_lds_dwordx4 v154, s[28:29] offset:2048
	global_load_lds_dwordx4 v155, s[28:29] offset:3072
	s_waitcnt lgkmcnt(10)
	v_mfma_f32_16x16x32_bf16 v[2:5], v[208:211], v[224:227], v[2:5]
	s_waitcnt lgkmcnt(9)
	v_mfma_f32_16x16x32_bf16 v[6:9], v[208:211], v[228:231], v[6:9]
	s_waitcnt lgkmcnt(8)
	v_mfma_f32_16x16x32_bf16 v[10:13], v[208:211], v[232:235], v[10:13]
	s_waitcnt lgkmcnt(7)
	v_mfma_f32_16x16x32_bf16 v[14:17], v[208:211], v[236:239], v[14:17]
	s_waitcnt lgkmcnt(6)
	v_mfma_f32_16x16x32_bf16 v[18:21], v[212:215], v[224:227], v[18:21]
	v_mfma_f32_16x16x32_bf16 v[22:25], v[212:215], v[228:231], v[22:25]
	v_mfma_f32_16x16x32_bf16 v[26:29], v[212:215], v[232:235], v[26:29]
	v_mfma_f32_16x16x32_bf16 v[30:33], v[212:215], v[236:239], v[30:33]
	s_waitcnt lgkmcnt(5)
	v_mfma_f32_16x16x32_bf16 v[34:37], v[216:219], v[224:227], v[34:37]
	v_mfma_f32_16x16x32_bf16 v[38:41], v[216:219], v[228:231], v[38:41]
	v_mfma_f32_16x16x32_bf16 v[42:45], v[216:219], v[232:235], v[42:45]
	v_mfma_f32_16x16x32_bf16 v[46:49], v[216:219], v[236:239], v[46:49]
	s_waitcnt lgkmcnt(4)
	v_mfma_f32_16x16x32_bf16 v[50:53], v[220:223], v[224:227], v[50:53]
	v_mfma_f32_16x16x32_bf16 v[54:57], v[220:223], v[228:231], v[54:57]
	v_mfma_f32_16x16x32_bf16 v[58:61], v[220:223], v[232:235], v[58:61]
	v_mfma_f32_16x16x32_bf16 v[62:65], v[220:223], v[236:239], v[62:65]
	s_waitcnt lgkmcnt(3)
	v_mfma_f32_16x16x32_bf16 v[74:77], v[208:211], v[240:243], v[74:77]
	s_waitcnt lgkmcnt(2)
	v_mfma_f32_16x16x32_bf16 v[78:81], v[208:211], v[244:247], v[78:81]
	s_waitcnt lgkmcnt(1)
	v_mfma_f32_16x16x32_bf16 v[82:85], v[208:211], v[248:251], v[82:85]
	s_waitcnt lgkmcnt(0)
	v_mfma_f32_16x16x32_bf16 v[86:89], v[208:211], v[156:159], v[86:89]
	v_mfma_f32_16x16x32_bf16 v[90:93], v[212:215], v[240:243], v[90:93]
	v_mfma_f32_16x16x32_bf16 v[94:97], v[212:215], v[244:247], v[94:97]
	v_mfma_f32_16x16x32_bf16 v[98:101], v[212:215], v[248:251], v[98:101]
	v_mfma_f32_16x16x32_bf16 v[102:105], v[212:215], v[156:159], v[102:105]
	v_mfma_f32_16x16x32_bf16 v[106:109], v[216:219], v[240:243], v[106:109]
	v_mfma_f32_16x16x32_bf16 v[110:113], v[216:219], v[244:247], v[110:113]
	v_mfma_f32_16x16x32_bf16 v[114:117], v[216:219], v[248:251], v[114:117]
	v_mfma_f32_16x16x32_bf16 v[118:121], v[216:219], v[156:159], v[118:121]
	v_mfma_f32_16x16x32_bf16 v[122:125], v[220:223], v[240:243], v[122:125]
	v_mfma_f32_16x16x32_bf16 v[126:129], v[220:223], v[244:247], v[126:129]
	v_mfma_f32_16x16x32_bf16 v[130:133], v[220:223], v[248:251], v[130:133]
	v_mfma_f32_16x16x32_bf16 v[134:137], v[220:223], v[156:159], v[134:137]
	s_setprio 0
	s_waitcnt vmcnt(8)
	s_barrier
	s_setprio 1
	ds_read_b128 v[208:211], v139 offset:16384
	ds_read_b128 v[224:227], v140 offset:32768
	ds_read_b128 v[228:231], v140 offset:33792
	ds_read_b128 v[232:235], v140 offset:34816
	ds_read_b128 v[236:239], v140 offset:35840
	ds_read_b128 v[212:215], v139 offset:18432
	ds_read_b128 v[216:219], v139 offset:20480
	ds_read_b128 v[220:223], v139 offset:22528
	ds_read_b128 v[240:243], v140 offset:40960
	ds_read_b128 v[244:247], v140 offset:41984
	ds_read_b128 v[248:251], v140 offset:43008
	ds_read_b128 v[156:159], v140 offset:44032
	s_add_u32 m0, s43, 0x4000
	s_add_u32 s30, s30, 0x40000
	s_addc_u32 s31, s31, 0
	global_load_lds_dwordx4 v144, s[30:31]
	global_load_lds_dwordx4 v145, s[30:31] offset:1024
	global_load_lds_dwordx4 v146, s[30:31] offset:2048
	global_load_lds_dwordx4 v147, s[30:31] offset:3072
	s_waitcnt lgkmcnt(10)
	v_mfma_f32_16x16x32_bf16 v[2:5], v[208:211], v[224:227], v[2:5]
	s_waitcnt lgkmcnt(9)
	v_mfma_f32_16x16x32_bf16 v[6:9], v[208:211], v[228:231], v[6:9]
	s_waitcnt lgkmcnt(8)
	v_mfma_f32_16x16x32_bf16 v[10:13], v[208:211], v[232:235], v[10:13]
	s_waitcnt lgkmcnt(7)
	v_mfma_f32_16x16x32_bf16 v[14:17], v[208:211], v[236:239], v[14:17]
	s_waitcnt lgkmcnt(6)
	v_mfma_f32_16x16x32_bf16 v[18:21], v[212:215], v[224:227], v[18:21]
	v_mfma_f32_16x16x32_bf16 v[22:25], v[212:215], v[228:231], v[22:25]
	v_mfma_f32_16x16x32_bf16 v[26:29], v[212:215], v[232:235], v[26:29]
	v_mfma_f32_16x16x32_bf16 v[30:33], v[212:215], v[236:239], v[30:33]
	s_waitcnt lgkmcnt(5)
	v_mfma_f32_16x16x32_bf16 v[34:37], v[216:219], v[224:227], v[34:37]
	v_mfma_f32_16x16x32_bf16 v[38:41], v[216:219], v[228:231], v[38:41]
	v_mfma_f32_16x16x32_bf16 v[42:45], v[216:219], v[232:235], v[42:45]
	v_mfma_f32_16x16x32_bf16 v[46:49], v[216:219], v[236:239], v[46:49]
	s_waitcnt lgkmcnt(4)
	v_mfma_f32_16x16x32_bf16 v[50:53], v[220:223], v[224:227], v[50:53]
	v_mfma_f32_16x16x32_bf16 v[54:57], v[220:223], v[228:231], v[54:57]
	v_mfma_f32_16x16x32_bf16 v[58:61], v[220:223], v[232:235], v[58:61]
	v_mfma_f32_16x16x32_bf16 v[62:65], v[220:223], v[236:239], v[62:65]
	s_waitcnt lgkmcnt(3)
	v_mfma_f32_16x16x32_bf16 v[74:77], v[208:211], v[240:243], v[74:77]
	s_waitcnt lgkmcnt(2)
	v_mfma_f32_16x16x32_bf16 v[78:81], v[208:211], v[244:247], v[78:81]
	s_waitcnt lgkmcnt(1)
	v_mfma_f32_16x16x32_bf16 v[82:85], v[208:211], v[248:251], v[82:85]
	s_waitcnt lgkmcnt(0)
	v_mfma_f32_16x16x32_bf16 v[86:89], v[208:211], v[156:159], v[86:89]
	v_mfma_f32_16x16x32_bf16 v[90:93], v[212:215], v[240:243], v[90:93]
	v_mfma_f32_16x16x32_bf16 v[94:97], v[212:215], v[244:247], v[94:97]
	v_mfma_f32_16x16x32_bf16 v[98:101], v[212:215], v[248:251], v[98:101]
	v_mfma_f32_16x16x32_bf16 v[102:105], v[212:215], v[156:159], v[102:105]
	v_mfma_f32_16x16x32_bf16 v[106:109], v[216:219], v[240:243], v[106:109]
	v_mfma_f32_16x16x32_bf16 v[110:113], v[216:219], v[244:247], v[110:113]
	v_mfma_f32_16x16x32_bf16 v[114:117], v[216:219], v[248:251], v[114:117]
	v_mfma_f32_16x16x32_bf16 v[118:121], v[216:219], v[156:159], v[118:121]
	v_mfma_f32_16x16x32_bf16 v[122:125], v[220:223], v[240:243], v[122:125]
	v_mfma_f32_16x16x32_bf16 v[126:129], v[220:223], v[244:247], v[126:129]
	v_mfma_f32_16x16x32_bf16 v[130:133], v[220:223], v[248:251], v[130:133]
	v_mfma_f32_16x16x32_bf16 v[134:137], v[220:223], v[156:159], v[134:137]
	s_setprio 0
	s_waitcnt vmcnt(4)
	s_barrier
; #define BLOAD(A_, B_, kt) do { _Pragma("unroll") for (int i = 0; i < 4; ++i) { \
;     A_[i] = *(const u32x4*)((const char*)Ap + (aoff + (unsigned)(32 * i * lda + (kt) * 64) * 2u)); B_[i] = *(const u32x4*)((const char*)Wt + (woff + (unsigned)(32 * i * K + (kt) * 64) * 2u)); } } while (0)
; #define BLOAD(A_, B_, kt) do { _Pragma("unroll") for (int i = 0; i < 4; ++i) { \
;     A_[i] = *(const u32x4*)((const char*)Ap + (aoff + (unsigned)(32 * i * lda + (kt) * 64) * 2u)); B_[i] = *(const u32x4*)((const char*)Wt + (woff + (unsigned)(32 * i * K + (kt) * 64) * 2u)); } } while (0)
; #define BSTORE(A_, B_, buf) do { _Pragma("unroll") for (int i = 0; i < 4; ++i) { \
;     *(u32x4*)&As[(buf) * GBUF + (srow + 32 * i) * LDT + sc8] = A_[i]; \
;     *(u32x4*)&Bs[(buf) * GBUF + (srow + 32 * i) * LDT + sc8] = B_[i]; } } while (0)
; template <int NK>
; DI void gemm_run(PF& pf, const u16* __restrict__ Ap, int lda, const u16* __restrict__ Wt, f32x16 (&acc)[2][2], char* smem) {
;     ...
;   __builtin_amdgcn_s_setprio(0);
;   __syncthreads();
;   BSTORE(pf.a0, pf.b0, 0);
;   BLOAD(pf.a0, pf.b0, 2);
;   __syncthreads();
; #pragma unroll
;   for (int kt = 0; kt < nk; kt += 2) {
;     BCOMP(0);
;     BSTORE(pf.a1, pf.b1, 1);
;     if (kt + 3 < nk) BLOAD(pf.a1, pf.b1, kt + 3);
;     __syncthreads();
;     BCOMP(1);
;     if (kt + 2 < nk) { BSTORE(pf.a0, pf.b0, 0); if (kt + 4 < nk) BLOAD(pf.a0, pf.b0, kt + 4); }
;     __syncthreads();
;   }
	s_setprio 1
	ds_read_b128 v[208:211], v138 offset:0
	ds_read_b128 v[224:227], v140 offset:0
	ds_read_b128 v[228:231], v140 offset:1024
	ds_read_b128 v[232:235], v140 offset:2048
	ds_read_b128 v[236:239], v140 offset:3072
	ds_read_b128 v[212:215], v138 offset:2048
	ds_read_b128 v[216:219], v138 offset:4096
	ds_read_b128 v[220:223], v138 offset:6144
	ds_read_b128 v[240:243], v140 offset:8192
	ds_read_b128 v[244:247], v140 offset:9216
	ds_read_b128 v[248:251], v140 offset:10240
	ds_read_b128 v[156:159], v140 offset:11264
	s_add_u32 m0, s43, 0x8000
	s_add_u32 s30, s30, 0x40000
	s_addc_u32 s31, s31, 0
	global_load_lds_dwordx4 v144, s[30:31]
	global_load_lds_dwordx4 v145, s[30:31] offset:1024
	global_load_lds_dwordx4 v146, s[30:31] offset:2048
	global_load_lds_dwordx4 v147, s[30:31] offset:3072
	s_add_u32 m0, s42, 0x4000
	s_add_u32 s28, s28, 0x80
	s_addc_u32 s29, s29, 0
	global_load_lds_dwordx4 v142, s[28:29]
	global_load_lds_dwordx4 v143, s[28:29] offset:1024
	global_load_lds_dwordx4 v154, s[28:29] offset:2048
	global_load_lds_dwordx4 v155, s[28:29] offset:3072
	s_waitcnt lgkmcnt(10)
	v_mfma_f32_16x16x32_bf16 v[2:5], v[208:211], v[224:227], v[2:5]
	s_waitcnt lgkmcnt(9)
	v_mfma_f32_16x16x32_bf16 v[6:9], v[208:211], v[228:231], v[6:9]
	s_waitcnt lgkmcnt(8)
	v_mfma_f32_16x16x32_bf16 v[10:13], v[208:211], v[232:235], v[10:13]
	s_waitcnt lgkmcnt(7)
	v_mfma_f32_16x16x32_bf16 v[14:17], v[208:211], v[236:239], v[14:17]
	s_waitcnt lgkmcnt(6)
	v_mfma_f32_16x16x32_bf16 v[18:21], v[212:215], v[224:227], v[18:21]
	v_mfma_f32_16x16x32_bf16 v[22:25], v[212:215], v[228:231], v[22:25]
	v_mfma_f32_16x16x32_bf16 v[26:29], v[212:215], v[232:235], v[26:29]
	v_mfma_f32_16x16x32_bf16 v[30:33], v[212:215], v[236:239], v[30:33]
	s_waitcnt lgkmcnt(5)
	v_mfma_f32_16x16x32_bf16 v[34:37], v[216:219], v[224:227], v[34:37]
	v_mfma_f32_16x16x32_bf16 v[38:41], v[216:219], v[228:231], v[38:41]
	v_mfma_f32_16x16x32_bf16 v[42:45], v[216:219], v[232:235], v[42:45]
	v_mfma_f32_16x16x32_bf16 v[46:49], v[216:219], v[236:239], v[46:49]
	s_waitcnt lgkmcnt(4)
	v_mfma_f32_16x16x32_bf16 v[50:53], v[220:223], v[224:227], v[50:53]
	v_mfma_f32_16x16x32_bf16 v[54:57], v[220:223], v[228:231], v[54:57]
	v_mfma_f32_16x16x32_bf16 v[58:61], v[220:223], v[232:235], v[58:61]
	v_mfma_f32_16x16x32_bf16 v[62:65], v[220:223], v[236:239], v[62:65]
	s_waitcnt lgkmcnt(3)
	v_mfma_f32_16x16x32_bf16 v[74:77], v[208:211], v[240:243], v[74:77]
	s_waitcnt lgkmcnt(2)
	v_mfma_f32_16x16x32_bf16 v[78:81], v[208:211], v[244:247], v[78:81]
	s_waitcnt lgkmcnt(1)
	v_mfma_f32_16x16x32_bf16 v[82:85], v[208:211], v[248:251], v[82:85]
	s_waitcnt lgkmcnt(0)
	v_mfma_f32_16x16x32_bf16 v[86:89], v[208:211], v[156:159], v[86:89]
	v_mfma_f32_16x16x32_bf16 v[90:93], v[212:215], v[240:243], v[90:93]
	v_mfma_f32_16x16x32_bf16 v[94:97], v[212:215], v[244:247], v[94:97]
	v_mfma_f32_16x16x32_bf16 v[98:101], v[212:215], v[248:251], v[98:101]
	v_mfma_f32_16x16x32_bf16 v[102:105], v[212:215], v[156:159], v[102:105]
	v_mfma_f32_16x16x32_bf16 v[106:109], v[216:219], v[240:243], v[106:109]
	v_mfma_f32_16x16x32_bf16 v[110:113], v[216:219], v[244:247], v[110:113]
	v_mfma_f32_16x16x32_bf16 v[114:117], v[216:219], v[248:251], v[114:117]
	v_mfma_f32_16x16x32_bf16 v[118:121], v[216:219], v[156:159], v[118:121]
	v_mfma_f32_16x16x32_bf16 v[122:125], v[220:223], v[240:243], v[122:125]
	v_mfma_f32_16x16x32_bf16 v[126:129], v[220:223], v[244:247], v[126:129]
	v_mfma_f32_16x16x32_bf16 v[130:133], v[220:223], v[248:251], v[130:133]
	v_mfma_f32_16x16x32_bf16 v[134:137], v[220:223], v[156:159], v[134:137]
	s_setprio 0
	s_waitcnt vmcnt(8)
	s_barrier
	s_setprio 1
	ds_read_b128 v[208:211], v139 offset:0
	ds_read_b128 v[224:227], v140 offset:16384
	ds_read_b128 v[228:231], v140 offset:17408
	ds_read_b128 v[232:235], v140 offset:18432
	ds_read_b128 v[236:239], v140 offset:19456
	ds_read_b128 v[212:215], v139 offset:2048
	ds_read_b128 v[216:219], v139 offset:4096
	ds_read_b128 v[220:223], v139 offset:6144
	ds_read_b128 v[240:243], v140 offset:24576
	ds_read_b128 v[244:247], v140 offset:25600
	ds_read_b128 v[248:251], v140 offset:26624
	ds_read_b128 v[156:159], v140 offset:27648
	s_add_u32 m0, s43, 0x0
	s_add_u32 s30, s30, 0x40000
	s_addc_u32 s31, s31, 0
	global_load_lds_dwordx4 v144, s[30:31]
	global_load_lds_dwordx4 v145, s[30:31] offset:1024
	global_load_lds_dwordx4 v146, s[30:31] offset:2048
	global_load_lds_dwordx4 v147, s[30:31] offset:3072
	s_waitcnt lgkmcnt(10)
	v_mfma_f32_16x16x32_bf16 v[2:5], v[208:211], v[224:227], v[2:5]
	s_waitcnt lgkmcnt(9)
	v_mfma_f32_16x16x32_bf16 v[6:9], v[208:211], v[228:231], v[6:9]
	s_waitcnt lgkmcnt(8)
	v_mfma_f32_16x16x32_bf16 v[10:13], v[208:211], v[232:235], v[10:13]
	s_waitcnt lgkmcnt(7)
	v_mfma_f32_16x16x32_bf16 v[14:17], v[208:211], v[236:239], v[14:17]
	s_waitcnt lgkmcnt(6)
	v_mfma_f32_16x16x32_bf16 v[18:21], v[212:215], v[224:227], v[18:21]
	v_mfma_f32_16x16x32_bf16 v[22:25], v[212:215], v[228:231], v[22:25]
	v_mfma_f32_16x16x32_bf16 v[26:29], v[212:215], v[232:235], v[26:29]
	v_mfma_f32_16x16x32_bf16 v[30:33], v[212:215], v[236:239], v[30:33]
	s_waitcnt lgkmcnt(5)
	v_mfma_f32_16x16x32_bf16 v[34:37], v[216:219], v[224:227], v[34:37]
	v_mfma_f32_16x16x32_bf16 v[38:41], v[216:219], v[228:231], v[38:41]
	v_mfma_f32_16x16x32_bf16 v[42:45], v[216:219], v[232:235], v[42:45]
	v_mfma_f32_16x16x32_bf16 v[46:49], v[216:219], v[236:239], v[46:49]
	s_waitcnt lgkmcnt(4)
	v_mfma_f32_16x16x32_bf16 v[50:53], v[220:223], v[224:227], v[50:53]
	v_mfma_f32_16x16x32_bf16 v[54:57], v[220:223], v[228:231], v[54:57]
	v_mfma_f32_16x16x32_bf16 v[58:61], v[220:223], v[232:235], v[58:61]
	v_mfma_f32_16x16x32_bf16 v[62:65], v[220:223], v[236:239], v[62:65]
	s_waitcnt lgkmcnt(3)
	v_mfma_f32_16x16x32_bf16 v[74:77], v[208:211], v[240:243], v[74:77]
	s_waitcnt lgkmcnt(2)
	v_mfma_f32_16x16x32_bf16 v[78:81], v[208:211], v[244:247], v[78:81]
	s_waitcnt lgkmcnt(1)
	v_mfma_f32_16x16x32_bf16 v[82:85], v[208:211], v[248:251], v[82:85]
	s_waitcnt lgkmcnt(0)
	v_mfma_f32_16x16x32_bf16 v[86:89], v[208:211], v[156:159], v[86:89]
	v_mfma_f32_16x16x32_bf16 v[90:93], v[212:215], v[240:243], v[90:93]
	v_mfma_f32_16x16x32_bf16 v[94:97], v[212:215], v[244:247], v[94:97]
	v_mfma_f32_16x16x32_bf16 v[98:101], v[212:215], v[248:251], v[98:101]
	v_mfma_f32_16x16x32_bf16 v[102:105], v[212:215], v[156:159], v[102:105]
	v_mfma_f32_16x16x32_bf16 v[106:109], v[216:219], v[240:243], v[106:109]
	v_mfma_f32_16x16x32_bf16 v[110:113], v[216:219], v[244:247], v[110:113]
	v_mfma_f32_16x16x32_bf16 v[114:117], v[216:219], v[248:251], v[114:117]
	v_mfma_f32_16x16x32_bf16 v[118:121], v[216:219], v[156:159], v[118:121]
	v_mfma_f32_16x16x32_bf16 v[122:125], v[220:223], v[240:243], v[122:125]
	v_mfma_f32_16x16x32_bf16 v[126:129], v[220:223], v[244:247], v[126:129]
	v_mfma_f32_16x16x32_bf16 v[130:133], v[220:223], v[248:251], v[130:133]
	v_mfma_f32_16x16x32_bf16 v[134:137], v[220:223], v[156:159], v[134:137]
	s_setprio 0
	s_waitcnt vmcnt(4)
	s_barrier
; #define BLOAD(A_, B_, kt) do { _Pragma("unroll") for (int i = 0; i < 4; ++i) { \
;     A_[i] = *(const u32x4*)((const char*)Ap + (aoff + (unsigned)(32 * i * lda + (kt) * 64) * 2u)); B_[i] = *(const u32x4*)((const char*)Wt + (woff + (unsigned)(32 * i * K + (kt) * 64) * 2u)); } } while (0)
; #define BLOAD(A_, B_, kt) do { _Pragma("unroll") for (int i = 0; i < 4; ++i) { \
;     A_[i] = *(const u32x4*)((const char*)Ap + (aoff + (unsigned)(32 * i * lda + (kt) * 64) * 2u)); B_[i] = *(const u32x4*)((const char*)Wt + (woff + (unsigned)(32 * i * K + (kt) * 64) * 2u)); } } while (0)
; #define BSTORE(A_, B_, buf) do { _Pragma("unroll") for (int i = 0; i < 4; ++i) { \
;     *(u32x4*)&As[(buf) * GBUF + (srow + 32 * i) * LDT + sc8] = A_[i]; \
;     *(u32x4*)&Bs[(buf) * GBUF + (srow + 32 * i) * LDT + sc8] = B_[i]; } } while (0)
; template <int NK>
; DI void gemm_run(PF& pf, const u16* __restrict__ Ap, int lda, const u16* __restrict__ Wt, f32x16 (&acc)[2][2], char* smem) {
;     ...
;   __builtin_amdgcn_s_setprio(0);
;   __syncthreads();
;   BSTORE(pf.a0, pf.b0, 0);
;   BLOAD(pf.a0, pf.b0, 2);
;   __syncthreads();
; #pragma unroll
;   for (int kt = 0; kt < nk; kt += 2) {
;     BCOMP(0);
;     BSTORE(pf.a1, pf.b1, 1);
;     if (kt + 3 < nk) BLOAD(pf.a1, pf.b1, kt + 3);
;     __syncthreads();
;     BCOMP(1);
;     if (kt + 2 < nk) { BSTORE(pf.a0, pf.b0, 0); if (kt + 4 < nk) BLOAD(pf.a0, pf.b0, kt + 4); }
;     __syncthreads();
;   }
	s_setprio 1
	ds_read_b128 v[208:211], v138 offset:16384
	ds_read_b128 v[224:227], v140 offset:32768
	ds_read_b128 v[228:231], v140 offset:33792
	ds_read_b128 v[232:235], v140 offset:34816
	ds_read_b128 v[236:239], v140 offset:35840
	ds_read_b128 v[212:215], v138 offset:18432
	ds_read_b128 v[216:219], v138 offset:20480
	ds_read_b128 v[220:223], v138 offset:22528
	ds_read_b128 v[240:243], v140 offset:40960
	ds_read_b128 v[244:247], v140 offset:41984
	ds_read_b128 v[248:251], v140 offset:43008
	ds_read_b128 v[156:159], v140 offset:44032
	s_add_u32 m0, s43, 0x4000
	s_add_u32 s30, s30, 0x40000
	s_addc_u32 s31, s31, 0
	global_load_lds_dwordx4 v144, s[30:31]
	global_load_lds_dwordx4 v145, s[30:31] offset:1024
	global_load_lds_dwordx4 v146, s[30:31] offset:2048
	global_load_lds_dwordx4 v147, s[30:31] offset:3072
	s_add_u32 m0, s42, 0x0
	s_add_u32 s28, s28, 0x80
	s_addc_u32 s29, s29, 0
	global_load_lds_dwordx4 v142, s[28:29]
	global_load_lds_dwordx4 v143, s[28:29] offset:1024
	global_load_lds_dwordx4 v154, s[28:29] offset:2048
	global_load_lds_dwordx4 v155, s[28:29] offset:3072
	s_waitcnt lgkmcnt(10)
	v_mfma_f32_16x16x32_bf16 v[2:5], v[208:211], v[224:227], v[2:5]
	s_waitcnt lgkmcnt(9)
	v_mfma_f32_16x16x32_bf16 v[6:9], v[208:211], v[228:231], v[6:9]
	s_waitcnt lgkmcnt(8)
	v_mfma_f32_16x16x32_bf16 v[10:13], v[208:211], v[232:235], v[10:13]
	s_waitcnt lgkmcnt(7)
	v_mfma_f32_16x16x32_bf16 v[14:17], v[208:211], v[236:239], v[14:17]
	s_waitcnt lgkmcnt(6)
	v_mfma_f32_16x16x32_bf16 v[18:21], v[212:215], v[224:227], v[18:21]
	v_mfma_f32_16x16x32_bf16 v[22:25], v[212:215], v[228:231], v[22:25]
	v_mfma_f32_16x16x32_bf16 v[26:29], v[212:215], v[232:235], v[26:29]
	v_mfma_f32_16x16x32_bf16 v[30:33], v[212:215], v[236:239], v[30:33]
	s_waitcnt lgkmcnt(5)
	v_mfma_f32_16x16x32_bf16 v[34:37], v[216:219], v[224:227], v[34:37]
	v_mfma_f32_16x16x32_bf16 v[38:41], v[216:219], v[228:231], v[38:41]
	v_mfma_f32_16x16x32_bf16 v[42:45], v[216:219], v[232:235], v[42:45]
	v_mfma_f32_16x16x32_bf16 v[46:49], v[216:219], v[236:239], v[46:49]
	s_waitcnt lgkmcnt(4)
	v_mfma_f32_16x16x32_bf16 v[50:53], v[220:223], v[224:227], v[50:53]
	v_mfma_f32_16x16x32_bf16 v[54:57], v[220:223], v[228:231], v[54:57]
	v_mfma_f32_16x16x32_bf16 v[58:61], v[220:223], v[232:235], v[58:61]
	v_mfma_f32_16x16x32_bf16 v[62:65], v[220:223], v[236:239], v[62:65]
	s_waitcnt lgkmcnt(3)
	v_mfma_f32_16x16x32_bf16 v[74:77], v[208:211], v[240:243], v[74:77]
	s_waitcnt lgkmcnt(2)
	v_mfma_f32_16x16x32_bf16 v[78:81], v[208:211], v[244:247], v[78:81]
	s_waitcnt lgkmcnt(1)
	v_mfma_f32_16x16x32_bf16 v[82:85], v[208:211], v[248:251], v[82:85]
	s_waitcnt lgkmcnt(0)
	v_mfma_f32_16x16x32_bf16 v[86:89], v[208:211], v[156:159], v[86:89]
	v_mfma_f32_16x16x32_bf16 v[90:93], v[212:215], v[240:243], v[90:93]
	v_mfma_f32_16x16x32_bf16 v[94:97], v[212:215], v[244:247], v[94:97]
	v_mfma_f32_16x16x32_bf16 v[98:101], v[212:215], v[248:251], v[98:101]
	v_mfma_f32_16x16x32_bf16 v[102:105], v[212:215], v[156:159], v[102:105]
	v_mfma_f32_16x16x32_bf16 v[106:109], v[216:219], v[240:243], v[106:109]
	v_mfma_f32_16x16x32_bf16 v[110:113], v[216:219], v[244:247], v[110:113]
	v_mfma_f32_16x16x32_bf16 v[114:117], v[216:219], v[248:251], v[114:117]
	v_mfma_f32_16x16x32_bf16 v[118:121], v[216:219], v[156:159], v[118:121]
	v_mfma_f32_16x16x32_bf16 v[122:125], v[220:223], v[240:243], v[122:125]
	v_mfma_f32_16x16x32_bf16 v[126:129], v[220:223], v[244:247], v[126:129]
	v_mfma_f32_16x16x32_bf16 v[130:133], v[220:223], v[248:251], v[130:133]
	v_mfma_f32_16x16x32_bf16 v[134:137], v[220:223], v[156:159], v[134:137]
	s_setprio 0
	s_waitcnt vmcnt(8)
	s_barrier
	s_setprio 1
	ds_read_b128 v[208:211], v139 offset:16384
	ds_read_b128 v[224:227], v140 offset:0
	ds_read_b128 v[228:231], v140 offset:1024
	ds_read_b128 v[232:235], v140 offset:2048
	ds_read_b128 v[236:239], v140 offset:3072
	ds_read_b128 v[212:215], v139 offset:18432
	ds_read_b128 v[216:219], v139 offset:20480
	ds_read_b128 v[220:223], v139 offset:22528
	ds_read_b128 v[240:243], v140 offset:8192
	ds_read_b128 v[244:247], v140 offset:9216
	ds_read_b128 v[248:251], v140 offset:10240
	ds_read_b128 v[156:159], v140 offset:11264
	s_add_u32 m0, s43, 0x8000
	s_add_u32 s30, s30, 0x40000
	s_addc_u32 s31, s31, 0
	global_load_lds_dwordx4 v144, s[30:31]
	global_load_lds_dwordx4 v145, s[30:31] offset:1024
	global_load_lds_dwordx4 v146, s[30:31] offset:2048
	global_load_lds_dwordx4 v147, s[30:31] offset:3072
	s_waitcnt lgkmcnt(10)
	v_mfma_f32_16x16x32_bf16 v[2:5], v[208:211], v[224:227], v[2:5]
	s_waitcnt lgkmcnt(9)
	v_mfma_f32_16x16x32_bf16 v[6:9], v[208:211], v[228:231], v[6:9]
	s_waitcnt lgkmcnt(8)
	v_mfma_f32_16x16x32_bf16 v[10:13], v[208:211], v[232:235], v[10:13]
	s_waitcnt lgkmcnt(7)
	v_mfma_f32_16x16x32_bf16 v[14:17], v[208:211], v[236:239], v[14:17]
	s_waitcnt lgkmcnt(6)
	v_mfma_f32_16x16x32_bf16 v[18:21], v[212:215], v[224:227], v[18:21]
	v_mfma_f32_16x16x32_bf16 v[22:25], v[212:215], v[228:231], v[22:25]
	v_mfma_f32_16x16x32_bf16 v[26:29], v[212:215], v[232:235], v[26:29]
	v_mfma_f32_16x16x32_bf16 v[30:33], v[212:215], v[236:239], v[30:33]
	s_waitcnt lgkmcnt(5)
	v_mfma_f32_16x16x32_bf16 v[34:37], v[216:219], v[224:227], v[34:37]
	v_mfma_f32_16x16x32_bf16 v[38:41], v[216:219], v[228:231], v[38:41]
	v_mfma_f32_16x16x32_bf16 v[42:45], v[216:219], v[232:235], v[42:45]
	v_mfma_f32_16x16x32_bf16 v[46:49], v[216:219], v[236:239], v[46:49]
	s_waitcnt lgkmcnt(4)
	v_mfma_f32_16x16x32_bf16 v[50:53], v[220:223], v[224:227], v[50:53]
	v_mfma_f32_16x16x32_bf16 v[54:57], v[220:223], v[228:231], v[54:57]
	v_mfma_f32_16x16x32_bf16 v[58:61], v[220:223], v[232:235], v[58:61]
	v_mfma_f32_16x16x32_bf16 v[62:65], v[220:223], v[236:239], v[62:65]
	s_waitcnt lgkmcnt(3)
	v_mfma_f32_16x16x32_bf16 v[74:77], v[208:211], v[240:243], v[74:77]
	s_waitcnt lgkmcnt(2)
	v_mfma_f32_16x16x32_bf16 v[78:81], v[208:211], v[244:247], v[78:81]
	s_waitcnt lgkmcnt(1)
	v_mfma_f32_16x16x32_bf16 v[82:85], v[208:211], v[248:251], v[82:85]
	s_waitcnt lgkmcnt(0)
	v_mfma_f32_16x16x32_bf16 v[86:89], v[208:211], v[156:159], v[86:89]
	v_mfma_f32_16x16x32_bf16 v[90:93], v[212:215], v[240:243], v[90:93]
	v_mfma_f32_16x16x32_bf16 v[94:97], v[212:215], v[244:247], v[94:97]
	v_mfma_f32_16x16x32_bf16 v[98:101], v[212:215], v[248:251], v[98:101]
	v_mfma_f32_16x16x32_bf16 v[102:105], v[212:215], v[156:159], v[102:105]
	v_mfma_f32_16x16x32_bf16 v[106:109], v[216:219], v[240:243], v[106:109]
	v_mfma_f32_16x16x32_bf16 v[110:113], v[216:219], v[244:247], v[110:113]
	v_mfma_f32_16x16x32_bf16 v[114:117], v[216:219], v[248:251], v[114:117]
	v_mfma_f32_16x16x32_bf16 v[118:121], v[216:219], v[156:159], v[118:121]
	v_mfma_f32_16x16x32_bf16 v[122:125], v[220:223], v[240:243], v[122:125]
	v_mfma_f32_16x16x32_bf16 v[126:129], v[220:223], v[244:247], v[126:129]
	v_mfma_f32_16x16x32_bf16 v[130:133], v[220:223], v[248:251], v[130:133]
	v_mfma_f32_16x16x32_bf16 v[134:137], v[220:223], v[156:159], v[134:137]
	s_setprio 0
	s_waitcnt vmcnt(4)
	s_barrier
; #define BLOAD(A_, B_, kt) do { _Pragma("unroll") for (int i = 0; i < 4; ++i) { \
;     A_[i] = *(const u32x4*)((const char*)Ap + (aoff + (unsigned)(32 * i * lda + (kt) * 64) * 2u)); B_[i] = *(const u32x4*)((const char*)Wt + (woff + (unsigned)(32 * i * K + (kt) * 64) * 2u)); } } while (0)
; #define BLOAD(A_, B_, kt) do { _Pragma("unroll") for (int i = 0; i < 4; ++i) { \
;     A_[i] = *(const u32x4*)((const char*)Ap + (aoff + (unsigned)(32 * i * lda + (kt) * 64) * 2u)); B_[i] = *(const u32x4*)((const char*)Wt + (woff + (unsigned)(32 * i * K + (kt) * 64) * 2u)); } } while (0)
; #define BSTORE(A_, B_, buf) do { _Pragma("unroll") for (int i = 0; i < 4; ++i) { \
;     *(u32x4*)&As[(buf) * GBUF + (srow + 32 * i) * LDT + sc8] = A_[i]; \
;     *(u32x4*)&Bs[(buf) * GBUF + (srow + 32 * i) * LDT + sc8] = B_[i]; } } while (0)
; template <int NK>
; DI void gemm_run(PF& pf, const u16* __restrict__ Ap, int lda, const u16* __restrict__ Wt, f32x16 (&acc)[2][2], char* smem) {
;     ...
;   __builtin_amdgcn_s_setprio(0);
;   __syncthreads();
;   BSTORE(pf.a0, pf.b0, 0);
;   BLOAD(pf.a0, pf.b0, 2);
;   __syncthreads();
; #pragma unroll
;   for (int kt = 0; kt < nk; kt += 2) {
;     BCOMP(0);
;     BSTORE(pf.a1, pf.b1, 1);
;     if (kt + 3 < nk) BLOAD(pf.a1, pf.b1, kt + 3);
;     __syncthreads();
;     BCOMP(1);
;     if (kt + 2 < nk) { BSTORE(pf.a0, pf.b0, 0); if (kt + 4 < nk) BLOAD(pf.a0, pf.b0, kt + 4); }
;     __syncthreads();
;   }
	s_setprio 1
	ds_read_b128 v[208:211], v138 offset:0
	ds_read_b128 v[224:227], v140 offset:16384
	ds_read_b128 v[228:231], v140 offset:17408
	ds_read_b128 v[232:235], v140 offset:18432
	ds_read_b128 v[236:239], v140 offset:19456
	ds_read_b128 v[212:215], v138 offset:2048
	ds_read_b128 v[216:219], v138 offset:4096
	ds_read_b128 v[220:223], v138 offset:6144
	ds_read_b128 v[240:243], v140 offset:24576
	ds_read_b128 v[244:247], v140 offset:25600
	ds_read_b128 v[248:251], v140 offset:26624
	ds_read_b128 v[156:159], v140 offset:27648
	s_add_u32 m0, s43, 0x0
	s_add_u32 s30, s30, 0x40000
	s_addc_u32 s31, s31, 0
	global_load_lds_dwordx4 v144, s[30:31]
	global_load_lds_dwordx4 v145, s[30:31] offset:1024
	global_load_lds_dwordx4 v146, s[30:31] offset:2048
	global_load_lds_dwordx4 v147, s[30:31] offset:3072
	s_add_u32 m0, s42, 0x4000
	s_add_u32 s28, s28, 0x80
	s_addc_u32 s29, s29, 0
	global_load_lds_dwordx4 v142, s[28:29]
	global_load_lds_dwordx4 v143, s[28:29] offset:1024
	global_load_lds_dwordx4 v154, s[28:29] offset:2048
	global_load_lds_dwordx4 v155, s[28:29] offset:3072
	s_waitcnt lgkmcnt(10)
	v_mfma_f32_16x16x32_bf16 v[2:5], v[208:211], v[224:227], v[2:5]
	s_waitcnt lgkmcnt(9)
	v_mfma_f32_16x16x32_bf16 v[6:9], v[208:211], v[228:231], v[6:9]
	s_waitcnt lgkmcnt(8)
	v_mfma_f32_16x16x32_bf16 v[10:13], v[208:211], v[232:235], v[10:13]
	s_waitcnt lgkmcnt(7)
	v_mfma_f32_16x16x32_bf16 v[14:17], v[208:211], v[236:239], v[14:17]
	s_waitcnt lgkmcnt(6)
	v_mfma_f32_16x16x32_bf16 v[18:21], v[212:215], v[224:227], v[18:21]
	v_mfma_f32_16x16x32_bf16 v[22:25], v[212:215], v[228:231], v[22:25]
	v_mfma_f32_16x16x32_bf16 v[26:29], v[212:215], v[232:235], v[26:29]
	v_mfma_f32_16x16x32_bf16 v[30:33], v[212:215], v[236:239], v[30:33]
	s_waitcnt lgkmcnt(5)
	v_mfma_f32_16x16x32_bf16 v[34:37], v[216:219], v[224:227], v[34:37]
	v_mfma_f32_16x16x32_bf16 v[38:41], v[216:219], v[228:231], v[38:41]
	v_mfma_f32_16x16x32_bf16 v[42:45], v[216:219], v[232:235], v[42:45]
	v_mfma_f32_16x16x32_bf16 v[46:49], v[216:219], v[236:239], v[46:49]
	s_waitcnt lgkmcnt(4)
	v_mfma_f32_16x16x32_bf16 v[50:53], v[220:223], v[224:227], v[50:53]
	v_mfma_f32_16x16x32_bf16 v[54:57], v[220:223], v[228:231], v[54:57]
	v_mfma_f32_16x16x32_bf16 v[58:61], v[220:223], v[232:235], v[58:61]
	v_mfma_f32_16x16x32_bf16 v[62:65], v[220:223], v[236:239], v[62:65]
	s_waitcnt lgkmcnt(3)
	v_mfma_f32_16x16x32_bf16 v[74:77], v[208:211], v[240:243], v[74:77]
	s_waitcnt lgkmcnt(2)
	v_mfma_f32_16x16x32_bf16 v[78:81], v[208:211], v[244:247], v[78:81]
	s_waitcnt lgkmcnt(1)
	v_mfma_f32_16x16x32_bf16 v[82:85], v[208:211], v[248:251], v[82:85]
	s_waitcnt lgkmcnt(0)
	v_mfma_f32_16x16x32_bf16 v[86:89], v[208:211], v[156:159], v[86:89]
	v_mfma_f32_16x16x32_bf16 v[90:93], v[212:215], v[240:243], v[90:93]
	v_mfma_f32_16x16x32_bf16 v[94:97], v[212:215], v[244:247], v[94:97]
	v_mfma_f32_16x16x32_bf16 v[98:101], v[212:215], v[248:251], v[98:101]
	v_mfma_f32_16x16x32_bf16 v[102:105], v[212:215], v[156:159], v[102:105]
	v_mfma_f32_16x16x32_bf16 v[106:109], v[216:219], v[240:243], v[106:109]
	v_mfma_f32_16x16x32_bf16 v[110:113], v[216:219], v[244:247], v[110:113]
	v_mfma_f32_16x16x32_bf16 v[114:117], v[216:219], v[248:251], v[114:117]
	v_mfma_f32_16x16x32_bf16 v[118:121], v[216:219], v[156:159], v[118:121]
	v_mfma_f32_16x16x32_bf16 v[122:125], v[220:223], v[240:243], v[122:125]
	v_mfma_f32_16x16x32_bf16 v[126:129], v[220:223], v[244:247], v[126:129]
	v_mfma_f32_16x16x32_bf16 v[130:133], v[220:223], v[248:251], v[130:133]
	v_mfma_f32_16x16x32_bf16 v[134:137], v[220:223], v[156:159], v[134:137]
	s_setprio 0
	s_waitcnt vmcnt(8)
	s_barrier
	s_setprio 1
	ds_read_b128 v[208:211], v139 offset:0
	ds_read_b128 v[224:227], v140 offset:32768
	ds_read_b128 v[228:231], v140 offset:33792
	ds_read_b128 v[232:235], v140 offset:34816
	ds_read_b128 v[236:239], v140 offset:35840
	ds_read_b128 v[212:215], v139 offset:2048
	ds_read_b128 v[216:219], v139 offset:4096
	ds_read_b128 v[220:223], v139 offset:6144
	ds_read_b128 v[240:243], v140 offset:40960
	ds_read_b128 v[244:247], v140 offset:41984
	ds_read_b128 v[248:251], v140 offset:43008
	ds_read_b128 v[156:159], v140 offset:44032
	s_add_u32 m0, s43, 0x4000
	s_add_u32 s30, s30, 0x40000
	s_addc_u32 s31, s31, 0
	global_load_lds_dwordx4 v144, s[30:31]
	global_load_lds_dwordx4 v145, s[30:31] offset:1024
	global_load_lds_dwordx4 v146, s[30:31] offset:2048
	global_load_lds_dwordx4 v147, s[30:31] offset:3072
	s_waitcnt lgkmcnt(10)
	v_mfma_f32_16x16x32_bf16 v[2:5], v[208:211], v[224:227], v[2:5]
	s_waitcnt lgkmcnt(9)
	v_mfma_f32_16x16x32_bf16 v[6:9], v[208:211], v[228:231], v[6:9]
	s_waitcnt lgkmcnt(8)
	v_mfma_f32_16x16x32_bf16 v[10:13], v[208:211], v[232:235], v[10:13]
	s_waitcnt lgkmcnt(7)
	v_mfma_f32_16x16x32_bf16 v[14:17], v[208:211], v[236:239], v[14:17]
	s_waitcnt lgkmcnt(6)
	v_mfma_f32_16x16x32_bf16 v[18:21], v[212:215], v[224:227], v[18:21]
	v_mfma_f32_16x16x32_bf16 v[22:25], v[212:215], v[228:231], v[22:25]
	v_mfma_f32_16x16x32_bf16 v[26:29], v[212:215], v[232:235], v[26:29]
	v_mfma_f32_16x16x32_bf16 v[30:33], v[212:215], v[236:239], v[30:33]
	s_waitcnt lgkmcnt(5)
	v_mfma_f32_16x16x32_bf16 v[34:37], v[216:219], v[224:227], v[34:37]
	v_mfma_f32_16x16x32_bf16 v[38:41], v[216:219], v[228:231], v[38:41]
	v_mfma_f32_16x16x32_bf16 v[42:45], v[216:219], v[232:235], v[42:45]
	v_mfma_f32_16x16x32_bf16 v[46:49], v[216:219], v[236:239], v[46:49]
	s_waitcnt lgkmcnt(4)
	v_mfma_f32_16x16x32_bf16 v[50:53], v[220:223], v[224:227], v[50:53]
	v_mfma_f32_16x16x32_bf16 v[54:57], v[220:223], v[228:231], v[54:57]
	v_mfma_f32_16x16x32_bf16 v[58:61], v[220:223], v[232:235], v[58:61]
	v_mfma_f32_16x16x32_bf16 v[62:65], v[220:223], v[236:239], v[62:65]
	s_waitcnt lgkmcnt(3)
	v_mfma_f32_16x16x32_bf16 v[74:77], v[208:211], v[240:243], v[74:77]
	s_waitcnt lgkmcnt(2)
	v_mfma_f32_16x16x32_bf16 v[78:81], v[208:211], v[244:247], v[78:81]
	s_waitcnt lgkmcnt(1)
	v_mfma_f32_16x16x32_bf16 v[82:85], v[208:211], v[248:251], v[82:85]
	s_waitcnt lgkmcnt(0)
	v_mfma_f32_16x16x32_bf16 v[86:89], v[208:211], v[156:159], v[86:89]
	v_mfma_f32_16x16x32_bf16 v[90:93], v[212:215], v[240:243], v[90:93]
	v_mfma_f32_16x16x32_bf16 v[94:97], v[212:215], v[244:247], v[94:97]
	v_mfma_f32_16x16x32_bf16 v[98:101], v[212:215], v[248:251], v[98:101]
	v_mfma_f32_16x16x32_bf16 v[102:105], v[212:215], v[156:159], v[102:105]
	v_mfma_f32_16x16x32_bf16 v[106:109], v[216:219], v[240:243], v[106:109]
	v_mfma_f32_16x16x32_bf16 v[110:113], v[216:219], v[244:247], v[110:113]
	v_mfma_f32_16x16x32_bf16 v[114:117], v[216:219], v[248:251], v[114:117]
	v_mfma_f32_16x16x32_bf16 v[118:121], v[216:219], v[156:159], v[118:121]
	v_mfma_f32_16x16x32_bf16 v[122:125], v[220:223], v[240:243], v[122:125]
	v_mfma_f32_16x16x32_bf16 v[126:129], v[220:223], v[244:247], v[126:129]
	v_mfma_f32_16x16x32_bf16 v[130:133], v[220:223], v[248:251], v[130:133]
	v_mfma_f32_16x16x32_bf16 v[134:137], v[220:223], v[156:159], v[134:137]
	s_setprio 0
	s_waitcnt vmcnt(4)
	s_barrier
; #define BLOAD(A_, B_, kt) do { _Pragma("unroll") for (int i = 0; i < 4; ++i) { \
;     A_[i] = *(const u32x4*)((const char*)Ap + (aoff + (unsigned)(32 * i * lda + (kt) * 64) * 2u)); B_[i] = *(const u32x4*)((const char*)Wt + (woff + (unsigned)(32 * i * K + (kt) * 64) * 2u)); } } while (0)
; #define BLOAD(A_, B_, kt) do { _Pragma("unroll") for (int i = 0; i < 4; ++i) { \
;     A_[i] = *(const u32x4*)((const char*)Ap + (aoff + (unsigned)(32 * i * lda + (kt) * 64) * 2u)); B_[i] = *(const u32x4*)((const char*)Wt + (woff + (unsigned)(32 * i * K + (kt) * 64) * 2u)); } } while (0)
; #define BSTORE(A_, B_, buf) do { _Pragma("unroll") for (int i = 0; i < 4; ++i) { \
;     *(u32x4*)&As[(buf) * GBUF + (srow + 32 * i) * LDT + sc8] = A_[i]; \
;     *(u32x4*)&Bs[(buf) * GBUF + (srow + 32 * i) * LDT + sc8] = B_[i]; } } while (0)
; template <int NK>
; DI void gemm_run(PF& pf, const u16* __restrict__ Ap, int lda, const u16* __restrict__ Wt, f32x16 (&acc)[2][2], char* smem) {
;     ...
;   __builtin_amdgcn_s_setprio(0);
;   __syncthreads();
;   BSTORE(pf.a0, pf.b0, 0);
;   BLOAD(pf.a0, pf.b0, 2);
;   __syncthreads();
; #pragma unroll
;   for (int kt = 0; kt < nk; kt += 2) {
;     BCOMP(0);
;     BSTORE(pf.a1, pf.b1, 1);
;     if (kt + 3 < nk) BLOAD(pf.a1, pf.b1, kt + 3);
;     __syncthreads();
;     BCOMP(1);
;     if (kt + 2 < nk) { BSTORE(pf.a0, pf.b0, 0); if (kt + 4 < nk) BLOAD(pf.a0, pf.b0, kt + 4); }
;     __syncthreads();
;   }
	s_setprio 1
	ds_read_b128 v[208:211], v138 offset:16384
	ds_read_b128 v[224:227], v140 offset:0
	ds_read_b128 v[228:231], v140 offset:1024
	ds_read_b128 v[232:235], v140 offset:2048
	ds_read_b128 v[236:239], v140 offset:3072
	ds_read_b128 v[212:215], v138 offset:18432
	ds_read_b128 v[216:219], v138 offset:20480
	ds_read_b128 v[220:223], v138 offset:22528
	ds_read_b128 v[240:243], v140 offset:8192
	ds_read_b128 v[244:247], v140 offset:9216
	ds_read_b128 v[248:251], v140 offset:10240
	ds_read_b128 v[156:159], v140 offset:11264
	s_waitcnt lgkmcnt(10)
	v_mfma_f32_16x16x32_bf16 v[2:5], v[208:211], v[224:227], v[2:5]
	s_waitcnt lgkmcnt(9)
	v_mfma_f32_16x16x32_bf16 v[6:9], v[208:211], v[228:231], v[6:9]
	s_waitcnt lgkmcnt(8)
	v_mfma_f32_16x16x32_bf16 v[10:13], v[208:211], v[232:235], v[10:13]
	s_waitcnt lgkmcnt(7)
	v_mfma_f32_16x16x32_bf16 v[14:17], v[208:211], v[236:239], v[14:17]
	s_waitcnt lgkmcnt(6)
	v_mfma_f32_16x16x32_bf16 v[18:21], v[212:215], v[224:227], v[18:21]
	v_mfma_f32_16x16x32_bf16 v[22:25], v[212:215], v[228:231], v[22:25]
	v_mfma_f32_16x16x32_bf16 v[26:29], v[212:215], v[232:235], v[26:29]
	v_mfma_f32_16x16x32_bf16 v[30:33], v[212:215], v[236:239], v[30:33]
	s_waitcnt lgkmcnt(5)
	v_mfma_f32_16x16x32_bf16 v[34:37], v[216:219], v[224:227], v[34:37]
	v_mfma_f32_16x16x32_bf16 v[38:41], v[216:219], v[228:231], v[38:41]
	v_mfma_f32_16x16x32_bf16 v[42:45], v[216:219], v[232:235], v[42:45]
	v_mfma_f32_16x16x32_bf16 v[46:49], v[216:219], v[236:239], v[46:49]
	s_waitcnt lgkmcnt(4)
	v_mfma_f32_16x16x32_bf16 v[50:53], v[220:223], v[224:227], v[50:53]
	v_mfma_f32_16x16x32_bf16 v[54:57], v[220:223], v[228:231], v[54:57]
	v_mfma_f32_16x16x32_bf16 v[58:61], v[220:223], v[232:235], v[58:61]
	v_mfma_f32_16x16x32_bf16 v[62:65], v[220:223], v[236:239], v[62:65]
	s_waitcnt lgkmcnt(3)
	v_mfma_f32_16x16x32_bf16 v[74:77], v[208:211], v[240:243], v[74:77]
	s_waitcnt lgkmcnt(2)
	v_mfma_f32_16x16x32_bf16 v[78:81], v[208:211], v[244:247], v[78:81]
	s_waitcnt lgkmcnt(1)
	v_mfma_f32_16x16x32_bf16 v[82:85], v[208:211], v[248:251], v[82:85]
	s_waitcnt lgkmcnt(0)
	v_mfma_f32_16x16x32_bf16 v[86:89], v[208:211], v[156:159], v[86:89]
	v_mfma_f32_16x16x32_bf16 v[90:93], v[212:215], v[240:243], v[90:93]
	v_mfma_f32_16x16x32_bf16 v[94:97], v[212:215], v[244:247], v[94:97]
	v_mfma_f32_16x16x32_bf16 v[98:101], v[212:215], v[248:251], v[98:101]
	v_mfma_f32_16x16x32_bf16 v[102:105], v[212:215], v[156:159], v[102:105]
	v_mfma_f32_16x16x32_bf16 v[106:109], v[216:219], v[240:243], v[106:109]
	v_mfma_f32_16x16x32_bf16 v[110:113], v[216:219], v[244:247], v[110:113]
	v_mfma_f32_16x16x32_bf16 v[114:117], v[216:219], v[248:251], v[114:117]
	v_mfma_f32_16x16x32_bf16 v[118:121], v[216:219], v[156:159], v[118:121]
	v_mfma_f32_16x16x32_bf16 v[122:125], v[220:223], v[240:243], v[122:125]
	v_mfma_f32_16x16x32_bf16 v[126:129], v[220:223], v[244:247], v[126:129]
	v_mfma_f32_16x16x32_bf16 v[130:133], v[220:223], v[248:251], v[130:133]
	v_mfma_f32_16x16x32_bf16 v[134:137], v[220:223], v[156:159], v[134:137]
	s_setprio 0
	s_waitcnt vmcnt(0)
	s_barrier
	s_setprio 1
	ds_read_b128 v[208:211], v139 offset:16384
	ds_read_b128 v[224:227], v140 offset:16384
	ds_read_b128 v[228:231], v140 offset:17408
	ds_read_b128 v[232:235], v140 offset:18432
	ds_read_b128 v[236:239], v140 offset:19456
	ds_read_b128 v[212:215], v139 offset:18432
	ds_read_b128 v[216:219], v139 offset:20480
	ds_read_b128 v[220:223], v139 offset:22528
	ds_read_b128 v[240:243], v140 offset:24576
	ds_read_b128 v[244:247], v140 offset:25600
	ds_read_b128 v[248:251], v140 offset:26624
	ds_read_b128 v[156:159], v140 offset:27648
	s_waitcnt lgkmcnt(10)
	v_mfma_f32_16x16x32_bf16 v[2:5], v[208:211], v[224:227], v[2:5]
	s_waitcnt lgkmcnt(9)
	v_mfma_f32_16x16x32_bf16 v[6:9], v[208:211], v[228:231], v[6:9]
	s_waitcnt lgkmcnt(8)
	v_mfma_f32_16x16x32_bf16 v[10:13], v[208:211], v[232:235], v[10:13]
	s_waitcnt lgkmcnt(7)
	v_mfma_f32_16x16x32_bf16 v[14:17], v[208:211], v[236:239], v[14:17]
	s_waitcnt lgkmcnt(6)
	v_mfma_f32_16x16x32_bf16 v[18:21], v[212:215], v[224:227], v[18:21]
	v_mfma_f32_16x16x32_bf16 v[22:25], v[212:215], v[228:231], v[22:25]
	v_mfma_f32_16x16x32_bf16 v[26:29], v[212:215], v[232:235], v[26:29]
	v_mfma_f32_16x16x32_bf16 v[30:33], v[212:215], v[236:239], v[30:33]
	s_waitcnt lgkmcnt(5)
	v_mfma_f32_16x16x32_bf16 v[34:37], v[216:219], v[224:227], v[34:37]
	v_mfma_f32_16x16x32_bf16 v[38:41], v[216:219], v[228:231], v[38:41]
	v_mfma_f32_16x16x32_bf16 v[42:45], v[216:219], v[232:235], v[42:45]
	v_mfma_f32_16x16x32_bf16 v[46:49], v[216:219], v[236:239], v[46:49]
	s_waitcnt lgkmcnt(4)
	v_mfma_f32_16x16x32_bf16 v[50:53], v[220:223], v[224:227], v[50:53]
	v_mfma_f32_16x16x32_bf16 v[54:57], v[220:223], v[228:231], v[54:57]
	v_mfma_f32_16x16x32_bf16 v[58:61], v[220:223], v[232:235], v[58:61]
	v_mfma_f32_16x16x32_bf16 v[62:65], v[220:223], v[236:239], v[62:65]
	s_waitcnt lgkmcnt(3)
	v_mfma_f32_16x16x32_bf16 v[74:77], v[208:211], v[240:243], v[74:77]
	s_waitcnt lgkmcnt(2)
	v_mfma_f32_16x16x32_bf16 v[78:81], v[208:211], v[244:247], v[78:81]
	s_waitcnt lgkmcnt(1)
	v_mfma_f32_16x16x32_bf16 v[82:85], v[208:211], v[248:251], v[82:85]
	s_waitcnt lgkmcnt(0)
	v_mfma_f32_16x16x32_bf16 v[86:89], v[208:211], v[156:159], v[86:89]
	v_mfma_f32_16x16x32_bf16 v[90:93], v[212:215], v[240:243], v[90:93]
	v_mfma_f32_16x16x32_bf16 v[94:97], v[212:215], v[244:247], v[94:97]
	v_mfma_f32_16x16x32_bf16 v[98:101], v[212:215], v[248:251], v[98:101]
	v_mfma_f32_16x16x32_bf16 v[102:105], v[212:215], v[156:159], v[102:105]
	v_mfma_f32_16x16x32_bf16 v[106:109], v[216:219], v[240:243], v[106:109]
	v_mfma_f32_16x16x32_bf16 v[110:113], v[216:219], v[244:247], v[110:113]
	v_mfma_f32_16x16x32_bf16 v[114:117], v[216:219], v[248:251], v[114:117]
	v_mfma_f32_16x16x32_bf16 v[118:121], v[216:219], v[156:159], v[118:121]
	v_mfma_f32_16x16x32_bf16 v[122:125], v[220:223], v[240:243], v[122:125]
	v_mfma_f32_16x16x32_bf16 v[126:129], v[220:223], v[244:247], v[126:129]
	v_mfma_f32_16x16x32_bf16 v[130:133], v[220:223], v[248:251], v[130:133]
	v_mfma_f32_16x16x32_bf16 v[134:137], v[220:223], v[156:159], v[134:137]
	s_setprio 0
	s_barrier

; DI unsigned xb_add(unsigned* p, unsigned v) { return __hip_atomic_fetch_add(p, v, __ATOMIC_RELAXED, __HIP_MEMORY_SCOPE_AGENT); }
; DI void xcd_barrier(const XcdBarrier& b) {
;     ...
;   if (threadIdx.x == 0) {
;     unsigned* bar = b.bar;
;     __builtin_amdgcn_s_waitcnt(0);
;     unsigned nloc = b.st[0], nx = b.st[1];
;     if (nloc == 0u) { xcd_barrier_complete(bar, b.x, nloc, nx); b.st[0] = nloc; b.st[1] = nx; }
;     const unsigned old = xb_add(&bar[XB_XSUB(b.x)], 1u);
;     const unsigned gen = old / nloc;
;     if (old + 1u == (gen + 1u) * nloc) {
.LBB1_429:
	s_waitcnt vmcnt(0) expcnt(0) lgkmcnt(0)
	v_readlane_b32 s0, v255, 60
	v_readlane_b32 vcc_lo, v255, 61
	s_nop 1
	v_mov_b32_e32 v3, s0
	v_mov_b32_e32 v2, vcc_lo
	s_waitcnt lgkmcnt(1)
	v_cmp_ne_u32_e32 vcc, 0, v3
	s_cbranch_vccnz .LBB1_444
	s_mov_b32 s0, 1
	s_branch .LBB1_432

; DI unsigned xb_ld(unsigned* p)              { return __hip_atomic_load(p, __ATOMIC_RELAXED, __HIP_MEMORY_SCOPE_AGENT); }
; DI void xcd_barrier_complete(unsigned* bar, unsigned x, unsigned& nloc, unsigned& nx) {
;     ...
;     sum = 0u; cnt = 0u; mine = 0u;
; #pragma unroll
;     for (unsigned j = 0; j < 16; ++j) { const unsigned c = xb_ld(&bar[XB_XCNT(j)]); sum += c; cnt += (c > 0u) ? 1u : 0u; mine = (j == x) ? c : mine; }
;     if (sum == G) break;
;     __builtin_amdgcn_s_sleep(1);
;     if ((++sp & 255u) == 0u) { if (xb_ld(&bar[XB_TMO])) break; if (sp > XB_SPIN_CAP) { atomicAdd(&bar[XB_TMO], 1u); break; } }
;   }
;   nloc = mine > 0u ? mine : 1u; nx = cnt > 0u ? cnt : 1u;
; DI void xcd_barrier(const XcdBarrier& b) {
;     ...
;     if (nloc == 0u) { xcd_barrier_complete(bar, b.x, nloc, nx); b.st[0] = nloc; b.st[1] = nx; }
.LBB1_443:
	v_readlane_b32 s14, v255, 12
	v_readlane_b32 s15, v255, 13
	v_cmp_ne_u32_e32 vcc, 0, v0
	s_nop 0
	v_cndmask_b32_e64 v17, 0, v0, s[14:15]
	v_readlane_b32 s14, v255, 10
	v_readlane_b32 s15, v255, 11
	v_cndmask_b32_e64 v0, 0, 1, vcc
	v_cmp_ne_u32_e32 vcc, 0, v2
	v_cndmask_b32_e64 v17, v17, v2, s[14:15]
	v_readlane_b32 s14, v255, 8
	v_readlane_b32 s15, v255, 9
	v_addc_co_u32_e32 v0, vcc, 0, v0, vcc
	s_nop 0
	v_cndmask_b32_e64 v17, v17, v3, s[14:15]
	v_readlane_b32 s14, v255, 6
	v_readlane_b32 s15, v255, 7
	v_cmp_ne_u32_e32 vcc, 0, v3
	s_nop 0
	v_cndmask_b32_e64 v17, v17, v4, s[14:15]
	v_readlane_b32 s14, v255, 4
	v_readlane_b32 s15, v255, 5
	v_cndmask_b32_e64 v2, 0, 1, vcc
	v_cmp_ne_u32_e32 vcc, 0, v4
	v_cndmask_b32_e64 v17, v17, v5, s[14:15]
	v_readlane_b32 s14, v255, 2
	v_readlane_b32 s15, v255, 3
	v_addc_co_u32_e32 v0, vcc, v0, v2, vcc
	s_nop 0
	v_cndmask_b32_e64 v17, v17, v6, s[14:15]
	v_readlane_b32 s14, v255, 0
	v_readlane_b32 s15, v255, 1
	v_cmp_ne_u32_e32 vcc, 0, v5
	s_nop 0
	v_cndmask_b32_e64 v17, v17, v7, s[14:15]
	v_readlane_b32 s14, v254, 62
	v_readlane_b32 s15, v254, 63
	v_cndmask_b32_e64 v2, 0, 1, vcc
	v_cmp_ne_u32_e32 vcc, 0, v6
	v_cndmask_b32_e64 v17, v17, v8, s[14:15]
	v_readlane_b32 s14, v254, 60
	v_readlane_b32 s15, v254, 61
	v_addc_co_u32_e32 v0, vcc, v0, v2, vcc
	s_nop 0
	v_cndmask_b32_e64 v17, v17, v9, s[14:15]
	v_readlane_b32 s14, v254, 58
	v_cmp_ne_u32_e32 vcc, 0, v7
	v_readlane_b32 s15, v254, 59
	s_nop 0
	v_cndmask_b32_e64 v2, 0, 1, vcc
	v_cmp_ne_u32_e32 vcc, 0, v8
	v_cndmask_b32_e64 v17, v17, v10, s[14:15]
	v_readlane_b32 s14, v254, 56
	v_addc_co_u32_e32 v0, vcc, v0, v2, vcc
	v_readlane_b32 s15, v254, 57
	v_cmp_ne_u32_e32 vcc, 0, v9
	s_nop 0
	v_cndmask_b32_e64 v17, v17, v11, s[14:15]
	v_readlane_b32 s14, v254, 54
	v_cndmask_b32_e64 v2, 0, 1, vcc
	v_cmp_ne_u32_e32 vcc, 0, v10
	v_readlane_b32 s15, v254, 55
	s_nop 0
	v_addc_co_u32_e32 v0, vcc, v0, v2, vcc
	v_cndmask_b32_e64 v17, v17, v12, s[14:15]
	v_readlane_b32 s14, v254, 52
	v_cmp_ne_u32_e32 vcc, 0, v11
	v_readlane_b32 s15, v254, 53
	s_nop 0
	v_cndmask_b32_e64 v2, 0, 1, vcc
	v_cmp_ne_u32_e32 vcc, 0, v12
	v_cndmask_b32_e64 v17, v17, v13, s[14:15]
	v_readlane_b32 s14, v254, 50
	v_addc_co_u32_e32 v0, vcc, v0, v2, vcc
	v_readlane_b32 s15, v254, 51
	v_cmp_ne_u32_e32 vcc, 0, v13
	s_nop 0
	v_cndmask_b32_e64 v17, v17, v14, s[14:15]
	v_readlane_b32 s14, v254, 48
	v_cndmask_b32_e64 v2, 0, 1, vcc
	v_cmp_ne_u32_e32 vcc, 0, v14
	v_readlane_b32 s15, v254, 49
	s_nop 0
	v_addc_co_u32_e32 v0, vcc, v0, v2, vcc
	v_cndmask_b32_e64 v17, v17, v15, s[14:15]
	v_readlane_b32 s14, v254, 46
	v_cmp_ne_u32_e32 vcc, 0, v15
	v_readlane_b32 s15, v254, 47
	s_nop 0
	v_cndmask_b32_e64 v2, 0, 1, vcc
	v_cmp_ne_u32_e32 vcc, 0, v16
	v_cndmask_b32_e64 v17, v17, v16, s[14:15]
	v_max_u32_e32 v3, 1, v17
	v_addc_co_u32_e32 v0, vcc, v0, v2, vcc
	v_max_u32_e32 v2, 1, v0
	v_readfirstlane_b32 s14, v3
	v_readfirstlane_b32 s15, v2
	s_nop 1
	v_writelane_b32 v255, s14, 60
	v_writelane_b32 v255, s15, 61

; __global__ void __launch_bounds__(256, 2) mega_kernel(Params p) {
;   __shared__ __attribute__((aligned(16))) char smem[SMEM_BYTES];
;   __shared__ uint4 xb_words;
	.amdhsa_kernel _Z11mega_kernel6Params
		.amdhsa_group_segment_fixed_size 81920
		.amdhsa_private_segment_fixed_size 0
		.amdhsa_kernarg_size 456
		.amdhsa_user_sgpr_count 2
		.amdhsa_user_sgpr_dispatch_ptr 0
		.amdhsa_user_sgpr_queue_ptr 0
		.amdhsa_user_sgpr_kernarg_segment_ptr 1
		.amdhsa_user_sgpr_dispatch_id 0
		.amdhsa_user_sgpr_kernarg_preload_length 0
		.amdhsa_user_sgpr_kernarg_preload_offset 0
		.amdhsa_user_sgpr_private_segment_size 0
		.amdhsa_uses_dynamic_stack 0
		.amdhsa_enable_private_segment 0
		.amdhsa_system_sgpr_workgroup_id_x 1
		.amdhsa_system_sgpr_workgroup_id_y 0
		.amdhsa_system_sgpr_workgroup_id_z 0
		.amdhsa_system_sgpr_workgroup_info 0
		.amdhsa_system_vgpr_workitem_id 2
		.amdhsa_next_free_vgpr 256
		.amdhsa_next_free_sgpr 100
		.amdhsa_accum_offset 256
		.amdhsa_reserve_vcc 1
		.amdhsa_float_round_mode_32 0
		.amdhsa_float_round_mode_16_64 0
		.amdhsa_float_denorm_mode_32 3
		.amdhsa_float_denorm_mode_16_64 3
		.amdhsa_dx10_clamp 1
		.amdhsa_ieee_mode 1
		.amdhsa_fp16_overflow 0
		.amdhsa_tg_split 0
		.amdhsa_exception_fp_ieee_invalid_op 0
		.amdhsa_exception_fp_denorm_src 0
		.amdhsa_exception_fp_ieee_div_zero 0
		.amdhsa_exception_fp_ieee_overflow 0
		.amdhsa_exception_fp_ieee_underflow 0
		.amdhsa_exception_fp_ieee_inexact 0
		.amdhsa_exception_int_div_zero 0
	.end_amdhsa_kernel

; __global__ void __launch_bounds__(256, 2) phase_kernel(Params p, int ph, int l, int c) {
;   __shared__ __attribute__((aligned(16))) char smem[SMEM_BYTES];
;   if (ph == PH_PREP) phase_prep(p, smem); else run_phase(p, ph, l, c, smem);
; }
; __global__ void __launch_bounds__(256, 2) mega_kernel(Params p) {
;   __shared__ __attribute__((aligned(16))) char smem[SMEM_BYTES];
;   __shared__ uint4 xb_words;
amdhsa.kernels:
  - .agpr_count:     0
    .args:
      - .offset:         0
        .size:           200
        .value_kind:     by_value
      - .offset:         200
        .size:           4
        .value_kind:     by_value
      - .offset:         204
        .size:           4
        .value_kind:     by_value
      - .offset:         208
        .size:           4
        .value_kind:     by_value
      - .offset:         216
        .size:           4
        .value_kind:     hidden_block_count_x
      - .offset:         220
        .size:           4
        .value_kind:     hidden_block_count_y
      - .offset:         224
        .size:           4
        .value_kind:     hidden_block_count_z
      - .offset:         228
        .size:           2
        .value_kind:     hidden_group_size_x
      - .offset:         230
        .size:           2
        .value_kind:     hidden_group_size_y
      - .offset:         232
        .size:           2
        .value_kind:     hidden_group_size_z
      - .offset:         234
        .size:           2
        .value_kind:     hidden_remainder_x
      - .offset:         236
        .size:           2
        .value_kind:     hidden_remainder_y
      - .offset:         238
        .size:           2
        .value_kind:     hidden_remainder_z
      - .offset:         256
        .size:           8
        .value_kind:     hidden_global_offset_x
      - .offset:         264
        .size:           8
        .value_kind:     hidden_global_offset_y
      - .offset:         272
        .size:           8
        .value_kind:     hidden_global_offset_z
      - .offset:         280
        .size:           2
        .value_kind:     hidden_grid_dims
    .group_segment_fixed_size: 74240
    .kernarg_segment_align: 8
    .kernarg_segment_size: 472
    .language:       OpenCL C
    .language_version:
      - 2
      - 0
    .max_flat_workgroup_size: 256
    .name:           _Z12phase_kernel6Paramsiii
    .private_segment_fixed_size: 0
    .sgpr_count:     106
    .sgpr_spill_count: 12
    .symbol:         _Z12phase_kernel6Paramsiii.kd
    .uniform_work_group_size: 1
    .uses_dynamic_stack: false
    .vgpr_count:     245
    .vgpr_spill_count: 0
    .wavefront_size: 64
  - .agpr_count:     0
    .args:
      - .offset:         0
        .size:           200
        .value_kind:     by_value
      - .offset:         200
        .size:           4
        .value_kind:     hidden_block_count_x
      - .offset:         204
        .size:           4
        .value_kind:     hidden_block_count_y
      - .offset:         208
        .size:           4
        .value_kind:     hidden_block_count_z
      - .offset:         212
        .size:           2
        .value_kind:     hidden_group_size_x
      - .offset:         214
        .size:           2
        .value_kind:     hidden_group_size_y
      - .offset:         216
        .size:           2
        .value_kind:     hidden_group_size_z
      - .offset:         218
        .size:           2
        .value_kind:     hidden_remainder_x
      - .offset:         220
        .size:           2
        .value_kind:     hidden_remainder_y
      - .offset:         222
        .size:           2
        .value_kind:     hidden_remainder_z
      - .offset:         240
        .size:           8
        .value_kind:     hidden_global_offset_x
      - .offset:         248
        .size:           8
        .value_kind:     hidden_global_offset_y
      - .offset:         256
        .size:           8
        .value_kind:     hidden_global_offset_z
      - .offset:         264
        .size:           2
        .value_kind:     hidden_grid_dims
      - .offset:         288
        .size:           8
        .value_kind:     hidden_multigrid_sync_arg
    .group_segment_fixed_size: 81920
    .kernarg_segment_align: 8
    .kernarg_segment_size: 456
    .language:       OpenCL C
    .language_version:
      - 2
      - 0
    .max_flat_workgroup_size: 256
    .name:           _Z11mega_kernel6Params
    .private_segment_fixed_size: 0
    .sgpr_count:     106
    .sgpr_spill_count: 121
    .symbol:         _Z11mega_kernel6Params.kd
    .uniform_work_group_size: 1
    .uses_dynamic_stack: false
    .vgpr_count:     256
    .vgpr_spill_count: 0
    .wavefront_size: 64
